# K-loop MFMA order: the two accumulating MFMAs (k=0,k=1) of each accumulator issued back-to-back (SrcC forwarding) instead of 8 apart; on split-K + moved cache conversion
# speedup vs baseline: 1.0062x; 1.0062x over previous
.LBB0_296:
	s_ashr_i32 s23, s22, 31
	s_lshl_b64 s[56:57], s[22:23], 21
	s_add_u32 s72, s2, s56
	s_addc_u32 s73, s3, s57
	s_and_b64 s[56:57], s[4:5], exec
	s_cselect_b32 s23, s73, s81
	s_cselect_b32 s56, s72, s80
	s_ashr_i32 s21, s20, 31
	s_lshl_b64 s[60:61], s[20:21], 20
	s_add_u32 s74, s14, s60
	s_addc_u32 s75, s15, s61
	s_and_b64 s[60:61], s[4:5], exec
	s_cselect_b32 s21, s75, s83
	s_cselect_b32 s57, s74, s82
	s_add_u32 s80, s80, 0x100080
	s_addc_u32 s81, s81, 0
	s_add_u32 s60, s82, 0x100
	s_addc_u32 s61, s83, 0
	s_mov_b32 s68, -2
	s_add_u32 s67, s80, 0xfff00080
	s_addc_u32 s69, s81, -1
	s_add_i32 s70, 0, 0x10000
	s_cmp_eq_u32 s68, 28
	s_cselect_b32 s85, s23, s69
	s_cselect_b32 s84, s56, s67
	s_cselect_b32 s83, s21, s61
	s_cselect_b32 s82, s57, s60
	s_add_i32 s67, 0, 0x14000
	v_add_u32_e32 v140, s70, v168
	v_add_u32_e32 v166, s67, v168
	ds_read_b128 v[80:83], v140
	ds_read_b128 v[116:119], v140 offset:1024
	ds_read_b128 v[136:139], v140 offset:2048
	ds_read_b128 v[140:143], v140 offset:3072
	ds_read_b128 v[158:161], v166
	ds_read_b128 v[162:165], v166 offset:1024
	ds_read_b128 v[170:173], v166 offset:2048
	ds_read_b128 v[174:177], v166 offset:3072
	v_lshl_add_u64 v[166:167], s[80:81], 0, v[154:155]
	s_add_i32 m0, s26, 0xc000
	ds_read_b128 v[178:181], v169
	ds_read_b128 v[182:185], v169 offset:1024
	ds_read_b128 v[186:189], v169 offset:2048
	ds_read_b128 v[190:193], v169 offset:3072
	ds_read_b128 v[194:197], v169 offset:4096
	ds_read_b128 v[198:201], v169 offset:5120
	ds_read_b128 v[202:205], v169 offset:6144
	ds_read_b128 v[206:209], v169 offset:7168
	global_load_lds_dwordx4 v[166:167], off
	v_lshl_add_u64 v[166:167], s[80:81], 0, v[156:157]
	s_add_i32 m0, s26, 0xe000
	s_nop 0
	global_load_lds_dwordx4 v[166:167], off
	s_waitcnt vmcnt(8)
	s_waitcnt lgkmcnt(0)
	s_barrier
	s_waitcnt lgkmcnt(0)
	v_mfma_f32_16x16x32_bf16 v[132:135], v[80:83], v[178:181], 0
	v_mfma_f32_16x16x32_bf16 v[132:135], v[116:119], v[182:185], v[132:135]
	v_mfma_f32_16x16x32_bf16 v[128:131], v[136:139], v[178:181], 0
	v_mfma_f32_16x16x32_bf16 v[128:131], v[140:143], v[182:185], v[128:131]
	v_mfma_f32_16x16x32_bf16 v[112:115], v[80:83], v[186:189], 0
	v_mfma_f32_16x16x32_bf16 v[112:115], v[116:119], v[190:193], v[112:115]
	v_mfma_f32_16x16x32_bf16 v[108:111], v[136:139], v[186:189], 0
	v_mfma_f32_16x16x32_bf16 v[108:111], v[140:143], v[190:193], v[108:111]
	v_mfma_f32_16x16x32_bf16 v[96:99], v[80:83], v[194:197], 0
	v_mfma_f32_16x16x32_bf16 v[96:99], v[116:119], v[198:201], v[96:99]
	v_mfma_f32_16x16x32_bf16 v[92:95], v[136:139], v[194:197], 0
	v_mfma_f32_16x16x32_bf16 v[92:95], v[140:143], v[198:201], v[92:95]
	v_mfma_f32_16x16x32_bf16 v[76:79], v[80:83], v[202:205], 0
	v_mfma_f32_16x16x32_bf16 v[76:79], v[116:119], v[206:209], v[76:79]
	v_mfma_f32_16x16x32_bf16 v[72:75], v[136:139], v[202:205], 0
	v_mfma_f32_16x16x32_bf16 v[72:75], v[140:143], v[206:209], v[72:75]
	v_mfma_f32_16x16x32_bf16 v[124:127], v[158:161], v[178:181], 0
	v_mfma_f32_16x16x32_bf16 v[124:127], v[162:165], v[182:185], v[124:127]
	v_mfma_f32_16x16x32_bf16 v[120:123], v[170:173], v[178:181], 0
	v_mfma_f32_16x16x32_bf16 v[120:123], v[174:177], v[182:185], v[120:123]
	v_mfma_f32_16x16x32_bf16 v[104:107], v[158:161], v[186:189], 0
	v_mfma_f32_16x16x32_bf16 v[104:107], v[162:165], v[190:193], v[104:107]
	v_mfma_f32_16x16x32_bf16 v[100:103], v[170:173], v[186:189], 0
	v_mfma_f32_16x16x32_bf16 v[100:103], v[174:177], v[190:193], v[100:103]
	v_mfma_f32_16x16x32_bf16 v[88:91], v[158:161], v[194:197], 0
	v_mfma_f32_16x16x32_bf16 v[88:91], v[162:165], v[198:201], v[88:91]
	v_mfma_f32_16x16x32_bf16 v[84:87], v[170:173], v[194:197], 0
	v_mfma_f32_16x16x32_bf16 v[84:87], v[174:177], v[198:201], v[84:87]
	v_mfma_f32_16x16x32_bf16 v[68:71], v[158:161], v[202:205], 0
	v_mfma_f32_16x16x32_bf16 v[68:71], v[162:165], v[206:209], v[68:71]
	v_mfma_f32_16x16x32_bf16 v[64:67], v[170:173], v[202:205], 0
	v_mfma_f32_16x16x32_bf16 v[64:67], v[174:177], v[206:209], v[64:67]
	s_barrier
	s_add_i32 s69, s70, s24
	v_lshl_add_u64 v[166:167], s[82:83], 0, v[146:147]
	s_mov_b32 m0, s69
	ds_read_b128 v[178:181], v169 offset:16384
	ds_read_b128 v[182:185], v169 offset:17408
	ds_read_b128 v[186:189], v169 offset:18432
	ds_read_b128 v[190:193], v169 offset:19456
	ds_read_b128 v[194:197], v169 offset:20480
	ds_read_b128 v[198:201], v169 offset:21504
	ds_read_b128 v[202:205], v169 offset:22528
	ds_read_b128 v[206:209], v169 offset:23552
	global_load_lds_dwordx4 v[166:167], off
	s_add_i32 m0, s69, 0x2000
	s_add_u32 s70, s82, 0x80000
	v_lshl_add_u64 v[210:211], s[82:83], 0, v[150:151]
	s_addc_u32 s71, s83, 0
	s_add_i32 s67, s67, s24
	global_load_lds_dwordx4 v[210:211], off
	v_lshl_add_u64 v[212:213], s[70:71], 0, v[146:147]
	s_mov_b32 m0, s67
	v_lshl_add_u64 v[214:215], s[84:85], 0, v[148:149]
	global_load_lds_dwordx4 v[212:213], off
	v_lshl_add_u64 v[212:213], s[70:71], 0, v[150:151]
	s_add_i32 m0, s67, 0x2000
	s_nop 0
	global_load_lds_dwordx4 v[212:213], off
	v_lshl_add_u64 v[212:213], s[84:85], 0, v[144:145]
	s_mov_b32 m0, s26
	s_nop 0
	global_load_lds_dwordx4 v[212:213], off
	s_mov_b32 m0, s28
	s_nop 0
	global_load_lds_dwordx4 v[214:215], off
	s_waitcnt vmcnt(8)
	s_waitcnt lgkmcnt(0)
	s_barrier
	s_waitcnt lgkmcnt(0)
	v_mfma_f32_16x16x32_bf16 v[60:63], v[80:83], v[178:181], 0
	v_mfma_f32_16x16x32_bf16 v[60:63], v[116:119], v[182:185], v[60:63]
	v_mfma_f32_16x16x32_bf16 v[56:59], v[136:139], v[178:181], 0
	v_mfma_f32_16x16x32_bf16 v[56:59], v[140:143], v[182:185], v[56:59]
	v_mfma_f32_16x16x32_bf16 v[44:47], v[80:83], v[186:189], 0
	v_mfma_f32_16x16x32_bf16 v[44:47], v[116:119], v[190:193], v[44:47]
	v_mfma_f32_16x16x32_bf16 v[40:43], v[136:139], v[186:189], 0
	v_mfma_f32_16x16x32_bf16 v[40:43], v[140:143], v[190:193], v[40:43]
	v_mfma_f32_16x16x32_bf16 v[28:31], v[80:83], v[194:197], 0
	v_mfma_f32_16x16x32_bf16 v[28:31], v[116:119], v[198:201], v[28:31]
	v_mfma_f32_16x16x32_bf16 v[24:27], v[136:139], v[194:197], 0
	v_mfma_f32_16x16x32_bf16 v[24:27], v[140:143], v[198:201], v[24:27]
	v_mfma_f32_16x16x32_bf16 v[12:15], v[80:83], v[202:205], 0
	v_mfma_f32_16x16x32_bf16 v[12:15], v[116:119], v[206:209], v[12:15]
	v_mfma_f32_16x16x32_bf16 v[8:11], v[136:139], v[202:205], 0
	v_mfma_f32_16x16x32_bf16 v[8:11], v[140:143], v[206:209], v[8:11]
	v_mfma_f32_16x16x32_bf16 v[52:55], v[158:161], v[178:181], 0
	v_mfma_f32_16x16x32_bf16 v[52:55], v[162:165], v[182:185], v[52:55]
	v_mfma_f32_16x16x32_bf16 v[48:51], v[170:173], v[178:181], 0
	v_mfma_f32_16x16x32_bf16 v[48:51], v[174:177], v[182:185], v[48:51]
	v_mfma_f32_16x16x32_bf16 v[36:39], v[158:161], v[186:189], 0
	v_mfma_f32_16x16x32_bf16 v[36:39], v[162:165], v[190:193], v[36:39]
	v_mfma_f32_16x16x32_bf16 v[32:35], v[170:173], v[186:189], 0
	v_mfma_f32_16x16x32_bf16 v[32:35], v[174:177], v[190:193], v[32:35]
	v_mfma_f32_16x16x32_bf16 v[20:23], v[158:161], v[194:197], 0
	v_mfma_f32_16x16x32_bf16 v[20:23], v[162:165], v[198:201], v[20:23]
	v_mfma_f32_16x16x32_bf16 v[16:19], v[170:173], v[194:197], 0
	v_mfma_f32_16x16x32_bf16 v[16:19], v[174:177], v[198:201], v[16:19]
	v_mfma_f32_16x16x32_bf16 v[4:7], v[158:161], v[202:205], 0
	v_mfma_f32_16x16x32_bf16 v[4:7], v[162:165], v[206:209], v[4:7]
	v_mfma_f32_16x16x32_bf16 v[0:3], v[170:173], v[202:205], 0
	v_mfma_f32_16x16x32_bf16 v[0:3], v[174:177], v[206:209], v[0:3]
	s_barrier
	s_add_i32 s67, 0, 0x18000
	s_add_i32 s69, 0, 0x1c000
	v_add_u32_e32 v140, s67, v168
	v_add_u32_e32 v174, s69, v168
	ds_read_b128 v[80:83], v140
	ds_read_b128 v[116:119], v140 offset:1024
	ds_read_b128 v[136:139], v140 offset:2048
	ds_read_b128 v[140:143], v140 offset:3072
	ds_read_b128 v[158:161], v174
	ds_read_b128 v[162:165], v174 offset:1024
	ds_read_b128 v[170:173], v174 offset:2048
	ds_read_b128 v[174:177], v174 offset:3072
	s_add_u32 s70, s84, 0x100000
	s_addc_u32 s71, s85, 0
	s_mov_b32 m0, s29
	v_lshl_add_u64 v[218:219], s[70:71], 0, v[144:145]
	ds_read_b128 v[178:181], v169 offset:32768
	ds_read_b128 v[182:185], v169 offset:33792
	ds_read_b128 v[186:189], v169 offset:34816
	ds_read_b128 v[190:193], v169 offset:35840
	ds_read_b128 v[194:197], v169 offset:36864
	ds_read_b128 v[198:201], v169 offset:37888
	ds_read_b128 v[202:205], v169 offset:38912
	ds_read_b128 v[206:209], v169 offset:39936
	global_load_lds_dwordx4 v[218:219], off
	v_lshl_add_u64 v[218:219], s[70:71], 0, v[148:149]
	s_mov_b32 m0, s34
	s_nop 0
	global_load_lds_dwordx4 v[218:219], off
	s_waitcnt vmcnt(8)
	s_waitcnt lgkmcnt(0)
	s_barrier
	s_waitcnt lgkmcnt(0)
	v_mfma_f32_16x16x32_bf16 v[132:135], v[80:83], v[178:181], v[132:135]
	v_mfma_f32_16x16x32_bf16 v[132:135], v[116:119], v[182:185], v[132:135]
	v_mfma_f32_16x16x32_bf16 v[128:131], v[136:139], v[178:181], v[128:131]
	v_mfma_f32_16x16x32_bf16 v[128:131], v[140:143], v[182:185], v[128:131]
	v_mfma_f32_16x16x32_bf16 v[112:115], v[80:83], v[186:189], v[112:115]
	v_mfma_f32_16x16x32_bf16 v[112:115], v[116:119], v[190:193], v[112:115]
	v_mfma_f32_16x16x32_bf16 v[108:111], v[136:139], v[186:189], v[108:111]
	v_mfma_f32_16x16x32_bf16 v[108:111], v[140:143], v[190:193], v[108:111]
	v_mfma_f32_16x16x32_bf16 v[96:99], v[80:83], v[194:197], v[96:99]
	v_mfma_f32_16x16x32_bf16 v[96:99], v[116:119], v[198:201], v[96:99]
	v_mfma_f32_16x16x32_bf16 v[92:95], v[136:139], v[194:197], v[92:95]
	v_mfma_f32_16x16x32_bf16 v[92:95], v[140:143], v[198:201], v[92:95]
	v_mfma_f32_16x16x32_bf16 v[76:79], v[80:83], v[202:205], v[76:79]
	v_mfma_f32_16x16x32_bf16 v[76:79], v[116:119], v[206:209], v[76:79]
	v_mfma_f32_16x16x32_bf16 v[72:75], v[136:139], v[202:205], v[72:75]
	v_mfma_f32_16x16x32_bf16 v[72:75], v[140:143], v[206:209], v[72:75]
	v_mfma_f32_16x16x32_bf16 v[124:127], v[158:161], v[178:181], v[124:127]
	v_mfma_f32_16x16x32_bf16 v[124:127], v[162:165], v[182:185], v[124:127]
	v_mfma_f32_16x16x32_bf16 v[120:123], v[170:173], v[178:181], v[120:123]
	v_mfma_f32_16x16x32_bf16 v[120:123], v[174:177], v[182:185], v[120:123]
	v_mfma_f32_16x16x32_bf16 v[104:107], v[158:161], v[186:189], v[104:107]
	v_mfma_f32_16x16x32_bf16 v[104:107], v[162:165], v[190:193], v[104:107]
	v_mfma_f32_16x16x32_bf16 v[100:103], v[170:173], v[186:189], v[100:103]
	v_mfma_f32_16x16x32_bf16 v[100:103], v[174:177], v[190:193], v[100:103]
	v_mfma_f32_16x16x32_bf16 v[88:91], v[158:161], v[194:197], v[88:91]
	v_mfma_f32_16x16x32_bf16 v[88:91], v[162:165], v[198:201], v[88:91]
	v_mfma_f32_16x16x32_bf16 v[84:87], v[170:173], v[194:197], v[84:87]
	v_mfma_f32_16x16x32_bf16 v[84:87], v[174:177], v[198:201], v[84:87]
	v_mfma_f32_16x16x32_bf16 v[68:71], v[158:161], v[202:205], v[68:71]
	v_mfma_f32_16x16x32_bf16 v[68:71], v[162:165], v[206:209], v[68:71]
	v_mfma_f32_16x16x32_bf16 v[64:67], v[170:173], v[202:205], v[64:67]
	v_mfma_f32_16x16x32_bf16 v[64:67], v[174:177], v[206:209], v[64:67]
	s_barrier
	s_add_i32 s67, s67, s24
	v_lshl_add_u64 v[166:167], v[166:167], 0, s[30:31]
	s_mov_b32 m0, s67
	ds_read_b128 v[178:181], v169 offset:49152
	ds_read_b128 v[182:185], v169 offset:50176
	ds_read_b128 v[186:189], v169 offset:51200
	ds_read_b128 v[190:193], v169 offset:52224
	ds_read_b128 v[194:197], v169 offset:53248
	ds_read_b128 v[198:201], v169 offset:54272
	ds_read_b128 v[202:205], v169 offset:55296
	ds_read_b128 v[206:209], v169 offset:56320
	global_load_lds_dwordx4 v[166:167], off
	s_add_i32 m0, s67, 0x2000
	s_add_u32 s70, s82, 0x80080
	v_lshl_add_u64 v[166:167], v[210:211], 0, s[30:31]
	s_addc_u32 s71, s83, 0
	s_add_i32 s67, s69, s24
	global_load_lds_dwordx4 v[166:167], off
	v_lshl_add_u64 v[166:167], s[70:71], 0, v[146:147]
	s_mov_b32 m0, s67
	s_nop 0
	global_load_lds_dwordx4 v[166:167], off
	v_lshl_add_u64 v[166:167], s[70:71], 0, v[150:151]
	s_add_i32 m0, s67, 0x2000
	s_nop 0
	global_load_lds_dwordx4 v[166:167], off
	v_lshl_add_u64 v[166:167], v[212:213], 0, s[30:31]
	s_mov_b32 m0, s39
	s_nop 0
	global_load_lds_dwordx4 v[166:167], off
	v_lshl_add_u64 v[166:167], v[214:215], 0, s[30:31]
	s_mov_b32 m0, s40
	s_nop 0
	global_load_lds_dwordx4 v[166:167], off
	s_waitcnt vmcnt(8)
	s_waitcnt lgkmcnt(0)
	s_barrier
	s_waitcnt lgkmcnt(0)
	v_mfma_f32_16x16x32_bf16 v[60:63], v[80:83], v[178:181], v[60:63]
	v_mfma_f32_16x16x32_bf16 v[60:63], v[116:119], v[182:185], v[60:63]
	v_mfma_f32_16x16x32_bf16 v[56:59], v[136:139], v[178:181], v[56:59]
	v_mfma_f32_16x16x32_bf16 v[56:59], v[140:143], v[182:185], v[56:59]
	v_mfma_f32_16x16x32_bf16 v[44:47], v[80:83], v[186:189], v[44:47]
	v_mfma_f32_16x16x32_bf16 v[44:47], v[116:119], v[190:193], v[44:47]
	v_mfma_f32_16x16x32_bf16 v[40:43], v[136:139], v[186:189], v[40:43]
	v_mfma_f32_16x16x32_bf16 v[40:43], v[140:143], v[190:193], v[40:43]
	v_mfma_f32_16x16x32_bf16 v[28:31], v[80:83], v[194:197], v[28:31]
	v_mfma_f32_16x16x32_bf16 v[28:31], v[116:119], v[198:201], v[28:31]
	v_mfma_f32_16x16x32_bf16 v[24:27], v[136:139], v[194:197], v[24:27]
	v_mfma_f32_16x16x32_bf16 v[24:27], v[140:143], v[198:201], v[24:27]
	v_mfma_f32_16x16x32_bf16 v[12:15], v[80:83], v[202:205], v[12:15]
	v_mfma_f32_16x16x32_bf16 v[12:15], v[116:119], v[206:209], v[12:15]
	v_mfma_f32_16x16x32_bf16 v[8:11], v[136:139], v[202:205], v[8:11]
	v_mfma_f32_16x16x32_bf16 v[8:11], v[140:143], v[206:209], v[8:11]
	v_mfma_f32_16x16x32_bf16 v[52:55], v[158:161], v[178:181], v[52:55]
	v_mfma_f32_16x16x32_bf16 v[52:55], v[162:165], v[182:185], v[52:55]
	v_mfma_f32_16x16x32_bf16 v[48:51], v[170:173], v[178:181], v[48:51]
	v_mfma_f32_16x16x32_bf16 v[48:51], v[174:177], v[182:185], v[48:51]
	v_mfma_f32_16x16x32_bf16 v[36:39], v[158:161], v[186:189], v[36:39]
	v_mfma_f32_16x16x32_bf16 v[36:39], v[162:165], v[190:193], v[36:39]
	v_mfma_f32_16x16x32_bf16 v[32:35], v[170:173], v[186:189], v[32:35]
	v_mfma_f32_16x16x32_bf16 v[32:35], v[174:177], v[190:193], v[32:35]
	v_mfma_f32_16x16x32_bf16 v[20:23], v[158:161], v[194:197], v[20:23]
	v_mfma_f32_16x16x32_bf16 v[20:23], v[162:165], v[198:201], v[20:23]
	v_mfma_f32_16x16x32_bf16 v[16:19], v[170:173], v[194:197], v[16:19]
	v_mfma_f32_16x16x32_bf16 v[16:19], v[174:177], v[198:201], v[16:19]
	v_mfma_f32_16x16x32_bf16 v[4:7], v[158:161], v[202:205], v[4:7]
	v_mfma_f32_16x16x32_bf16 v[4:7], v[162:165], v[206:209], v[4:7]
	v_mfma_f32_16x16x32_bf16 v[0:3], v[170:173], v[202:205], v[0:3]
	v_mfma_f32_16x16x32_bf16 v[0:3], v[174:177], v[206:209], v[0:3]
	s_barrier
	s_add_i32 s68, s68, 2
	s_add_u32 s80, s80, 0x100
	s_addc_u32 s81, s81, 0
	s_add_u32 s60, s60, 0x100
	s_addc_u32 s61, s61, 0
.LBB0_297:
	s_add_u32 s67, s80, 0xfff00080
	s_addc_u32 s69, s81, -1
	s_add_i32 s70, 0, 0x10000
	s_cmp_eq_u32 s68, 28
	s_cselect_b32 s85, s23, s69
	s_cselect_b32 s84, s56, s67
	s_cselect_b32 s83, s21, s61
	s_cselect_b32 s82, s57, s60
	s_add_i32 s67, 0, 0x14000
	v_add_u32_e32 v140, s70, v168
	v_add_u32_e32 v166, s67, v168
	ds_read_b128 v[80:83], v140
	ds_read_b128 v[116:119], v140 offset:1024
	ds_read_b128 v[136:139], v140 offset:2048
	ds_read_b128 v[140:143], v140 offset:3072
	ds_read_b128 v[158:161], v166
	ds_read_b128 v[162:165], v166 offset:1024
	ds_read_b128 v[170:173], v166 offset:2048
	ds_read_b128 v[174:177], v166 offset:3072
	v_lshl_add_u64 v[166:167], s[80:81], 0, v[154:155]
	s_add_i32 m0, s26, 0xc000
	ds_read_b128 v[178:181], v169
	ds_read_b128 v[182:185], v169 offset:1024
	ds_read_b128 v[186:189], v169 offset:2048
	ds_read_b128 v[190:193], v169 offset:3072
	ds_read_b128 v[194:197], v169 offset:4096
	ds_read_b128 v[198:201], v169 offset:5120
	ds_read_b128 v[202:205], v169 offset:6144
	ds_read_b128 v[206:209], v169 offset:7168
	global_load_lds_dwordx4 v[166:167], off
	v_lshl_add_u64 v[166:167], s[80:81], 0, v[156:157]
	s_add_i32 m0, s26, 0xe000
	s_nop 0
	global_load_lds_dwordx4 v[166:167], off
	s_waitcnt vmcnt(8)
	s_waitcnt lgkmcnt(0)
	s_barrier
	s_waitcnt lgkmcnt(0)
	v_mfma_f32_16x16x32_bf16 v[132:135], v[80:83], v[178:181], v[132:135]
	v_mfma_f32_16x16x32_bf16 v[132:135], v[116:119], v[182:185], v[132:135]
	v_mfma_f32_16x16x32_bf16 v[128:131], v[136:139], v[178:181], v[128:131]
	v_mfma_f32_16x16x32_bf16 v[128:131], v[140:143], v[182:185], v[128:131]
	v_mfma_f32_16x16x32_bf16 v[112:115], v[80:83], v[186:189], v[112:115]
	v_mfma_f32_16x16x32_bf16 v[112:115], v[116:119], v[190:193], v[112:115]
	v_mfma_f32_16x16x32_bf16 v[108:111], v[136:139], v[186:189], v[108:111]
	v_mfma_f32_16x16x32_bf16 v[108:111], v[140:143], v[190:193], v[108:111]
	v_mfma_f32_16x16x32_bf16 v[96:99], v[80:83], v[194:197], v[96:99]
	v_mfma_f32_16x16x32_bf16 v[96:99], v[116:119], v[198:201], v[96:99]
	v_mfma_f32_16x16x32_bf16 v[92:95], v[136:139], v[194:197], v[92:95]
	v_mfma_f32_16x16x32_bf16 v[92:95], v[140:143], v[198:201], v[92:95]
	v_mfma_f32_16x16x32_bf16 v[76:79], v[80:83], v[202:205], v[76:79]
	v_mfma_f32_16x16x32_bf16 v[76:79], v[116:119], v[206:209], v[76:79]
	v_mfma_f32_16x16x32_bf16 v[72:75], v[136:139], v[202:205], v[72:75]
	v_mfma_f32_16x16x32_bf16 v[72:75], v[140:143], v[206:209], v[72:75]
	v_mfma_f32_16x16x32_bf16 v[124:127], v[158:161], v[178:181], v[124:127]
	v_mfma_f32_16x16x32_bf16 v[124:127], v[162:165], v[182:185], v[124:127]
	v_mfma_f32_16x16x32_bf16 v[120:123], v[170:173], v[178:181], v[120:123]
	v_mfma_f32_16x16x32_bf16 v[120:123], v[174:177], v[182:185], v[120:123]
	v_mfma_f32_16x16x32_bf16 v[104:107], v[158:161], v[186:189], v[104:107]
	v_mfma_f32_16x16x32_bf16 v[104:107], v[162:165], v[190:193], v[104:107]
	v_mfma_f32_16x16x32_bf16 v[100:103], v[170:173], v[186:189], v[100:103]
	v_mfma_f32_16x16x32_bf16 v[100:103], v[174:177], v[190:193], v[100:103]
	v_mfma_f32_16x16x32_bf16 v[88:91], v[158:161], v[194:197], v[88:91]
	v_mfma_f32_16x16x32_bf16 v[88:91], v[162:165], v[198:201], v[88:91]
	v_mfma_f32_16x16x32_bf16 v[84:87], v[170:173], v[194:197], v[84:87]
	v_mfma_f32_16x16x32_bf16 v[84:87], v[174:177], v[198:201], v[84:87]
	v_mfma_f32_16x16x32_bf16 v[68:71], v[158:161], v[202:205], v[68:71]
	v_mfma_f32_16x16x32_bf16 v[68:71], v[162:165], v[206:209], v[68:71]
	v_mfma_f32_16x16x32_bf16 v[64:67], v[170:173], v[202:205], v[64:67]
	v_mfma_f32_16x16x32_bf16 v[64:67], v[174:177], v[206:209], v[64:67]
	s_barrier
	s_add_i32 s69, s70, s24
	v_lshl_add_u64 v[166:167], s[82:83], 0, v[146:147]
	s_mov_b32 m0, s69
	ds_read_b128 v[178:181], v169 offset:16384
	ds_read_b128 v[182:185], v169 offset:17408
	ds_read_b128 v[186:189], v169 offset:18432
	ds_read_b128 v[190:193], v169 offset:19456
	ds_read_b128 v[194:197], v169 offset:20480
	ds_read_b128 v[198:201], v169 offset:21504
	ds_read_b128 v[202:205], v169 offset:22528
	ds_read_b128 v[206:209], v169 offset:23552
	global_load_lds_dwordx4 v[166:167], off
	s_add_i32 m0, s69, 0x2000
	s_add_u32 s70, s82, 0x80000
	v_lshl_add_u64 v[210:211], s[82:83], 0, v[150:151]
	s_addc_u32 s71, s83, 0
	s_add_i32 s67, s67, s24
	global_load_lds_dwordx4 v[210:211], off
	v_lshl_add_u64 v[212:213], s[70:71], 0, v[146:147]
	s_mov_b32 m0, s67
	v_lshl_add_u64 v[214:215], s[84:85], 0, v[148:149]
	global_load_lds_dwordx4 v[212:213], off
	v_lshl_add_u64 v[212:213], s[70:71], 0, v[150:151]
	s_add_i32 m0, s67, 0x2000
	s_nop 0
	global_load_lds_dwordx4 v[212:213], off
	v_lshl_add_u64 v[212:213], s[84:85], 0, v[144:145]
	s_mov_b32 m0, s26
	s_nop 0
	global_load_lds_dwordx4 v[212:213], off
	s_mov_b32 m0, s28
	s_nop 0
	global_load_lds_dwordx4 v[214:215], off
	s_waitcnt vmcnt(8)
	s_waitcnt lgkmcnt(0)
	s_barrier
	s_waitcnt lgkmcnt(0)
	v_mfma_f32_16x16x32_bf16 v[60:63], v[80:83], v[178:181], v[60:63]
	v_mfma_f32_16x16x32_bf16 v[60:63], v[116:119], v[182:185], v[60:63]
	v_mfma_f32_16x16x32_bf16 v[56:59], v[136:139], v[178:181], v[56:59]
	v_mfma_f32_16x16x32_bf16 v[56:59], v[140:143], v[182:185], v[56:59]
	v_mfma_f32_16x16x32_bf16 v[44:47], v[80:83], v[186:189], v[44:47]
	v_mfma_f32_16x16x32_bf16 v[44:47], v[116:119], v[190:193], v[44:47]
	v_mfma_f32_16x16x32_bf16 v[40:43], v[136:139], v[186:189], v[40:43]
	v_mfma_f32_16x16x32_bf16 v[40:43], v[140:143], v[190:193], v[40:43]
	v_mfma_f32_16x16x32_bf16 v[28:31], v[80:83], v[194:197], v[28:31]
	v_mfma_f32_16x16x32_bf16 v[28:31], v[116:119], v[198:201], v[28:31]
	v_mfma_f32_16x16x32_bf16 v[24:27], v[136:139], v[194:197], v[24:27]
	v_mfma_f32_16x16x32_bf16 v[24:27], v[140:143], v[198:201], v[24:27]
	v_mfma_f32_16x16x32_bf16 v[12:15], v[80:83], v[202:205], v[12:15]
	v_mfma_f32_16x16x32_bf16 v[12:15], v[116:119], v[206:209], v[12:15]
	v_mfma_f32_16x16x32_bf16 v[8:11], v[136:139], v[202:205], v[8:11]
	v_mfma_f32_16x16x32_bf16 v[8:11], v[140:143], v[206:209], v[8:11]
	v_mfma_f32_16x16x32_bf16 v[52:55], v[158:161], v[178:181], v[52:55]
	v_mfma_f32_16x16x32_bf16 v[52:55], v[162:165], v[182:185], v[52:55]
	v_mfma_f32_16x16x32_bf16 v[48:51], v[170:173], v[178:181], v[48:51]
	v_mfma_f32_16x16x32_bf16 v[48:51], v[174:177], v[182:185], v[48:51]
	v_mfma_f32_16x16x32_bf16 v[36:39], v[158:161], v[186:189], v[36:39]
	v_mfma_f32_16x16x32_bf16 v[36:39], v[162:165], v[190:193], v[36:39]
	v_mfma_f32_16x16x32_bf16 v[32:35], v[170:173], v[186:189], v[32:35]
	v_mfma_f32_16x16x32_bf16 v[32:35], v[174:177], v[190:193], v[32:35]
	v_mfma_f32_16x16x32_bf16 v[20:23], v[158:161], v[194:197], v[20:23]
	v_mfma_f32_16x16x32_bf16 v[20:23], v[162:165], v[198:201], v[20:23]
	v_mfma_f32_16x16x32_bf16 v[16:19], v[170:173], v[194:197], v[16:19]
	v_mfma_f32_16x16x32_bf16 v[16:19], v[174:177], v[198:201], v[16:19]
	v_mfma_f32_16x16x32_bf16 v[4:7], v[158:161], v[202:205], v[4:7]
	v_mfma_f32_16x16x32_bf16 v[4:7], v[162:165], v[206:209], v[4:7]
	v_mfma_f32_16x16x32_bf16 v[0:3], v[170:173], v[202:205], v[0:3]
	v_mfma_f32_16x16x32_bf16 v[0:3], v[174:177], v[206:209], v[0:3]
	s_barrier
	s_add_i32 s67, 0, 0x18000
	s_add_i32 s69, 0, 0x1c000
	v_add_u32_e32 v140, s67, v168
	v_add_u32_e32 v174, s69, v168
	ds_read_b128 v[80:83], v140
	ds_read_b128 v[116:119], v140 offset:1024
	ds_read_b128 v[136:139], v140 offset:2048
	ds_read_b128 v[140:143], v140 offset:3072
	ds_read_b128 v[158:161], v174
	ds_read_b128 v[162:165], v174 offset:1024
	ds_read_b128 v[170:173], v174 offset:2048
	ds_read_b128 v[174:177], v174 offset:3072
	s_add_u32 s70, s84, 0x100000
	s_addc_u32 s71, s85, 0
	s_mov_b32 m0, s29
	v_lshl_add_u64 v[218:219], s[70:71], 0, v[144:145]
	ds_read_b128 v[178:181], v169 offset:32768
	ds_read_b128 v[182:185], v169 offset:33792
	ds_read_b128 v[186:189], v169 offset:34816
	ds_read_b128 v[190:193], v169 offset:35840
	ds_read_b128 v[194:197], v169 offset:36864
	ds_read_b128 v[198:201], v169 offset:37888
	ds_read_b128 v[202:205], v169 offset:38912
	ds_read_b128 v[206:209], v169 offset:39936
	global_load_lds_dwordx4 v[218:219], off
	v_lshl_add_u64 v[218:219], s[70:71], 0, v[148:149]
	s_mov_b32 m0, s34
	s_nop 0
	global_load_lds_dwordx4 v[218:219], off
	s_waitcnt vmcnt(8)
	s_waitcnt lgkmcnt(0)
	s_barrier
	s_waitcnt lgkmcnt(0)
	v_mfma_f32_16x16x32_bf16 v[132:135], v[80:83], v[178:181], v[132:135]
	v_mfma_f32_16x16x32_bf16 v[132:135], v[116:119], v[182:185], v[132:135]
	v_mfma_f32_16x16x32_bf16 v[128:131], v[136:139], v[178:181], v[128:131]
	v_mfma_f32_16x16x32_bf16 v[128:131], v[140:143], v[182:185], v[128:131]
	v_mfma_f32_16x16x32_bf16 v[112:115], v[80:83], v[186:189], v[112:115]
	v_mfma_f32_16x16x32_bf16 v[112:115], v[116:119], v[190:193], v[112:115]
	v_mfma_f32_16x16x32_bf16 v[108:111], v[136:139], v[186:189], v[108:111]
	v_mfma_f32_16x16x32_bf16 v[108:111], v[140:143], v[190:193], v[108:111]
	v_mfma_f32_16x16x32_bf16 v[96:99], v[80:83], v[194:197], v[96:99]
	v_mfma_f32_16x16x32_bf16 v[96:99], v[116:119], v[198:201], v[96:99]
	v_mfma_f32_16x16x32_bf16 v[92:95], v[136:139], v[194:197], v[92:95]
	v_mfma_f32_16x16x32_bf16 v[92:95], v[140:143], v[198:201], v[92:95]
	v_mfma_f32_16x16x32_bf16 v[76:79], v[80:83], v[202:205], v[76:79]
	v_mfma_f32_16x16x32_bf16 v[76:79], v[116:119], v[206:209], v[76:79]
	v_mfma_f32_16x16x32_bf16 v[72:75], v[136:139], v[202:205], v[72:75]
	v_mfma_f32_16x16x32_bf16 v[72:75], v[140:143], v[206:209], v[72:75]
	v_mfma_f32_16x16x32_bf16 v[124:127], v[158:161], v[178:181], v[124:127]
	v_mfma_f32_16x16x32_bf16 v[124:127], v[162:165], v[182:185], v[124:127]
	v_mfma_f32_16x16x32_bf16 v[120:123], v[170:173], v[178:181], v[120:123]
	v_mfma_f32_16x16x32_bf16 v[120:123], v[174:177], v[182:185], v[120:123]
	v_mfma_f32_16x16x32_bf16 v[104:107], v[158:161], v[186:189], v[104:107]
	v_mfma_f32_16x16x32_bf16 v[104:107], v[162:165], v[190:193], v[104:107]
	v_mfma_f32_16x16x32_bf16 v[100:103], v[170:173], v[186:189], v[100:103]
	v_mfma_f32_16x16x32_bf16 v[100:103], v[174:177], v[190:193], v[100:103]
	v_mfma_f32_16x16x32_bf16 v[88:91], v[158:161], v[194:197], v[88:91]
	v_mfma_f32_16x16x32_bf16 v[88:91], v[162:165], v[198:201], v[88:91]
	v_mfma_f32_16x16x32_bf16 v[84:87], v[170:173], v[194:197], v[84:87]
	v_mfma_f32_16x16x32_bf16 v[84:87], v[174:177], v[198:201], v[84:87]
	v_mfma_f32_16x16x32_bf16 v[68:71], v[158:161], v[202:205], v[68:71]
	v_mfma_f32_16x16x32_bf16 v[68:71], v[162:165], v[206:209], v[68:71]
	v_mfma_f32_16x16x32_bf16 v[64:67], v[170:173], v[202:205], v[64:67]
	v_mfma_f32_16x16x32_bf16 v[64:67], v[174:177], v[206:209], v[64:67]
	s_barrier
	s_add_i32 s67, s67, s24
	v_lshl_add_u64 v[166:167], v[166:167], 0, s[30:31]
	s_mov_b32 m0, s67
	ds_read_b128 v[178:181], v169 offset:49152
	ds_read_b128 v[182:185], v169 offset:50176
	ds_read_b128 v[186:189], v169 offset:51200
	ds_read_b128 v[190:193], v169 offset:52224
	ds_read_b128 v[194:197], v169 offset:53248
	ds_read_b128 v[198:201], v169 offset:54272
	ds_read_b128 v[202:205], v169 offset:55296
	ds_read_b128 v[206:209], v169 offset:56320
	global_load_lds_dwordx4 v[166:167], off
	s_add_i32 m0, s67, 0x2000
	s_add_u32 s70, s82, 0x80080
	v_lshl_add_u64 v[166:167], v[210:211], 0, s[30:31]
	s_addc_u32 s71, s83, 0
	s_add_i32 s67, s69, s24
	global_load_lds_dwordx4 v[166:167], off
	v_lshl_add_u64 v[166:167], s[70:71], 0, v[146:147]
	s_mov_b32 m0, s67
	s_nop 0
	global_load_lds_dwordx4 v[166:167], off
	v_lshl_add_u64 v[166:167], s[70:71], 0, v[150:151]
	s_add_i32 m0, s67, 0x2000
	s_nop 0
	global_load_lds_dwordx4 v[166:167], off
	v_lshl_add_u64 v[166:167], v[212:213], 0, s[30:31]
	s_mov_b32 m0, s39
	s_nop 0
	global_load_lds_dwordx4 v[166:167], off
	v_lshl_add_u64 v[166:167], v[214:215], 0, s[30:31]
	s_mov_b32 m0, s40
	s_nop 0
	global_load_lds_dwordx4 v[166:167], off
	s_waitcnt vmcnt(8)
	s_waitcnt lgkmcnt(0)
	s_barrier
	s_waitcnt lgkmcnt(0)
	v_mfma_f32_16x16x32_bf16 v[60:63], v[80:83], v[178:181], v[60:63]
	v_mfma_f32_16x16x32_bf16 v[60:63], v[116:119], v[182:185], v[60:63]
	v_mfma_f32_16x16x32_bf16 v[56:59], v[136:139], v[178:181], v[56:59]
	v_mfma_f32_16x16x32_bf16 v[56:59], v[140:143], v[182:185], v[56:59]
	v_mfma_f32_16x16x32_bf16 v[44:47], v[80:83], v[186:189], v[44:47]
	v_mfma_f32_16x16x32_bf16 v[44:47], v[116:119], v[190:193], v[44:47]
	v_mfma_f32_16x16x32_bf16 v[40:43], v[136:139], v[186:189], v[40:43]
	v_mfma_f32_16x16x32_bf16 v[40:43], v[140:143], v[190:193], v[40:43]
	v_mfma_f32_16x16x32_bf16 v[28:31], v[80:83], v[194:197], v[28:31]
	v_mfma_f32_16x16x32_bf16 v[28:31], v[116:119], v[198:201], v[28:31]
	v_mfma_f32_16x16x32_bf16 v[24:27], v[136:139], v[194:197], v[24:27]
	v_mfma_f32_16x16x32_bf16 v[24:27], v[140:143], v[198:201], v[24:27]
	v_mfma_f32_16x16x32_bf16 v[12:15], v[80:83], v[202:205], v[12:15]
	v_mfma_f32_16x16x32_bf16 v[12:15], v[116:119], v[206:209], v[12:15]
	v_mfma_f32_16x16x32_bf16 v[8:11], v[136:139], v[202:205], v[8:11]
	v_mfma_f32_16x16x32_bf16 v[8:11], v[140:143], v[206:209], v[8:11]
	v_mfma_f32_16x16x32_bf16 v[52:55], v[158:161], v[178:181], v[52:55]
	v_mfma_f32_16x16x32_bf16 v[52:55], v[162:165], v[182:185], v[52:55]
	v_mfma_f32_16x16x32_bf16 v[48:51], v[170:173], v[178:181], v[48:51]
	v_mfma_f32_16x16x32_bf16 v[48:51], v[174:177], v[182:185], v[48:51]
	v_mfma_f32_16x16x32_bf16 v[36:39], v[158:161], v[186:189], v[36:39]
	v_mfma_f32_16x16x32_bf16 v[36:39], v[162:165], v[190:193], v[36:39]
	v_mfma_f32_16x16x32_bf16 v[32:35], v[170:173], v[186:189], v[32:35]
	v_mfma_f32_16x16x32_bf16 v[32:35], v[174:177], v[190:193], v[32:35]
	v_mfma_f32_16x16x32_bf16 v[20:23], v[158:161], v[194:197], v[20:23]
	v_mfma_f32_16x16x32_bf16 v[20:23], v[162:165], v[198:201], v[20:23]
	v_mfma_f32_16x16x32_bf16 v[16:19], v[170:173], v[194:197], v[16:19]
	v_mfma_f32_16x16x32_bf16 v[16:19], v[174:177], v[198:201], v[16:19]
	v_mfma_f32_16x16x32_bf16 v[4:7], v[158:161], v[202:205], v[4:7]
	v_mfma_f32_16x16x32_bf16 v[4:7], v[162:165], v[206:209], v[4:7]
	v_mfma_f32_16x16x32_bf16 v[0:3], v[170:173], v[202:205], v[0:3]
	v_mfma_f32_16x16x32_bf16 v[0:3], v[174:177], v[206:209], v[0:3]
	s_barrier
	s_add_i32 s68, s68, 2
	s_add_u32 s80, s80, 0x100
	s_addc_u32 s81, s81, 0
	s_add_u32 s60, s60, 0x100
	s_addc_u32 s61, s61, 0
	s_cmp_gt_u32 s68, 29
	s_cbranch_scc0 .LBB0_297
	s_and_b64 vcc, exec, s[18:19]
	s_cbranch_vccz .LBB0_300
	s_barrier

.LBB0_384:
	s_ashr_i32 s73, s72, 31
	s_lshl_b64 s[74:75], s[72:73], 20
	s_add_u32 s74, s2, s74
	s_addc_u32 s75, s3, s75
	s_and_b64 s[76:77], s[4:5], exec
	s_cselect_b32 s73, s75, s81
	s_cselect_b32 s79, s74, s80
	s_ashr_i32 s23, s22, 31
	s_lshl_b64 s[76:77], s[22:23], 20
	s_add_u32 s76, s14, s76
	s_addc_u32 s77, s15, s77
	s_and_b64 s[84:85], s[4:5], exec
	s_cselect_b32 s23, s77, s83
	s_cselect_b32 s86, s76, s82
	s_add_u32 s80, s80, 0x80080
	s_addc_u32 s81, s81, 0
	s_add_u32 s87, s82, 0x100
	s_addc_u32 s88, s83, 0
	s_mov_b32 s89, -2
	s_add_u32 s67, s80, 0xfff80080
	s_addc_u32 s82, s81, -1
	s_add_i32 s90, 0, 0x10000
	s_cmp_eq_u32 s89, 28
	s_cselect_b32 s85, s73, s82
	s_cselect_b32 s84, s79, s67
	s_cselect_b32 s83, s23, s88
	s_cselect_b32 s82, s86, s87
	s_add_i32 s67, 0, 0x14000
	v_add_u32_e32 v140, s90, v186
	v_add_u32_e32 v156, s67, v186
	ds_read_b128 v[128:131], v140
	ds_read_b128 v[132:135], v140 offset:1024
	ds_read_b128 v[136:139], v140 offset:2048
	ds_read_b128 v[140:143], v140 offset:3072
	ds_read_b128 v[144:147], v156
	ds_read_b128 v[148:151], v156 offset:1024
	ds_read_b128 v[152:155], v156 offset:2048
	ds_read_b128 v[156:159], v156 offset:3072
	v_lshl_add_u64 v[208:209], s[80:81], 0, v[178:179]
	s_add_i32 m0, s29, 0xc000
	ds_read_b128 v[160:163], v187
	ds_read_b128 v[164:167], v187 offset:1024
	ds_read_b128 v[182:185], v187 offset:2048
	ds_read_b128 v[188:191], v187 offset:3072
	ds_read_b128 v[192:195], v187 offset:4096
	ds_read_b128 v[196:199], v187 offset:5120
	ds_read_b128 v[200:203], v187 offset:6144
	ds_read_b128 v[204:207], v187 offset:7168
	global_load_lds_dwordx4 v[208:209], off
	v_lshl_add_u64 v[208:209], s[80:81], 0, v[180:181]
	s_add_i32 m0, s29, 0xe000
	s_nop 0
	global_load_lds_dwordx4 v[208:209], off
	s_waitcnt vmcnt(8)
	s_waitcnt lgkmcnt(0)
	s_barrier
	s_waitcnt lgkmcnt(0)
	v_mfma_f32_16x16x32_bf16 v[124:127], v[128:131], v[160:163], 0
	v_mfma_f32_16x16x32_bf16 v[124:127], v[132:135], v[164:167], v[124:127]
	v_mfma_f32_16x16x32_bf16 v[120:123], v[136:139], v[160:163], 0
	v_mfma_f32_16x16x32_bf16 v[120:123], v[140:143], v[164:167], v[120:123]
	v_mfma_f32_16x16x32_bf16 v[108:111], v[128:131], v[182:185], 0
	v_mfma_f32_16x16x32_bf16 v[108:111], v[132:135], v[188:191], v[108:111]
	v_mfma_f32_16x16x32_bf16 v[104:107], v[136:139], v[182:185], 0
	v_mfma_f32_16x16x32_bf16 v[104:107], v[140:143], v[188:191], v[104:107]
	v_mfma_f32_16x16x32_bf16 v[92:95], v[128:131], v[192:195], 0
	v_mfma_f32_16x16x32_bf16 v[92:95], v[132:135], v[196:199], v[92:95]
	v_mfma_f32_16x16x32_bf16 v[88:91], v[136:139], v[192:195], 0
	v_mfma_f32_16x16x32_bf16 v[88:91], v[140:143], v[196:199], v[88:91]
	v_mfma_f32_16x16x32_bf16 v[76:79], v[128:131], v[200:203], 0
	v_mfma_f32_16x16x32_bf16 v[76:79], v[132:135], v[204:207], v[76:79]
	v_mfma_f32_16x16x32_bf16 v[72:75], v[136:139], v[200:203], 0
	v_mfma_f32_16x16x32_bf16 v[72:75], v[140:143], v[204:207], v[72:75]
	v_mfma_f32_16x16x32_bf16 v[116:119], v[144:147], v[160:163], 0
	v_mfma_f32_16x16x32_bf16 v[116:119], v[148:151], v[164:167], v[116:119]
	v_mfma_f32_16x16x32_bf16 v[112:115], v[152:155], v[160:163], 0
	v_mfma_f32_16x16x32_bf16 v[112:115], v[156:159], v[164:167], v[112:115]
	v_mfma_f32_16x16x32_bf16 v[100:103], v[144:147], v[182:185], 0
	v_mfma_f32_16x16x32_bf16 v[100:103], v[148:151], v[188:191], v[100:103]
	v_mfma_f32_16x16x32_bf16 v[96:99], v[152:155], v[182:185], 0
	v_mfma_f32_16x16x32_bf16 v[96:99], v[156:159], v[188:191], v[96:99]
	v_mfma_f32_16x16x32_bf16 v[84:87], v[144:147], v[192:195], 0
	v_mfma_f32_16x16x32_bf16 v[84:87], v[148:151], v[196:199], v[84:87]
	v_mfma_f32_16x16x32_bf16 v[80:83], v[152:155], v[192:195], 0
	v_mfma_f32_16x16x32_bf16 v[80:83], v[156:159], v[196:199], v[80:83]
	v_mfma_f32_16x16x32_bf16 v[68:71], v[144:147], v[200:203], 0
	v_mfma_f32_16x16x32_bf16 v[68:71], v[148:151], v[204:207], v[68:71]
	v_mfma_f32_16x16x32_bf16 v[64:67], v[152:155], v[200:203], 0
	v_mfma_f32_16x16x32_bf16 v[64:67], v[156:159], v[204:207], v[64:67]
	s_barrier
	s_add_i32 s90, s90, s24
	v_lshl_add_u64 v[208:209], s[82:83], 0, v[172:173]
	s_mov_b32 m0, s90
	ds_read_b128 v[160:163], v187 offset:16384
	ds_read_b128 v[164:167], v187 offset:17408
	ds_read_b128 v[182:185], v187 offset:18432
	ds_read_b128 v[188:191], v187 offset:19456
	ds_read_b128 v[192:195], v187 offset:20480
	ds_read_b128 v[196:199], v187 offset:21504
	ds_read_b128 v[200:203], v187 offset:22528
	ds_read_b128 v[204:207], v187 offset:23552
	global_load_lds_dwordx4 v[208:209], off
	s_add_i32 m0, s90, 0x2000
	s_add_u32 s90, s82, 0x80000
	v_lshl_add_u64 v[210:211], s[82:83], 0, v[168:169]
	s_addc_u32 s91, s83, 0
	s_add_i32 s67, s67, s24
	global_load_lds_dwordx4 v[210:211], off
	v_lshl_add_u64 v[212:213], s[90:91], 0, v[172:173]
	s_mov_b32 m0, s67
	v_lshl_add_u64 v[214:215], s[84:85], 0, v[170:171]
	global_load_lds_dwordx4 v[212:213], off
	v_lshl_add_u64 v[212:213], s[90:91], 0, v[168:169]
	s_add_i32 m0, s67, 0x2000
	s_nop 0
	global_load_lds_dwordx4 v[212:213], off
	v_lshl_add_u64 v[212:213], s[84:85], 0, v[174:175]
	s_mov_b32 m0, s29
	s_nop 0
	global_load_lds_dwordx4 v[212:213], off
	s_mov_b32 m0, s34
	s_nop 0
	global_load_lds_dwordx4 v[214:215], off
	s_waitcnt vmcnt(8)
	s_waitcnt lgkmcnt(0)
	s_barrier
	s_waitcnt lgkmcnt(0)
	v_mfma_f32_16x16x32_bf16 v[60:63], v[128:131], v[160:163], 0
	v_mfma_f32_16x16x32_bf16 v[60:63], v[132:135], v[164:167], v[60:63]
	v_mfma_f32_16x16x32_bf16 v[56:59], v[136:139], v[160:163], 0
	v_mfma_f32_16x16x32_bf16 v[56:59], v[140:143], v[164:167], v[56:59]
	v_mfma_f32_16x16x32_bf16 v[44:47], v[128:131], v[182:185], 0
	v_mfma_f32_16x16x32_bf16 v[44:47], v[132:135], v[188:191], v[44:47]
	v_mfma_f32_16x16x32_bf16 v[40:43], v[136:139], v[182:185], 0
	v_mfma_f32_16x16x32_bf16 v[40:43], v[140:143], v[188:191], v[40:43]
	v_mfma_f32_16x16x32_bf16 v[28:31], v[128:131], v[192:195], 0
	v_mfma_f32_16x16x32_bf16 v[28:31], v[132:135], v[196:199], v[28:31]
	v_mfma_f32_16x16x32_bf16 v[24:27], v[136:139], v[192:195], 0
	v_mfma_f32_16x16x32_bf16 v[24:27], v[140:143], v[196:199], v[24:27]
	v_mfma_f32_16x16x32_bf16 v[12:15], v[128:131], v[200:203], 0
	v_mfma_f32_16x16x32_bf16 v[12:15], v[132:135], v[204:207], v[12:15]
	v_mfma_f32_16x16x32_bf16 v[8:11], v[136:139], v[200:203], 0
	v_mfma_f32_16x16x32_bf16 v[8:11], v[140:143], v[204:207], v[8:11]
	v_mfma_f32_16x16x32_bf16 v[52:55], v[144:147], v[160:163], 0
	v_mfma_f32_16x16x32_bf16 v[52:55], v[148:151], v[164:167], v[52:55]
	v_mfma_f32_16x16x32_bf16 v[48:51], v[152:155], v[160:163], 0
	v_mfma_f32_16x16x32_bf16 v[48:51], v[156:159], v[164:167], v[48:51]
	v_mfma_f32_16x16x32_bf16 v[36:39], v[144:147], v[182:185], 0
	v_mfma_f32_16x16x32_bf16 v[36:39], v[148:151], v[188:191], v[36:39]
	v_mfma_f32_16x16x32_bf16 v[32:35], v[152:155], v[182:185], 0
	v_mfma_f32_16x16x32_bf16 v[32:35], v[156:159], v[188:191], v[32:35]
	v_mfma_f32_16x16x32_bf16 v[20:23], v[144:147], v[192:195], 0
	v_mfma_f32_16x16x32_bf16 v[20:23], v[148:151], v[196:199], v[20:23]
	v_mfma_f32_16x16x32_bf16 v[16:19], v[152:155], v[192:195], 0
	v_mfma_f32_16x16x32_bf16 v[16:19], v[156:159], v[196:199], v[16:19]
	v_mfma_f32_16x16x32_bf16 v[4:7], v[144:147], v[200:203], 0
	v_mfma_f32_16x16x32_bf16 v[4:7], v[148:151], v[204:207], v[4:7]
	v_mfma_f32_16x16x32_bf16 v[0:3], v[152:155], v[200:203], 0
	v_mfma_f32_16x16x32_bf16 v[0:3], v[156:159], v[204:207], v[0:3]
	s_barrier
	s_add_i32 s67, 0, 0x18000
	s_add_i32 s90, 0, 0x1c000
	v_add_u32_e32 v140, s67, v186
	v_add_u32_e32 v156, s90, v186
	ds_read_b128 v[128:131], v140
	ds_read_b128 v[132:135], v140 offset:1024
	ds_read_b128 v[136:139], v140 offset:2048
	ds_read_b128 v[140:143], v140 offset:3072
	ds_read_b128 v[144:147], v156
	ds_read_b128 v[148:151], v156 offset:1024
	ds_read_b128 v[152:155], v156 offset:2048
	ds_read_b128 v[156:159], v156 offset:3072
	s_add_u32 s84, s84, 0x80000
	s_addc_u32 s85, s85, 0
	s_mov_b32 m0, s35
	v_lshl_add_u64 v[218:219], s[84:85], 0, v[174:175]
	ds_read_b128 v[160:163], v187 offset:32768
	ds_read_b128 v[164:167], v187 offset:33792
	ds_read_b128 v[182:185], v187 offset:34816
	ds_read_b128 v[188:191], v187 offset:35840
	ds_read_b128 v[192:195], v187 offset:36864
	ds_read_b128 v[196:199], v187 offset:37888
	ds_read_b128 v[200:203], v187 offset:38912
	ds_read_b128 v[204:207], v187 offset:39936
	global_load_lds_dwordx4 v[218:219], off
	v_lshl_add_u64 v[218:219], s[84:85], 0, v[170:171]
	s_mov_b32 m0, s38
	s_nop 0
	global_load_lds_dwordx4 v[218:219], off
	s_waitcnt vmcnt(8)
	s_waitcnt lgkmcnt(0)
	s_barrier
	s_waitcnt lgkmcnt(0)
	v_mfma_f32_16x16x32_bf16 v[124:127], v[128:131], v[160:163], v[124:127]
	v_mfma_f32_16x16x32_bf16 v[124:127], v[132:135], v[164:167], v[124:127]
	v_mfma_f32_16x16x32_bf16 v[120:123], v[136:139], v[160:163], v[120:123]
	v_mfma_f32_16x16x32_bf16 v[120:123], v[140:143], v[164:167], v[120:123]
	v_mfma_f32_16x16x32_bf16 v[108:111], v[128:131], v[182:185], v[108:111]
	v_mfma_f32_16x16x32_bf16 v[108:111], v[132:135], v[188:191], v[108:111]
	v_mfma_f32_16x16x32_bf16 v[104:107], v[136:139], v[182:185], v[104:107]
	v_mfma_f32_16x16x32_bf16 v[104:107], v[140:143], v[188:191], v[104:107]
	v_mfma_f32_16x16x32_bf16 v[92:95], v[128:131], v[192:195], v[92:95]
	v_mfma_f32_16x16x32_bf16 v[92:95], v[132:135], v[196:199], v[92:95]
	v_mfma_f32_16x16x32_bf16 v[88:91], v[136:139], v[192:195], v[88:91]
	v_mfma_f32_16x16x32_bf16 v[88:91], v[140:143], v[196:199], v[88:91]
	v_mfma_f32_16x16x32_bf16 v[76:79], v[128:131], v[200:203], v[76:79]
	v_mfma_f32_16x16x32_bf16 v[76:79], v[132:135], v[204:207], v[76:79]
	v_mfma_f32_16x16x32_bf16 v[72:75], v[136:139], v[200:203], v[72:75]
	v_mfma_f32_16x16x32_bf16 v[72:75], v[140:143], v[204:207], v[72:75]
	v_mfma_f32_16x16x32_bf16 v[116:119], v[144:147], v[160:163], v[116:119]
	v_mfma_f32_16x16x32_bf16 v[116:119], v[148:151], v[164:167], v[116:119]
	v_mfma_f32_16x16x32_bf16 v[112:115], v[152:155], v[160:163], v[112:115]
	v_mfma_f32_16x16x32_bf16 v[112:115], v[156:159], v[164:167], v[112:115]
	v_mfma_f32_16x16x32_bf16 v[100:103], v[144:147], v[182:185], v[100:103]
	v_mfma_f32_16x16x32_bf16 v[100:103], v[148:151], v[188:191], v[100:103]
	v_mfma_f32_16x16x32_bf16 v[96:99], v[152:155], v[182:185], v[96:99]
	v_mfma_f32_16x16x32_bf16 v[96:99], v[156:159], v[188:191], v[96:99]
	v_mfma_f32_16x16x32_bf16 v[84:87], v[144:147], v[192:195], v[84:87]
	v_mfma_f32_16x16x32_bf16 v[84:87], v[148:151], v[196:199], v[84:87]
	v_mfma_f32_16x16x32_bf16 v[80:83], v[152:155], v[192:195], v[80:83]
	v_mfma_f32_16x16x32_bf16 v[80:83], v[156:159], v[196:199], v[80:83]
	v_mfma_f32_16x16x32_bf16 v[68:71], v[144:147], v[200:203], v[68:71]
	v_mfma_f32_16x16x32_bf16 v[68:71], v[148:151], v[204:207], v[68:71]
	v_mfma_f32_16x16x32_bf16 v[64:67], v[152:155], v[200:203], v[64:67]
	v_mfma_f32_16x16x32_bf16 v[64:67], v[156:159], v[204:207], v[64:67]
	s_barrier
	s_add_i32 s67, s67, s24
	v_lshl_add_u64 v[208:209], v[208:209], 0, s[30:31]
	s_mov_b32 m0, s67
	ds_read_b128 v[160:163], v187 offset:49152
	ds_read_b128 v[164:167], v187 offset:50176
	ds_read_b128 v[182:185], v187 offset:51200
	ds_read_b128 v[188:191], v187 offset:52224
	ds_read_b128 v[192:195], v187 offset:53248
	ds_read_b128 v[196:199], v187 offset:54272
	ds_read_b128 v[200:203], v187 offset:55296
	ds_read_b128 v[204:207], v187 offset:56320
	global_load_lds_dwordx4 v[208:209], off
	s_add_i32 m0, s67, 0x2000
	s_add_u32 s82, s82, 0x80080
	v_lshl_add_u64 v[208:209], v[210:211], 0, s[30:31]
	s_addc_u32 s83, s83, 0
	s_add_i32 s67, s90, s24
	global_load_lds_dwordx4 v[208:209], off
	v_lshl_add_u64 v[208:209], s[82:83], 0, v[172:173]
	s_mov_b32 m0, s67
	s_nop 0
	global_load_lds_dwordx4 v[208:209], off
	v_lshl_add_u64 v[208:209], s[82:83], 0, v[168:169]
	s_add_i32 m0, s67, 0x2000
	s_nop 0
	global_load_lds_dwordx4 v[208:209], off
	v_lshl_add_u64 v[208:209], v[212:213], 0, s[30:31]
	s_mov_b32 m0, s54
	s_nop 0
	global_load_lds_dwordx4 v[208:209], off
	v_lshl_add_u64 v[208:209], v[214:215], 0, s[30:31]
	s_mov_b32 m0, s55
	s_nop 0
	global_load_lds_dwordx4 v[208:209], off
	s_waitcnt vmcnt(8)
	s_waitcnt lgkmcnt(0)
	s_barrier
	s_waitcnt lgkmcnt(0)
	v_mfma_f32_16x16x32_bf16 v[60:63], v[128:131], v[160:163], v[60:63]
	v_mfma_f32_16x16x32_bf16 v[60:63], v[132:135], v[164:167], v[60:63]
	v_mfma_f32_16x16x32_bf16 v[56:59], v[136:139], v[160:163], v[56:59]
	v_mfma_f32_16x16x32_bf16 v[56:59], v[140:143], v[164:167], v[56:59]
	v_mfma_f32_16x16x32_bf16 v[44:47], v[128:131], v[182:185], v[44:47]
	v_mfma_f32_16x16x32_bf16 v[44:47], v[132:135], v[188:191], v[44:47]
	v_mfma_f32_16x16x32_bf16 v[40:43], v[136:139], v[182:185], v[40:43]
	v_mfma_f32_16x16x32_bf16 v[40:43], v[140:143], v[188:191], v[40:43]
	v_mfma_f32_16x16x32_bf16 v[28:31], v[128:131], v[192:195], v[28:31]
	v_mfma_f32_16x16x32_bf16 v[28:31], v[132:135], v[196:199], v[28:31]
	v_mfma_f32_16x16x32_bf16 v[24:27], v[136:139], v[192:195], v[24:27]
	v_mfma_f32_16x16x32_bf16 v[24:27], v[140:143], v[196:199], v[24:27]
	v_mfma_f32_16x16x32_bf16 v[12:15], v[128:131], v[200:203], v[12:15]
	v_mfma_f32_16x16x32_bf16 v[12:15], v[132:135], v[204:207], v[12:15]
	v_mfma_f32_16x16x32_bf16 v[8:11], v[136:139], v[200:203], v[8:11]
	v_mfma_f32_16x16x32_bf16 v[8:11], v[140:143], v[204:207], v[8:11]
	v_mfma_f32_16x16x32_bf16 v[52:55], v[144:147], v[160:163], v[52:55]
	v_mfma_f32_16x16x32_bf16 v[52:55], v[148:151], v[164:167], v[52:55]
	v_mfma_f32_16x16x32_bf16 v[48:51], v[152:155], v[160:163], v[48:51]
	v_mfma_f32_16x16x32_bf16 v[48:51], v[156:159], v[164:167], v[48:51]
	v_mfma_f32_16x16x32_bf16 v[36:39], v[144:147], v[182:185], v[36:39]
	v_mfma_f32_16x16x32_bf16 v[36:39], v[148:151], v[188:191], v[36:39]
	v_mfma_f32_16x16x32_bf16 v[32:35], v[152:155], v[182:185], v[32:35]
	v_mfma_f32_16x16x32_bf16 v[32:35], v[156:159], v[188:191], v[32:35]
	v_mfma_f32_16x16x32_bf16 v[20:23], v[144:147], v[192:195], v[20:23]
	v_mfma_f32_16x16x32_bf16 v[20:23], v[148:151], v[196:199], v[20:23]
	v_mfma_f32_16x16x32_bf16 v[16:19], v[152:155], v[192:195], v[16:19]
	v_mfma_f32_16x16x32_bf16 v[16:19], v[156:159], v[196:199], v[16:19]
	v_mfma_f32_16x16x32_bf16 v[4:7], v[144:147], v[200:203], v[4:7]
	v_mfma_f32_16x16x32_bf16 v[4:7], v[148:151], v[204:207], v[4:7]
	v_mfma_f32_16x16x32_bf16 v[0:3], v[152:155], v[200:203], v[0:3]
	v_mfma_f32_16x16x32_bf16 v[0:3], v[156:159], v[204:207], v[0:3]
	s_barrier
	s_add_i32 s89, s89, 2
	s_add_u32 s80, s80, 0x100
	s_addc_u32 s81, s81, 0
	s_add_u32 s87, s87, 0x100
	s_addc_u32 s88, s88, 0
.LBB0_385:
	s_add_u32 s67, s80, 0xfff80080
	s_addc_u32 s82, s81, -1
	s_add_i32 s90, 0, 0x10000
	s_cmp_eq_u32 s89, 28
	s_cselect_b32 s85, s73, s82
	s_cselect_b32 s84, s79, s67
	s_cselect_b32 s83, s23, s88
	s_cselect_b32 s82, s86, s87
	s_add_i32 s67, 0, 0x14000
	v_add_u32_e32 v140, s90, v186
	v_add_u32_e32 v156, s67, v186
	ds_read_b128 v[128:131], v140
	ds_read_b128 v[132:135], v140 offset:1024
	ds_read_b128 v[136:139], v140 offset:2048
	ds_read_b128 v[140:143], v140 offset:3072
	ds_read_b128 v[144:147], v156
	ds_read_b128 v[148:151], v156 offset:1024
	ds_read_b128 v[152:155], v156 offset:2048
	ds_read_b128 v[156:159], v156 offset:3072
	v_lshl_add_u64 v[208:209], s[80:81], 0, v[178:179]
	s_add_i32 m0, s29, 0xc000
	ds_read_b128 v[160:163], v187
	ds_read_b128 v[164:167], v187 offset:1024
	ds_read_b128 v[182:185], v187 offset:2048
	ds_read_b128 v[188:191], v187 offset:3072
	ds_read_b128 v[192:195], v187 offset:4096
	ds_read_b128 v[196:199], v187 offset:5120
	ds_read_b128 v[200:203], v187 offset:6144
	ds_read_b128 v[204:207], v187 offset:7168
	global_load_lds_dwordx4 v[208:209], off
	v_lshl_add_u64 v[208:209], s[80:81], 0, v[180:181]
	s_add_i32 m0, s29, 0xe000
	s_nop 0
	global_load_lds_dwordx4 v[208:209], off
	s_waitcnt vmcnt(8)
	s_waitcnt lgkmcnt(0)
	s_barrier
	s_waitcnt lgkmcnt(0)
	v_mfma_f32_16x16x32_bf16 v[124:127], v[128:131], v[160:163], v[124:127]
	v_mfma_f32_16x16x32_bf16 v[124:127], v[132:135], v[164:167], v[124:127]
	v_mfma_f32_16x16x32_bf16 v[120:123], v[136:139], v[160:163], v[120:123]
	v_mfma_f32_16x16x32_bf16 v[120:123], v[140:143], v[164:167], v[120:123]
	v_mfma_f32_16x16x32_bf16 v[108:111], v[128:131], v[182:185], v[108:111]
	v_mfma_f32_16x16x32_bf16 v[108:111], v[132:135], v[188:191], v[108:111]
	v_mfma_f32_16x16x32_bf16 v[104:107], v[136:139], v[182:185], v[104:107]
	v_mfma_f32_16x16x32_bf16 v[104:107], v[140:143], v[188:191], v[104:107]
	v_mfma_f32_16x16x32_bf16 v[92:95], v[128:131], v[192:195], v[92:95]
	v_mfma_f32_16x16x32_bf16 v[92:95], v[132:135], v[196:199], v[92:95]
	v_mfma_f32_16x16x32_bf16 v[88:91], v[136:139], v[192:195], v[88:91]
	v_mfma_f32_16x16x32_bf16 v[88:91], v[140:143], v[196:199], v[88:91]
	v_mfma_f32_16x16x32_bf16 v[76:79], v[128:131], v[200:203], v[76:79]
	v_mfma_f32_16x16x32_bf16 v[76:79], v[132:135], v[204:207], v[76:79]
	v_mfma_f32_16x16x32_bf16 v[72:75], v[136:139], v[200:203], v[72:75]
	v_mfma_f32_16x16x32_bf16 v[72:75], v[140:143], v[204:207], v[72:75]
	v_mfma_f32_16x16x32_bf16 v[116:119], v[144:147], v[160:163], v[116:119]
	v_mfma_f32_16x16x32_bf16 v[116:119], v[148:151], v[164:167], v[116:119]
	v_mfma_f32_16x16x32_bf16 v[112:115], v[152:155], v[160:163], v[112:115]
	v_mfma_f32_16x16x32_bf16 v[112:115], v[156:159], v[164:167], v[112:115]
	v_mfma_f32_16x16x32_bf16 v[100:103], v[144:147], v[182:185], v[100:103]
	v_mfma_f32_16x16x32_bf16 v[100:103], v[148:151], v[188:191], v[100:103]
	v_mfma_f32_16x16x32_bf16 v[96:99], v[152:155], v[182:185], v[96:99]
	v_mfma_f32_16x16x32_bf16 v[96:99], v[156:159], v[188:191], v[96:99]
	v_mfma_f32_16x16x32_bf16 v[84:87], v[144:147], v[192:195], v[84:87]
	v_mfma_f32_16x16x32_bf16 v[84:87], v[148:151], v[196:199], v[84:87]
	v_mfma_f32_16x16x32_bf16 v[80:83], v[152:155], v[192:195], v[80:83]
	v_mfma_f32_16x16x32_bf16 v[80:83], v[156:159], v[196:199], v[80:83]
	v_mfma_f32_16x16x32_bf16 v[68:71], v[144:147], v[200:203], v[68:71]
	v_mfma_f32_16x16x32_bf16 v[68:71], v[148:151], v[204:207], v[68:71]
	v_mfma_f32_16x16x32_bf16 v[64:67], v[152:155], v[200:203], v[64:67]
	v_mfma_f32_16x16x32_bf16 v[64:67], v[156:159], v[204:207], v[64:67]
	s_barrier
	s_add_i32 s90, s90, s24
	v_lshl_add_u64 v[208:209], s[82:83], 0, v[172:173]
	s_mov_b32 m0, s90
	ds_read_b128 v[160:163], v187 offset:16384
	ds_read_b128 v[164:167], v187 offset:17408
	ds_read_b128 v[182:185], v187 offset:18432
	ds_read_b128 v[188:191], v187 offset:19456
	ds_read_b128 v[192:195], v187 offset:20480
	ds_read_b128 v[196:199], v187 offset:21504
	ds_read_b128 v[200:203], v187 offset:22528
	ds_read_b128 v[204:207], v187 offset:23552
	global_load_lds_dwordx4 v[208:209], off
	s_add_i32 m0, s90, 0x2000
	s_add_u32 s90, s82, 0x80000
	v_lshl_add_u64 v[210:211], s[82:83], 0, v[168:169]
	s_addc_u32 s91, s83, 0
	s_add_i32 s67, s67, s24
	global_load_lds_dwordx4 v[210:211], off
	v_lshl_add_u64 v[212:213], s[90:91], 0, v[172:173]
	s_mov_b32 m0, s67
	v_lshl_add_u64 v[214:215], s[84:85], 0, v[170:171]
	global_load_lds_dwordx4 v[212:213], off
	v_lshl_add_u64 v[212:213], s[90:91], 0, v[168:169]
	s_add_i32 m0, s67, 0x2000
	s_nop 0
	global_load_lds_dwordx4 v[212:213], off
	v_lshl_add_u64 v[212:213], s[84:85], 0, v[174:175]
	s_mov_b32 m0, s29
	s_nop 0
	global_load_lds_dwordx4 v[212:213], off
	s_mov_b32 m0, s34
	s_nop 0
	global_load_lds_dwordx4 v[214:215], off
	s_waitcnt vmcnt(8)
	s_waitcnt lgkmcnt(0)
	s_barrier
	s_waitcnt lgkmcnt(0)
	v_mfma_f32_16x16x32_bf16 v[60:63], v[128:131], v[160:163], v[60:63]
	v_mfma_f32_16x16x32_bf16 v[60:63], v[132:135], v[164:167], v[60:63]
	v_mfma_f32_16x16x32_bf16 v[56:59], v[136:139], v[160:163], v[56:59]
	v_mfma_f32_16x16x32_bf16 v[56:59], v[140:143], v[164:167], v[56:59]
	v_mfma_f32_16x16x32_bf16 v[44:47], v[128:131], v[182:185], v[44:47]
	v_mfma_f32_16x16x32_bf16 v[44:47], v[132:135], v[188:191], v[44:47]
	v_mfma_f32_16x16x32_bf16 v[40:43], v[136:139], v[182:185], v[40:43]
	v_mfma_f32_16x16x32_bf16 v[40:43], v[140:143], v[188:191], v[40:43]
	v_mfma_f32_16x16x32_bf16 v[28:31], v[128:131], v[192:195], v[28:31]
	v_mfma_f32_16x16x32_bf16 v[28:31], v[132:135], v[196:199], v[28:31]
	v_mfma_f32_16x16x32_bf16 v[24:27], v[136:139], v[192:195], v[24:27]
	v_mfma_f32_16x16x32_bf16 v[24:27], v[140:143], v[196:199], v[24:27]
	v_mfma_f32_16x16x32_bf16 v[12:15], v[128:131], v[200:203], v[12:15]
	v_mfma_f32_16x16x32_bf16 v[12:15], v[132:135], v[204:207], v[12:15]
	v_mfma_f32_16x16x32_bf16 v[8:11], v[136:139], v[200:203], v[8:11]
	v_mfma_f32_16x16x32_bf16 v[8:11], v[140:143], v[204:207], v[8:11]
	v_mfma_f32_16x16x32_bf16 v[52:55], v[144:147], v[160:163], v[52:55]
	v_mfma_f32_16x16x32_bf16 v[52:55], v[148:151], v[164:167], v[52:55]
	v_mfma_f32_16x16x32_bf16 v[48:51], v[152:155], v[160:163], v[48:51]
	v_mfma_f32_16x16x32_bf16 v[48:51], v[156:159], v[164:167], v[48:51]
	v_mfma_f32_16x16x32_bf16 v[36:39], v[144:147], v[182:185], v[36:39]
	v_mfma_f32_16x16x32_bf16 v[36:39], v[148:151], v[188:191], v[36:39]
	v_mfma_f32_16x16x32_bf16 v[32:35], v[152:155], v[182:185], v[32:35]
	v_mfma_f32_16x16x32_bf16 v[32:35], v[156:159], v[188:191], v[32:35]
	v_mfma_f32_16x16x32_bf16 v[20:23], v[144:147], v[192:195], v[20:23]
	v_mfma_f32_16x16x32_bf16 v[20:23], v[148:151], v[196:199], v[20:23]
	v_mfma_f32_16x16x32_bf16 v[16:19], v[152:155], v[192:195], v[16:19]
	v_mfma_f32_16x16x32_bf16 v[16:19], v[156:159], v[196:199], v[16:19]
	v_mfma_f32_16x16x32_bf16 v[4:7], v[144:147], v[200:203], v[4:7]
	v_mfma_f32_16x16x32_bf16 v[4:7], v[148:151], v[204:207], v[4:7]
	v_mfma_f32_16x16x32_bf16 v[0:3], v[152:155], v[200:203], v[0:3]
	v_mfma_f32_16x16x32_bf16 v[0:3], v[156:159], v[204:207], v[0:3]
	s_barrier
	s_add_i32 s67, 0, 0x18000
	s_add_i32 s90, 0, 0x1c000
	v_add_u32_e32 v140, s67, v186
	v_add_u32_e32 v156, s90, v186
	ds_read_b128 v[128:131], v140
	ds_read_b128 v[132:135], v140 offset:1024
	ds_read_b128 v[136:139], v140 offset:2048
	ds_read_b128 v[140:143], v140 offset:3072
	ds_read_b128 v[144:147], v156
	ds_read_b128 v[148:151], v156 offset:1024
	ds_read_b128 v[152:155], v156 offset:2048
	ds_read_b128 v[156:159], v156 offset:3072
	s_add_u32 s84, s84, 0x80000
	s_addc_u32 s85, s85, 0
	s_mov_b32 m0, s35
	v_lshl_add_u64 v[218:219], s[84:85], 0, v[174:175]
	ds_read_b128 v[160:163], v187 offset:32768
	ds_read_b128 v[164:167], v187 offset:33792
	ds_read_b128 v[182:185], v187 offset:34816
	ds_read_b128 v[188:191], v187 offset:35840
	ds_read_b128 v[192:195], v187 offset:36864
	ds_read_b128 v[196:199], v187 offset:37888
	ds_read_b128 v[200:203], v187 offset:38912
	ds_read_b128 v[204:207], v187 offset:39936
	global_load_lds_dwordx4 v[218:219], off
	v_lshl_add_u64 v[218:219], s[84:85], 0, v[170:171]
	s_mov_b32 m0, s38
	s_nop 0
	global_load_lds_dwordx4 v[218:219], off
	s_waitcnt vmcnt(8)
	s_waitcnt lgkmcnt(0)
	s_barrier
	s_waitcnt lgkmcnt(0)
	v_mfma_f32_16x16x32_bf16 v[124:127], v[128:131], v[160:163], v[124:127]
	v_mfma_f32_16x16x32_bf16 v[124:127], v[132:135], v[164:167], v[124:127]
	v_mfma_f32_16x16x32_bf16 v[120:123], v[136:139], v[160:163], v[120:123]
	v_mfma_f32_16x16x32_bf16 v[120:123], v[140:143], v[164:167], v[120:123]
	v_mfma_f32_16x16x32_bf16 v[108:111], v[128:131], v[182:185], v[108:111]
	v_mfma_f32_16x16x32_bf16 v[108:111], v[132:135], v[188:191], v[108:111]
	v_mfma_f32_16x16x32_bf16 v[104:107], v[136:139], v[182:185], v[104:107]
	v_mfma_f32_16x16x32_bf16 v[104:107], v[140:143], v[188:191], v[104:107]
	v_mfma_f32_16x16x32_bf16 v[92:95], v[128:131], v[192:195], v[92:95]
	v_mfma_f32_16x16x32_bf16 v[92:95], v[132:135], v[196:199], v[92:95]
	v_mfma_f32_16x16x32_bf16 v[88:91], v[136:139], v[192:195], v[88:91]
	v_mfma_f32_16x16x32_bf16 v[88:91], v[140:143], v[196:199], v[88:91]
	v_mfma_f32_16x16x32_bf16 v[76:79], v[128:131], v[200:203], v[76:79]
	v_mfma_f32_16x16x32_bf16 v[76:79], v[132:135], v[204:207], v[76:79]
	v_mfma_f32_16x16x32_bf16 v[72:75], v[136:139], v[200:203], v[72:75]
	v_mfma_f32_16x16x32_bf16 v[72:75], v[140:143], v[204:207], v[72:75]
	v_mfma_f32_16x16x32_bf16 v[116:119], v[144:147], v[160:163], v[116:119]
	v_mfma_f32_16x16x32_bf16 v[116:119], v[148:151], v[164:167], v[116:119]
	v_mfma_f32_16x16x32_bf16 v[112:115], v[152:155], v[160:163], v[112:115]
	v_mfma_f32_16x16x32_bf16 v[112:115], v[156:159], v[164:167], v[112:115]
	v_mfma_f32_16x16x32_bf16 v[100:103], v[144:147], v[182:185], v[100:103]
	v_mfma_f32_16x16x32_bf16 v[100:103], v[148:151], v[188:191], v[100:103]
	v_mfma_f32_16x16x32_bf16 v[96:99], v[152:155], v[182:185], v[96:99]
	v_mfma_f32_16x16x32_bf16 v[96:99], v[156:159], v[188:191], v[96:99]
	v_mfma_f32_16x16x32_bf16 v[84:87], v[144:147], v[192:195], v[84:87]
	v_mfma_f32_16x16x32_bf16 v[84:87], v[148:151], v[196:199], v[84:87]
	v_mfma_f32_16x16x32_bf16 v[80:83], v[152:155], v[192:195], v[80:83]
	v_mfma_f32_16x16x32_bf16 v[80:83], v[156:159], v[196:199], v[80:83]
	v_mfma_f32_16x16x32_bf16 v[68:71], v[144:147], v[200:203], v[68:71]
	v_mfma_f32_16x16x32_bf16 v[68:71], v[148:151], v[204:207], v[68:71]
	v_mfma_f32_16x16x32_bf16 v[64:67], v[152:155], v[200:203], v[64:67]
	v_mfma_f32_16x16x32_bf16 v[64:67], v[156:159], v[204:207], v[64:67]
	s_barrier
	s_add_i32 s67, s67, s24
	v_lshl_add_u64 v[208:209], v[208:209], 0, s[30:31]
	s_mov_b32 m0, s67
	ds_read_b128 v[160:163], v187 offset:49152
	ds_read_b128 v[164:167], v187 offset:50176
	ds_read_b128 v[182:185], v187 offset:51200
	ds_read_b128 v[188:191], v187 offset:52224
	ds_read_b128 v[192:195], v187 offset:53248
	ds_read_b128 v[196:199], v187 offset:54272
	ds_read_b128 v[200:203], v187 offset:55296
	ds_read_b128 v[204:207], v187 offset:56320
	global_load_lds_dwordx4 v[208:209], off
	s_add_i32 m0, s67, 0x2000
	s_add_u32 s82, s82, 0x80080
	v_lshl_add_u64 v[208:209], v[210:211], 0, s[30:31]
	s_addc_u32 s83, s83, 0
	s_add_i32 s67, s90, s24
	global_load_lds_dwordx4 v[208:209], off
	v_lshl_add_u64 v[208:209], s[82:83], 0, v[172:173]
	s_mov_b32 m0, s67
	s_nop 0
	global_load_lds_dwordx4 v[208:209], off
	v_lshl_add_u64 v[208:209], s[82:83], 0, v[168:169]
	s_add_i32 m0, s67, 0x2000
	s_nop 0
	global_load_lds_dwordx4 v[208:209], off
	v_lshl_add_u64 v[208:209], v[212:213], 0, s[30:31]
	s_mov_b32 m0, s54
	s_nop 0
	global_load_lds_dwordx4 v[208:209], off
	v_lshl_add_u64 v[208:209], v[214:215], 0, s[30:31]
	s_mov_b32 m0, s55
	s_nop 0
	global_load_lds_dwordx4 v[208:209], off
	s_waitcnt vmcnt(8)
	s_waitcnt lgkmcnt(0)
	s_barrier
	s_waitcnt lgkmcnt(0)
	v_mfma_f32_16x16x32_bf16 v[60:63], v[128:131], v[160:163], v[60:63]
	v_mfma_f32_16x16x32_bf16 v[60:63], v[132:135], v[164:167], v[60:63]
	v_mfma_f32_16x16x32_bf16 v[56:59], v[136:139], v[160:163], v[56:59]
	v_mfma_f32_16x16x32_bf16 v[56:59], v[140:143], v[164:167], v[56:59]
	v_mfma_f32_16x16x32_bf16 v[44:47], v[128:131], v[182:185], v[44:47]
	v_mfma_f32_16x16x32_bf16 v[44:47], v[132:135], v[188:191], v[44:47]
	v_mfma_f32_16x16x32_bf16 v[40:43], v[136:139], v[182:185], v[40:43]
	v_mfma_f32_16x16x32_bf16 v[40:43], v[140:143], v[188:191], v[40:43]
	v_mfma_f32_16x16x32_bf16 v[28:31], v[128:131], v[192:195], v[28:31]
	v_mfma_f32_16x16x32_bf16 v[28:31], v[132:135], v[196:199], v[28:31]
	v_mfma_f32_16x16x32_bf16 v[24:27], v[136:139], v[192:195], v[24:27]
	v_mfma_f32_16x16x32_bf16 v[24:27], v[140:143], v[196:199], v[24:27]
	v_mfma_f32_16x16x32_bf16 v[12:15], v[128:131], v[200:203], v[12:15]
	v_mfma_f32_16x16x32_bf16 v[12:15], v[132:135], v[204:207], v[12:15]
	v_mfma_f32_16x16x32_bf16 v[8:11], v[136:139], v[200:203], v[8:11]
	v_mfma_f32_16x16x32_bf16 v[8:11], v[140:143], v[204:207], v[8:11]
	v_mfma_f32_16x16x32_bf16 v[52:55], v[144:147], v[160:163], v[52:55]
	v_mfma_f32_16x16x32_bf16 v[52:55], v[148:151], v[164:167], v[52:55]
	v_mfma_f32_16x16x32_bf16 v[48:51], v[152:155], v[160:163], v[48:51]
	v_mfma_f32_16x16x32_bf16 v[48:51], v[156:159], v[164:167], v[48:51]
	v_mfma_f32_16x16x32_bf16 v[36:39], v[144:147], v[182:185], v[36:39]
	v_mfma_f32_16x16x32_bf16 v[36:39], v[148:151], v[188:191], v[36:39]
	v_mfma_f32_16x16x32_bf16 v[32:35], v[152:155], v[182:185], v[32:35]
	v_mfma_f32_16x16x32_bf16 v[32:35], v[156:159], v[188:191], v[32:35]
	v_mfma_f32_16x16x32_bf16 v[20:23], v[144:147], v[192:195], v[20:23]
	v_mfma_f32_16x16x32_bf16 v[20:23], v[148:151], v[196:199], v[20:23]
	v_mfma_f32_16x16x32_bf16 v[16:19], v[152:155], v[192:195], v[16:19]
	v_mfma_f32_16x16x32_bf16 v[16:19], v[156:159], v[196:199], v[16:19]
	v_mfma_f32_16x16x32_bf16 v[4:7], v[144:147], v[200:203], v[4:7]
	v_mfma_f32_16x16x32_bf16 v[4:7], v[148:151], v[204:207], v[4:7]
	v_mfma_f32_16x16x32_bf16 v[0:3], v[152:155], v[200:203], v[0:3]
	v_mfma_f32_16x16x32_bf16 v[0:3], v[156:159], v[204:207], v[0:3]
	s_barrier
	s_add_i32 s89, s89, 2
	s_add_u32 s80, s80, 0x100
	s_addc_u32 s81, s81, 0
	s_add_u32 s87, s87, 0x100
	s_addc_u32 s88, s88, 0
	s_cmp_gt_u32 s89, 29
	s_cbranch_scc0 .LBB0_385
	s_and_b64 vcc, exec, s[18:19]
	s_cbranch_vccz .LBB0_388
	s_barrier

.LBB0_594:
	s_ashr_i32 s81, s80, 31
	s_lshl_b64 s[84:85], s[80:81], 20
	s_add_u32 s84, s29, s84
	s_addc_u32 s85, s34, s85
	s_and_b64 s[86:87], s[82:83], exec
	s_cselect_b32 s81, s85, s95
	s_cselect_b32 vcc_lo, s84, s94
	s_ashr_i32 s79, s78, 31
	s_lshl_b64 s[86:87], s[78:79], 20
	s_add_u32 s86, s35, s86
	s_addc_u32 s87, s38, s87
	s_and_b64 s[2:3], s[82:83], exec
	s_cselect_b32 s79, s87, s93
	s_cselect_b32 vcc_hi, s86, s92
	s_lshl_b32 s88, s88, 8
	s_ashr_i32 s89, s88, 31
	s_lshl_b64 s[2:3], s[88:89], 2
	s_add_u32 s2, s90, s2
	s_addc_u32 s3, s91, s3
	s_add_i32 m0, s14, s41
	s_add_u32 s90, s94, 0x80080
	global_load_lds_dwordx4 v239, s[2:3]
	s_addc_u32 s91, s95, 0
	s_add_u32 s89, s92, 0x100
	s_addc_u32 s14, s93, 0
	s_mov_b32 s20, -2
	s_waitcnt vmcnt(0)
	s_add_u32 s2, s90, 0xfff80080
	s_addc_u32 s3, s91, -1
	s_add_i32 s67, 0, 0x10000
	s_cmp_eq_u32 s20, 28
	s_cselect_b32 s95, s81, s3
	s_cselect_b32 s94, vcc_lo, s2
	s_cselect_b32 s93, s79, s14
	s_cselect_b32 s92, vcc_hi, s89
	s_add_i32 s76, 0, 0x14000
	v_add_u32_e32 v96, s67, v238
	v_add_u32_e32 v140, s76, v238
	ds_read_b128 v[64:67], v96
	ds_read_b128 v[72:75], v96 offset:1024
	ds_read_b128 v[88:91], v96 offset:2048
	ds_read_b128 v[96:99], v96 offset:3072
	ds_read_b128 v[108:111], v140
	ds_read_b128 v[116:119], v140 offset:1024
	ds_read_b128 v[128:131], v140 offset:2048
	ds_read_b128 v[140:143], v140 offset:3072
	v_lshl_add_u64 v[192:193], s[90:91], 0, v[230:231]
	s_add_i32 m0, s39, 0xc000
	ds_read_b128 v[152:155], v240
	ds_read_b128 v[156:159], v240 offset:1024
	ds_read_b128 v[160:163], v240 offset:2048
	ds_read_b128 v[164:167], v240 offset:3072
	ds_read_b128 v[168:171], v240 offset:4096
	ds_read_b128 v[180:183], v240 offset:5120
	ds_read_b128 v[184:187], v240 offset:6144
	ds_read_b128 v[188:191], v240 offset:7168
	global_load_lds_dwordx4 v[192:193], off
	v_lshl_add_u64 v[192:193], s[90:91], 0, v[232:233]
	s_add_i32 m0, s39, 0xe000
	s_nop 0
	global_load_lds_dwordx4 v[192:193], off
	s_waitcnt vmcnt(8)
	s_waitcnt lgkmcnt(0)
	s_barrier
	s_waitcnt lgkmcnt(0)
	v_mfma_f32_16x16x32_bf16 v[176:179], v[64:67], v[152:155], 0
	v_mfma_f32_16x16x32_bf16 v[176:179], v[72:75], v[156:159], v[176:179]
	v_mfma_f32_16x16x32_bf16 v[172:175], v[88:91], v[152:155], 0
	v_mfma_f32_16x16x32_bf16 v[172:175], v[96:99], v[156:159], v[172:175]
	v_mfma_f32_16x16x32_bf16 v[136:139], v[64:67], v[160:163], 0
	v_mfma_f32_16x16x32_bf16 v[136:139], v[72:75], v[164:167], v[136:139]
	v_mfma_f32_16x16x32_bf16 v[132:135], v[88:91], v[160:163], 0
	v_mfma_f32_16x16x32_bf16 v[132:135], v[96:99], v[164:167], v[132:135]
	v_mfma_f32_16x16x32_bf16 v[112:115], v[64:67], v[168:171], 0
	v_mfma_f32_16x16x32_bf16 v[112:115], v[72:75], v[180:183], v[112:115]
	v_mfma_f32_16x16x32_bf16 v[104:107], v[88:91], v[168:171], 0
	v_mfma_f32_16x16x32_bf16 v[104:107], v[96:99], v[180:183], v[104:107]
	v_mfma_f32_16x16x32_bf16 v[84:87], v[64:67], v[184:187], 0
	v_mfma_f32_16x16x32_bf16 v[84:87], v[72:75], v[188:191], v[84:87]
	v_mfma_f32_16x16x32_bf16 v[80:83], v[88:91], v[184:187], 0
	v_mfma_f32_16x16x32_bf16 v[80:83], v[96:99], v[188:191], v[80:83]
	v_mfma_f32_16x16x32_bf16 v[148:151], v[108:111], v[152:155], 0
	v_mfma_f32_16x16x32_bf16 v[148:151], v[116:119], v[156:159], v[148:151]
	v_mfma_f32_16x16x32_bf16 v[144:147], v[128:131], v[152:155], 0
	v_mfma_f32_16x16x32_bf16 v[144:147], v[140:143], v[156:159], v[144:147]
	v_mfma_f32_16x16x32_bf16 v[124:127], v[108:111], v[160:163], 0
	v_mfma_f32_16x16x32_bf16 v[124:127], v[116:119], v[164:167], v[124:127]
	v_mfma_f32_16x16x32_bf16 v[120:123], v[128:131], v[160:163], 0
	v_mfma_f32_16x16x32_bf16 v[120:123], v[140:143], v[164:167], v[120:123]
	v_mfma_f32_16x16x32_bf16 v[100:103], v[108:111], v[168:171], 0
	v_mfma_f32_16x16x32_bf16 v[100:103], v[116:119], v[180:183], v[100:103]
	v_mfma_f32_16x16x32_bf16 v[92:95], v[128:131], v[168:171], 0
	v_mfma_f32_16x16x32_bf16 v[92:95], v[140:143], v[180:183], v[92:95]
	v_mfma_f32_16x16x32_bf16 v[76:79], v[108:111], v[184:187], 0
	v_mfma_f32_16x16x32_bf16 v[76:79], v[116:119], v[188:191], v[76:79]
	v_mfma_f32_16x16x32_bf16 v[68:71], v[128:131], v[184:187], 0
	v_mfma_f32_16x16x32_bf16 v[68:71], v[140:143], v[188:191], v[68:71]
	s_barrier
	s_add_i32 s2, s67, s28
	v_lshl_add_u64 v[192:193], s[92:93], 0, v[216:217]
	s_mov_b32 m0, s2
	ds_read_b128 v[152:155], v240 offset:16384
	ds_read_b128 v[156:159], v240 offset:17408
	ds_read_b128 v[160:163], v240 offset:18432
	ds_read_b128 v[164:167], v240 offset:19456
	ds_read_b128 v[168:171], v240 offset:20480
	ds_read_b128 v[180:183], v240 offset:21504
	ds_read_b128 v[184:187], v240 offset:22528
	ds_read_b128 v[188:191], v240 offset:23552
	global_load_lds_dwordx4 v[192:193], off
	s_add_i32 m0, s2, 0x2000
	s_add_u32 s2, s92, 0x80000
	v_lshl_add_u64 v[194:195], s[92:93], 0, v[228:229]
	s_addc_u32 s3, s93, 0
	s_add_i32 s67, s76, s28
	global_load_lds_dwordx4 v[194:195], off
	v_lshl_add_u64 v[196:197], s[2:3], 0, v[216:217]
	s_mov_b32 m0, s67
	v_lshl_add_u64 v[198:199], s[94:95], 0, v[226:227]
	global_load_lds_dwordx4 v[196:197], off
	v_lshl_add_u64 v[196:197], s[2:3], 0, v[228:229]
	s_add_i32 m0, s67, 0x2000
	s_nop 0
	global_load_lds_dwordx4 v[196:197], off
	v_lshl_add_u64 v[196:197], s[94:95], 0, v[224:225]
	s_mov_b32 m0, s39
	s_nop 0
	global_load_lds_dwordx4 v[196:197], off
	s_mov_b32 m0, s53
	s_nop 0
	global_load_lds_dwordx4 v[198:199], off
	s_waitcnt vmcnt(8)
	s_waitcnt lgkmcnt(0)
	s_barrier
	s_waitcnt lgkmcnt(0)
	v_mfma_f32_16x16x32_bf16 v[60:63], v[64:67], v[152:155], 0
	v_mfma_f32_16x16x32_bf16 v[60:63], v[72:75], v[156:159], v[60:63]
	v_mfma_f32_16x16x32_bf16 v[56:59], v[88:91], v[152:155], 0
	v_mfma_f32_16x16x32_bf16 v[56:59], v[96:99], v[156:159], v[56:59]
	v_mfma_f32_16x16x32_bf16 v[44:47], v[64:67], v[160:163], 0
	v_mfma_f32_16x16x32_bf16 v[44:47], v[72:75], v[164:167], v[44:47]
	v_mfma_f32_16x16x32_bf16 v[40:43], v[88:91], v[160:163], 0
	v_mfma_f32_16x16x32_bf16 v[40:43], v[96:99], v[164:167], v[40:43]
	v_mfma_f32_16x16x32_bf16 v[28:31], v[64:67], v[168:171], 0
	v_mfma_f32_16x16x32_bf16 v[28:31], v[72:75], v[180:183], v[28:31]
	v_mfma_f32_16x16x32_bf16 v[24:27], v[88:91], v[168:171], 0
	v_mfma_f32_16x16x32_bf16 v[24:27], v[96:99], v[180:183], v[24:27]
	v_mfma_f32_16x16x32_bf16 v[12:15], v[64:67], v[184:187], 0
	v_mfma_f32_16x16x32_bf16 v[12:15], v[72:75], v[188:191], v[12:15]
	v_mfma_f32_16x16x32_bf16 v[8:11], v[88:91], v[184:187], 0
	v_mfma_f32_16x16x32_bf16 v[8:11], v[96:99], v[188:191], v[8:11]
	v_mfma_f32_16x16x32_bf16 v[52:55], v[108:111], v[152:155], 0
	v_mfma_f32_16x16x32_bf16 v[52:55], v[116:119], v[156:159], v[52:55]
	v_mfma_f32_16x16x32_bf16 v[48:51], v[128:131], v[152:155], 0
	v_mfma_f32_16x16x32_bf16 v[48:51], v[140:143], v[156:159], v[48:51]
	v_mfma_f32_16x16x32_bf16 v[36:39], v[108:111], v[160:163], 0
	v_mfma_f32_16x16x32_bf16 v[36:39], v[116:119], v[164:167], v[36:39]
	v_mfma_f32_16x16x32_bf16 v[32:35], v[128:131], v[160:163], 0
	v_mfma_f32_16x16x32_bf16 v[32:35], v[140:143], v[164:167], v[32:35]
	v_mfma_f32_16x16x32_bf16 v[20:23], v[108:111], v[168:171], 0
	v_mfma_f32_16x16x32_bf16 v[20:23], v[116:119], v[180:183], v[20:23]
	v_mfma_f32_16x16x32_bf16 v[16:19], v[128:131], v[168:171], 0
	v_mfma_f32_16x16x32_bf16 v[16:19], v[140:143], v[180:183], v[16:19]
	v_mfma_f32_16x16x32_bf16 v[4:7], v[108:111], v[184:187], 0
	v_mfma_f32_16x16x32_bf16 v[4:7], v[116:119], v[188:191], v[4:7]
	v_mfma_f32_16x16x32_bf16 v[0:3], v[128:131], v[184:187], 0
	v_mfma_f32_16x16x32_bf16 v[0:3], v[140:143], v[188:191], v[0:3]
	s_barrier
	s_add_i32 s67, 0, 0x18000
	s_add_i32 s76, 0, 0x1c000
	v_add_u32_e32 v96, s67, v238
	v_add_u32_e32 v140, s76, v238
	ds_read_b128 v[64:67], v96
	ds_read_b128 v[72:75], v96 offset:1024
	ds_read_b128 v[88:91], v96 offset:2048
	ds_read_b128 v[96:99], v96 offset:3072
	ds_read_b128 v[108:111], v140
	ds_read_b128 v[116:119], v140 offset:1024
	ds_read_b128 v[128:131], v140 offset:2048
	ds_read_b128 v[140:143], v140 offset:3072
	s_add_u32 s2, s94, 0x80000
	s_addc_u32 s3, s95, 0
	s_mov_b32 m0, s55
	v_lshl_add_u64 v[200:201], s[2:3], 0, v[224:225]
	ds_read_b128 v[152:155], v240 offset:32768
	ds_read_b128 v[156:159], v240 offset:33792
	ds_read_b128 v[160:163], v240 offset:34816
	ds_read_b128 v[164:167], v240 offset:35840
	ds_read_b128 v[168:171], v240 offset:36864
	ds_read_b128 v[180:183], v240 offset:37888
	ds_read_b128 v[184:187], v240 offset:38912
	ds_read_b128 v[188:191], v240 offset:39936
	global_load_lds_dwordx4 v[200:201], off
	v_lshl_add_u64 v[200:201], s[2:3], 0, v[226:227]
	s_mov_b32 m0, s56
	s_nop 0
	global_load_lds_dwordx4 v[200:201], off
	s_waitcnt vmcnt(8)
	s_waitcnt lgkmcnt(0)
	s_barrier
	s_waitcnt lgkmcnt(0)
	v_mfma_f32_16x16x32_bf16 v[176:179], v[64:67], v[152:155], v[176:179]
	v_mfma_f32_16x16x32_bf16 v[176:179], v[72:75], v[156:159], v[176:179]
	v_mfma_f32_16x16x32_bf16 v[172:175], v[88:91], v[152:155], v[172:175]
	v_mfma_f32_16x16x32_bf16 v[172:175], v[96:99], v[156:159], v[172:175]
	v_mfma_f32_16x16x32_bf16 v[136:139], v[64:67], v[160:163], v[136:139]
	v_mfma_f32_16x16x32_bf16 v[136:139], v[72:75], v[164:167], v[136:139]
	v_mfma_f32_16x16x32_bf16 v[132:135], v[88:91], v[160:163], v[132:135]
	v_mfma_f32_16x16x32_bf16 v[132:135], v[96:99], v[164:167], v[132:135]
	v_mfma_f32_16x16x32_bf16 v[112:115], v[64:67], v[168:171], v[112:115]
	v_mfma_f32_16x16x32_bf16 v[112:115], v[72:75], v[180:183], v[112:115]
	v_mfma_f32_16x16x32_bf16 v[104:107], v[88:91], v[168:171], v[104:107]
	v_mfma_f32_16x16x32_bf16 v[104:107], v[96:99], v[180:183], v[104:107]
	v_mfma_f32_16x16x32_bf16 v[84:87], v[64:67], v[184:187], v[84:87]
	v_mfma_f32_16x16x32_bf16 v[84:87], v[72:75], v[188:191], v[84:87]
	v_mfma_f32_16x16x32_bf16 v[80:83], v[88:91], v[184:187], v[80:83]
	v_mfma_f32_16x16x32_bf16 v[80:83], v[96:99], v[188:191], v[80:83]
	v_mfma_f32_16x16x32_bf16 v[148:151], v[108:111], v[152:155], v[148:151]
	v_mfma_f32_16x16x32_bf16 v[148:151], v[116:119], v[156:159], v[148:151]
	v_mfma_f32_16x16x32_bf16 v[144:147], v[128:131], v[152:155], v[144:147]
	v_mfma_f32_16x16x32_bf16 v[144:147], v[140:143], v[156:159], v[144:147]
	v_mfma_f32_16x16x32_bf16 v[124:127], v[108:111], v[160:163], v[124:127]
	v_mfma_f32_16x16x32_bf16 v[124:127], v[116:119], v[164:167], v[124:127]
	v_mfma_f32_16x16x32_bf16 v[120:123], v[128:131], v[160:163], v[120:123]
	v_mfma_f32_16x16x32_bf16 v[120:123], v[140:143], v[164:167], v[120:123]
	v_mfma_f32_16x16x32_bf16 v[100:103], v[108:111], v[168:171], v[100:103]
	v_mfma_f32_16x16x32_bf16 v[100:103], v[116:119], v[180:183], v[100:103]
	v_mfma_f32_16x16x32_bf16 v[92:95], v[128:131], v[168:171], v[92:95]
	v_mfma_f32_16x16x32_bf16 v[92:95], v[140:143], v[180:183], v[92:95]
	v_mfma_f32_16x16x32_bf16 v[76:79], v[108:111], v[184:187], v[76:79]
	v_mfma_f32_16x16x32_bf16 v[76:79], v[116:119], v[188:191], v[76:79]
	v_mfma_f32_16x16x32_bf16 v[68:71], v[128:131], v[184:187], v[68:71]
	v_mfma_f32_16x16x32_bf16 v[68:71], v[140:143], v[188:191], v[68:71]
	s_barrier
	s_add_i32 s2, s67, s28
	v_lshl_add_u64 v[192:193], v[192:193], 0, s[30:31]
	s_mov_b32 m0, s2
	ds_read_b128 v[152:155], v240 offset:49152
	ds_read_b128 v[156:159], v240 offset:50176
	ds_read_b128 v[160:163], v240 offset:51200
	ds_read_b128 v[164:167], v240 offset:52224
	ds_read_b128 v[168:171], v240 offset:53248
	ds_read_b128 v[180:183], v240 offset:54272
	ds_read_b128 v[184:187], v240 offset:55296
	ds_read_b128 v[188:191], v240 offset:56320
	global_load_lds_dwordx4 v[192:193], off
	s_add_i32 m0, s2, 0x2000
	s_add_u32 s2, s92, 0x80080
	v_lshl_add_u64 v[192:193], v[194:195], 0, s[30:31]
	s_addc_u32 s3, s93, 0
	s_add_i32 s67, s76, s28
	global_load_lds_dwordx4 v[192:193], off
	v_lshl_add_u64 v[192:193], s[2:3], 0, v[216:217]
	s_mov_b32 m0, s67
	s_nop 0
	global_load_lds_dwordx4 v[192:193], off
	v_lshl_add_u64 v[192:193], s[2:3], 0, v[228:229]
	s_add_i32 m0, s67, 0x2000
	s_nop 0
	global_load_lds_dwordx4 v[192:193], off
	v_lshl_add_u64 v[192:193], v[196:197], 0, s[30:31]
	s_mov_b32 m0, s70
	s_nop 0
	global_load_lds_dwordx4 v[192:193], off
	v_lshl_add_u64 v[192:193], v[198:199], 0, s[30:31]
	s_mov_b32 m0, s71
	s_nop 0
	global_load_lds_dwordx4 v[192:193], off
	s_waitcnt vmcnt(8)
	s_waitcnt lgkmcnt(0)
	s_barrier
	s_waitcnt lgkmcnt(0)
	v_mfma_f32_16x16x32_bf16 v[60:63], v[64:67], v[152:155], v[60:63]
	v_mfma_f32_16x16x32_bf16 v[60:63], v[72:75], v[156:159], v[60:63]
	v_mfma_f32_16x16x32_bf16 v[56:59], v[88:91], v[152:155], v[56:59]
	v_mfma_f32_16x16x32_bf16 v[56:59], v[96:99], v[156:159], v[56:59]
	v_mfma_f32_16x16x32_bf16 v[44:47], v[64:67], v[160:163], v[44:47]
	v_mfma_f32_16x16x32_bf16 v[44:47], v[72:75], v[164:167], v[44:47]
	v_mfma_f32_16x16x32_bf16 v[40:43], v[88:91], v[160:163], v[40:43]
	v_mfma_f32_16x16x32_bf16 v[40:43], v[96:99], v[164:167], v[40:43]
	v_mfma_f32_16x16x32_bf16 v[28:31], v[64:67], v[168:171], v[28:31]
	v_mfma_f32_16x16x32_bf16 v[28:31], v[72:75], v[180:183], v[28:31]
	v_mfma_f32_16x16x32_bf16 v[24:27], v[88:91], v[168:171], v[24:27]
	v_mfma_f32_16x16x32_bf16 v[24:27], v[96:99], v[180:183], v[24:27]
	v_mfma_f32_16x16x32_bf16 v[12:15], v[64:67], v[184:187], v[12:15]
	v_mfma_f32_16x16x32_bf16 v[12:15], v[72:75], v[188:191], v[12:15]
	v_mfma_f32_16x16x32_bf16 v[8:11], v[88:91], v[184:187], v[8:11]
	v_mfma_f32_16x16x32_bf16 v[8:11], v[96:99], v[188:191], v[8:11]
	v_mfma_f32_16x16x32_bf16 v[52:55], v[108:111], v[152:155], v[52:55]
	v_mfma_f32_16x16x32_bf16 v[52:55], v[116:119], v[156:159], v[52:55]
	v_mfma_f32_16x16x32_bf16 v[48:51], v[128:131], v[152:155], v[48:51]
	v_mfma_f32_16x16x32_bf16 v[48:51], v[140:143], v[156:159], v[48:51]
	v_mfma_f32_16x16x32_bf16 v[36:39], v[108:111], v[160:163], v[36:39]
	v_mfma_f32_16x16x32_bf16 v[36:39], v[116:119], v[164:167], v[36:39]
	v_mfma_f32_16x16x32_bf16 v[32:35], v[128:131], v[160:163], v[32:35]
	v_mfma_f32_16x16x32_bf16 v[32:35], v[140:143], v[164:167], v[32:35]
	v_mfma_f32_16x16x32_bf16 v[20:23], v[108:111], v[168:171], v[20:23]
	v_mfma_f32_16x16x32_bf16 v[20:23], v[116:119], v[180:183], v[20:23]
	v_mfma_f32_16x16x32_bf16 v[16:19], v[128:131], v[168:171], v[16:19]
	v_mfma_f32_16x16x32_bf16 v[16:19], v[140:143], v[180:183], v[16:19]
	v_mfma_f32_16x16x32_bf16 v[4:7], v[108:111], v[184:187], v[4:7]
	v_mfma_f32_16x16x32_bf16 v[4:7], v[116:119], v[188:191], v[4:7]
	v_mfma_f32_16x16x32_bf16 v[0:3], v[128:131], v[184:187], v[0:3]
	v_mfma_f32_16x16x32_bf16 v[0:3], v[140:143], v[188:191], v[0:3]
	s_barrier
	s_add_i32 s20, s20, 2
	s_add_u32 s90, s90, 0x100
	s_addc_u32 s91, s91, 0
	s_add_u32 s89, s89, 0x100
	s_addc_u32 s14, s14, 0
.LBB0_595:
	s_add_u32 s2, s90, 0xfff80080
	s_addc_u32 s3, s91, -1
	s_add_i32 s67, 0, 0x10000
	s_cmp_eq_u32 s20, 28
	s_cselect_b32 s95, s81, s3
	s_cselect_b32 s94, vcc_lo, s2
	s_cselect_b32 s93, s79, s14
	s_cselect_b32 s92, vcc_hi, s89
	s_add_i32 s76, 0, 0x14000
	v_add_u32_e32 v96, s67, v238
	v_add_u32_e32 v140, s76, v238
	ds_read_b128 v[64:67], v96
	ds_read_b128 v[72:75], v96 offset:1024
	ds_read_b128 v[88:91], v96 offset:2048
	ds_read_b128 v[96:99], v96 offset:3072
	ds_read_b128 v[108:111], v140
	ds_read_b128 v[116:119], v140 offset:1024
	ds_read_b128 v[128:131], v140 offset:2048
	ds_read_b128 v[140:143], v140 offset:3072
	v_lshl_add_u64 v[192:193], s[90:91], 0, v[230:231]
	s_add_i32 m0, s39, 0xc000
	ds_read_b128 v[152:155], v240
	ds_read_b128 v[156:159], v240 offset:1024
	ds_read_b128 v[160:163], v240 offset:2048
	ds_read_b128 v[164:167], v240 offset:3072
	ds_read_b128 v[168:171], v240 offset:4096
	ds_read_b128 v[180:183], v240 offset:5120
	ds_read_b128 v[184:187], v240 offset:6144
	ds_read_b128 v[188:191], v240 offset:7168
	global_load_lds_dwordx4 v[192:193], off
	v_lshl_add_u64 v[192:193], s[90:91], 0, v[232:233]
	s_add_i32 m0, s39, 0xe000
	s_nop 0
	global_load_lds_dwordx4 v[192:193], off
	s_waitcnt vmcnt(8)
	s_waitcnt lgkmcnt(0)
	s_barrier
	s_waitcnt lgkmcnt(0)
	v_mfma_f32_16x16x32_bf16 v[176:179], v[64:67], v[152:155], v[176:179]
	v_mfma_f32_16x16x32_bf16 v[176:179], v[72:75], v[156:159], v[176:179]
	v_mfma_f32_16x16x32_bf16 v[172:175], v[88:91], v[152:155], v[172:175]
	v_mfma_f32_16x16x32_bf16 v[172:175], v[96:99], v[156:159], v[172:175]
	v_mfma_f32_16x16x32_bf16 v[136:139], v[64:67], v[160:163], v[136:139]
	v_mfma_f32_16x16x32_bf16 v[136:139], v[72:75], v[164:167], v[136:139]
	v_mfma_f32_16x16x32_bf16 v[132:135], v[88:91], v[160:163], v[132:135]
	v_mfma_f32_16x16x32_bf16 v[132:135], v[96:99], v[164:167], v[132:135]
	v_mfma_f32_16x16x32_bf16 v[112:115], v[64:67], v[168:171], v[112:115]
	v_mfma_f32_16x16x32_bf16 v[112:115], v[72:75], v[180:183], v[112:115]
	v_mfma_f32_16x16x32_bf16 v[104:107], v[88:91], v[168:171], v[104:107]
	v_mfma_f32_16x16x32_bf16 v[104:107], v[96:99], v[180:183], v[104:107]
	v_mfma_f32_16x16x32_bf16 v[84:87], v[64:67], v[184:187], v[84:87]
	v_mfma_f32_16x16x32_bf16 v[84:87], v[72:75], v[188:191], v[84:87]
	v_mfma_f32_16x16x32_bf16 v[80:83], v[88:91], v[184:187], v[80:83]
	v_mfma_f32_16x16x32_bf16 v[80:83], v[96:99], v[188:191], v[80:83]
	v_mfma_f32_16x16x32_bf16 v[148:151], v[108:111], v[152:155], v[148:151]
	v_mfma_f32_16x16x32_bf16 v[148:151], v[116:119], v[156:159], v[148:151]
	v_mfma_f32_16x16x32_bf16 v[144:147], v[128:131], v[152:155], v[144:147]
	v_mfma_f32_16x16x32_bf16 v[144:147], v[140:143], v[156:159], v[144:147]
	v_mfma_f32_16x16x32_bf16 v[124:127], v[108:111], v[160:163], v[124:127]
	v_mfma_f32_16x16x32_bf16 v[124:127], v[116:119], v[164:167], v[124:127]
	v_mfma_f32_16x16x32_bf16 v[120:123], v[128:131], v[160:163], v[120:123]
	v_mfma_f32_16x16x32_bf16 v[120:123], v[140:143], v[164:167], v[120:123]
	v_mfma_f32_16x16x32_bf16 v[100:103], v[108:111], v[168:171], v[100:103]
	v_mfma_f32_16x16x32_bf16 v[100:103], v[116:119], v[180:183], v[100:103]
	v_mfma_f32_16x16x32_bf16 v[92:95], v[128:131], v[168:171], v[92:95]
	v_mfma_f32_16x16x32_bf16 v[92:95], v[140:143], v[180:183], v[92:95]
	v_mfma_f32_16x16x32_bf16 v[76:79], v[108:111], v[184:187], v[76:79]
	v_mfma_f32_16x16x32_bf16 v[76:79], v[116:119], v[188:191], v[76:79]
	v_mfma_f32_16x16x32_bf16 v[68:71], v[128:131], v[184:187], v[68:71]
	v_mfma_f32_16x16x32_bf16 v[68:71], v[140:143], v[188:191], v[68:71]
	s_barrier
	s_add_i32 s2, s67, s28
	v_lshl_add_u64 v[192:193], s[92:93], 0, v[216:217]
	s_mov_b32 m0, s2
	ds_read_b128 v[152:155], v240 offset:16384
	ds_read_b128 v[156:159], v240 offset:17408
	ds_read_b128 v[160:163], v240 offset:18432
	ds_read_b128 v[164:167], v240 offset:19456
	ds_read_b128 v[168:171], v240 offset:20480
	ds_read_b128 v[180:183], v240 offset:21504
	ds_read_b128 v[184:187], v240 offset:22528
	ds_read_b128 v[188:191], v240 offset:23552
	global_load_lds_dwordx4 v[192:193], off
	s_add_i32 m0, s2, 0x2000
	s_add_u32 s2, s92, 0x80000
	v_lshl_add_u64 v[194:195], s[92:93], 0, v[228:229]
	s_addc_u32 s3, s93, 0
	s_add_i32 s67, s76, s28
	global_load_lds_dwordx4 v[194:195], off
	v_lshl_add_u64 v[196:197], s[2:3], 0, v[216:217]
	s_mov_b32 m0, s67
	v_lshl_add_u64 v[198:199], s[94:95], 0, v[226:227]
	global_load_lds_dwordx4 v[196:197], off
	v_lshl_add_u64 v[196:197], s[2:3], 0, v[228:229]
	s_add_i32 m0, s67, 0x2000
	s_nop 0
	global_load_lds_dwordx4 v[196:197], off
	v_lshl_add_u64 v[196:197], s[94:95], 0, v[224:225]
	s_mov_b32 m0, s39
	s_nop 0
	global_load_lds_dwordx4 v[196:197], off
	s_mov_b32 m0, s53
	s_nop 0
	global_load_lds_dwordx4 v[198:199], off
	s_waitcnt vmcnt(8)
	s_waitcnt lgkmcnt(0)
	s_barrier
	s_waitcnt lgkmcnt(0)
	v_mfma_f32_16x16x32_bf16 v[60:63], v[64:67], v[152:155], v[60:63]
	v_mfma_f32_16x16x32_bf16 v[60:63], v[72:75], v[156:159], v[60:63]
	v_mfma_f32_16x16x32_bf16 v[56:59], v[88:91], v[152:155], v[56:59]
	v_mfma_f32_16x16x32_bf16 v[56:59], v[96:99], v[156:159], v[56:59]
	v_mfma_f32_16x16x32_bf16 v[44:47], v[64:67], v[160:163], v[44:47]
	v_mfma_f32_16x16x32_bf16 v[44:47], v[72:75], v[164:167], v[44:47]
	v_mfma_f32_16x16x32_bf16 v[40:43], v[88:91], v[160:163], v[40:43]
	v_mfma_f32_16x16x32_bf16 v[40:43], v[96:99], v[164:167], v[40:43]
	v_mfma_f32_16x16x32_bf16 v[28:31], v[64:67], v[168:171], v[28:31]
	v_mfma_f32_16x16x32_bf16 v[28:31], v[72:75], v[180:183], v[28:31]
	v_mfma_f32_16x16x32_bf16 v[24:27], v[88:91], v[168:171], v[24:27]
	v_mfma_f32_16x16x32_bf16 v[24:27], v[96:99], v[180:183], v[24:27]
	v_mfma_f32_16x16x32_bf16 v[12:15], v[64:67], v[184:187], v[12:15]
	v_mfma_f32_16x16x32_bf16 v[12:15], v[72:75], v[188:191], v[12:15]
	v_mfma_f32_16x16x32_bf16 v[8:11], v[88:91], v[184:187], v[8:11]
	v_mfma_f32_16x16x32_bf16 v[8:11], v[96:99], v[188:191], v[8:11]
	v_mfma_f32_16x16x32_bf16 v[52:55], v[108:111], v[152:155], v[52:55]
	v_mfma_f32_16x16x32_bf16 v[52:55], v[116:119], v[156:159], v[52:55]
	v_mfma_f32_16x16x32_bf16 v[48:51], v[128:131], v[152:155], v[48:51]
	v_mfma_f32_16x16x32_bf16 v[48:51], v[140:143], v[156:159], v[48:51]
	v_mfma_f32_16x16x32_bf16 v[36:39], v[108:111], v[160:163], v[36:39]
	v_mfma_f32_16x16x32_bf16 v[36:39], v[116:119], v[164:167], v[36:39]
	v_mfma_f32_16x16x32_bf16 v[32:35], v[128:131], v[160:163], v[32:35]
	v_mfma_f32_16x16x32_bf16 v[32:35], v[140:143], v[164:167], v[32:35]
	v_mfma_f32_16x16x32_bf16 v[20:23], v[108:111], v[168:171], v[20:23]
	v_mfma_f32_16x16x32_bf16 v[20:23], v[116:119], v[180:183], v[20:23]
	v_mfma_f32_16x16x32_bf16 v[16:19], v[128:131], v[168:171], v[16:19]
	v_mfma_f32_16x16x32_bf16 v[16:19], v[140:143], v[180:183], v[16:19]
	v_mfma_f32_16x16x32_bf16 v[4:7], v[108:111], v[184:187], v[4:7]
	v_mfma_f32_16x16x32_bf16 v[4:7], v[116:119], v[188:191], v[4:7]
	v_mfma_f32_16x16x32_bf16 v[0:3], v[128:131], v[184:187], v[0:3]
	v_mfma_f32_16x16x32_bf16 v[0:3], v[140:143], v[188:191], v[0:3]
	s_barrier
	s_add_i32 s67, 0, 0x18000
	s_add_i32 s76, 0, 0x1c000
	v_add_u32_e32 v96, s67, v238
	v_add_u32_e32 v140, s76, v238
	ds_read_b128 v[64:67], v96
	ds_read_b128 v[72:75], v96 offset:1024
	ds_read_b128 v[88:91], v96 offset:2048
	ds_read_b128 v[96:99], v96 offset:3072
	ds_read_b128 v[108:111], v140
	ds_read_b128 v[116:119], v140 offset:1024
	ds_read_b128 v[128:131], v140 offset:2048
	ds_read_b128 v[140:143], v140 offset:3072
	s_add_u32 s2, s94, 0x80000
	s_addc_u32 s3, s95, 0
	s_mov_b32 m0, s55
	v_lshl_add_u64 v[200:201], s[2:3], 0, v[224:225]
	ds_read_b128 v[152:155], v240 offset:32768
	ds_read_b128 v[156:159], v240 offset:33792
	ds_read_b128 v[160:163], v240 offset:34816
	ds_read_b128 v[164:167], v240 offset:35840
	ds_read_b128 v[168:171], v240 offset:36864
	ds_read_b128 v[180:183], v240 offset:37888
	ds_read_b128 v[184:187], v240 offset:38912
	ds_read_b128 v[188:191], v240 offset:39936
	global_load_lds_dwordx4 v[200:201], off
	v_lshl_add_u64 v[200:201], s[2:3], 0, v[226:227]
	s_mov_b32 m0, s56
	s_nop 0
	global_load_lds_dwordx4 v[200:201], off
	s_waitcnt vmcnt(8)
	s_waitcnt lgkmcnt(0)
	s_barrier
	s_waitcnt lgkmcnt(0)
	v_mfma_f32_16x16x32_bf16 v[176:179], v[64:67], v[152:155], v[176:179]
	v_mfma_f32_16x16x32_bf16 v[176:179], v[72:75], v[156:159], v[176:179]
	v_mfma_f32_16x16x32_bf16 v[172:175], v[88:91], v[152:155], v[172:175]
	v_mfma_f32_16x16x32_bf16 v[172:175], v[96:99], v[156:159], v[172:175]
	v_mfma_f32_16x16x32_bf16 v[136:139], v[64:67], v[160:163], v[136:139]
	v_mfma_f32_16x16x32_bf16 v[136:139], v[72:75], v[164:167], v[136:139]
	v_mfma_f32_16x16x32_bf16 v[132:135], v[88:91], v[160:163], v[132:135]
	v_mfma_f32_16x16x32_bf16 v[132:135], v[96:99], v[164:167], v[132:135]
	v_mfma_f32_16x16x32_bf16 v[112:115], v[64:67], v[168:171], v[112:115]
	v_mfma_f32_16x16x32_bf16 v[112:115], v[72:75], v[180:183], v[112:115]
	v_mfma_f32_16x16x32_bf16 v[104:107], v[88:91], v[168:171], v[104:107]
	v_mfma_f32_16x16x32_bf16 v[104:107], v[96:99], v[180:183], v[104:107]
	v_mfma_f32_16x16x32_bf16 v[84:87], v[64:67], v[184:187], v[84:87]
	v_mfma_f32_16x16x32_bf16 v[84:87], v[72:75], v[188:191], v[84:87]
	v_mfma_f32_16x16x32_bf16 v[80:83], v[88:91], v[184:187], v[80:83]
	v_mfma_f32_16x16x32_bf16 v[80:83], v[96:99], v[188:191], v[80:83]
	v_mfma_f32_16x16x32_bf16 v[148:151], v[108:111], v[152:155], v[148:151]
	v_mfma_f32_16x16x32_bf16 v[148:151], v[116:119], v[156:159], v[148:151]
	v_mfma_f32_16x16x32_bf16 v[144:147], v[128:131], v[152:155], v[144:147]
	v_mfma_f32_16x16x32_bf16 v[144:147], v[140:143], v[156:159], v[144:147]
	v_mfma_f32_16x16x32_bf16 v[124:127], v[108:111], v[160:163], v[124:127]
	v_mfma_f32_16x16x32_bf16 v[124:127], v[116:119], v[164:167], v[124:127]
	v_mfma_f32_16x16x32_bf16 v[120:123], v[128:131], v[160:163], v[120:123]
	v_mfma_f32_16x16x32_bf16 v[120:123], v[140:143], v[164:167], v[120:123]
	v_mfma_f32_16x16x32_bf16 v[100:103], v[108:111], v[168:171], v[100:103]
	v_mfma_f32_16x16x32_bf16 v[100:103], v[116:119], v[180:183], v[100:103]
	v_mfma_f32_16x16x32_bf16 v[92:95], v[128:131], v[168:171], v[92:95]
	v_mfma_f32_16x16x32_bf16 v[92:95], v[140:143], v[180:183], v[92:95]
	v_mfma_f32_16x16x32_bf16 v[76:79], v[108:111], v[184:187], v[76:79]
	v_mfma_f32_16x16x32_bf16 v[76:79], v[116:119], v[188:191], v[76:79]
	v_mfma_f32_16x16x32_bf16 v[68:71], v[128:131], v[184:187], v[68:71]
	v_mfma_f32_16x16x32_bf16 v[68:71], v[140:143], v[188:191], v[68:71]
	s_barrier
	s_add_i32 s2, s67, s28
	v_lshl_add_u64 v[192:193], v[192:193], 0, s[30:31]
	s_mov_b32 m0, s2
	ds_read_b128 v[152:155], v240 offset:49152
	ds_read_b128 v[156:159], v240 offset:50176
	ds_read_b128 v[160:163], v240 offset:51200
	ds_read_b128 v[164:167], v240 offset:52224
	ds_read_b128 v[168:171], v240 offset:53248
	ds_read_b128 v[180:183], v240 offset:54272
	ds_read_b128 v[184:187], v240 offset:55296
	ds_read_b128 v[188:191], v240 offset:56320
	global_load_lds_dwordx4 v[192:193], off
	s_add_i32 m0, s2, 0x2000
	s_add_u32 s2, s92, 0x80080
	v_lshl_add_u64 v[192:193], v[194:195], 0, s[30:31]
	s_addc_u32 s3, s93, 0
	s_add_i32 s67, s76, s28
	global_load_lds_dwordx4 v[192:193], off
	v_lshl_add_u64 v[192:193], s[2:3], 0, v[216:217]
	s_mov_b32 m0, s67
	s_nop 0
	global_load_lds_dwordx4 v[192:193], off
	v_lshl_add_u64 v[192:193], s[2:3], 0, v[228:229]
	s_add_i32 m0, s67, 0x2000
	s_nop 0
	global_load_lds_dwordx4 v[192:193], off
	v_lshl_add_u64 v[192:193], v[196:197], 0, s[30:31]
	s_mov_b32 m0, s70
	s_nop 0
	global_load_lds_dwordx4 v[192:193], off
	v_lshl_add_u64 v[192:193], v[198:199], 0, s[30:31]
	s_mov_b32 m0, s71
	s_nop 0
	global_load_lds_dwordx4 v[192:193], off
	s_waitcnt vmcnt(8)
	s_waitcnt lgkmcnt(0)
	s_barrier
	s_waitcnt lgkmcnt(0)
	v_mfma_f32_16x16x32_bf16 v[60:63], v[64:67], v[152:155], v[60:63]
	v_mfma_f32_16x16x32_bf16 v[60:63], v[72:75], v[156:159], v[60:63]
	v_mfma_f32_16x16x32_bf16 v[56:59], v[88:91], v[152:155], v[56:59]
	v_mfma_f32_16x16x32_bf16 v[56:59], v[96:99], v[156:159], v[56:59]
	v_mfma_f32_16x16x32_bf16 v[44:47], v[64:67], v[160:163], v[44:47]
	v_mfma_f32_16x16x32_bf16 v[44:47], v[72:75], v[164:167], v[44:47]
	v_mfma_f32_16x16x32_bf16 v[40:43], v[88:91], v[160:163], v[40:43]
	v_mfma_f32_16x16x32_bf16 v[40:43], v[96:99], v[164:167], v[40:43]
	v_mfma_f32_16x16x32_bf16 v[28:31], v[64:67], v[168:171], v[28:31]
	v_mfma_f32_16x16x32_bf16 v[28:31], v[72:75], v[180:183], v[28:31]
	v_mfma_f32_16x16x32_bf16 v[24:27], v[88:91], v[168:171], v[24:27]
	v_mfma_f32_16x16x32_bf16 v[24:27], v[96:99], v[180:183], v[24:27]
	v_mfma_f32_16x16x32_bf16 v[12:15], v[64:67], v[184:187], v[12:15]
	v_mfma_f32_16x16x32_bf16 v[12:15], v[72:75], v[188:191], v[12:15]
	v_mfma_f32_16x16x32_bf16 v[8:11], v[88:91], v[184:187], v[8:11]
	v_mfma_f32_16x16x32_bf16 v[8:11], v[96:99], v[188:191], v[8:11]
	v_mfma_f32_16x16x32_bf16 v[52:55], v[108:111], v[152:155], v[52:55]
	v_mfma_f32_16x16x32_bf16 v[52:55], v[116:119], v[156:159], v[52:55]
	v_mfma_f32_16x16x32_bf16 v[48:51], v[128:131], v[152:155], v[48:51]
	v_mfma_f32_16x16x32_bf16 v[48:51], v[140:143], v[156:159], v[48:51]
	v_mfma_f32_16x16x32_bf16 v[36:39], v[108:111], v[160:163], v[36:39]
	v_mfma_f32_16x16x32_bf16 v[36:39], v[116:119], v[164:167], v[36:39]
	v_mfma_f32_16x16x32_bf16 v[32:35], v[128:131], v[160:163], v[32:35]
	v_mfma_f32_16x16x32_bf16 v[32:35], v[140:143], v[164:167], v[32:35]
	v_mfma_f32_16x16x32_bf16 v[20:23], v[108:111], v[168:171], v[20:23]
	v_mfma_f32_16x16x32_bf16 v[20:23], v[116:119], v[180:183], v[20:23]
	v_mfma_f32_16x16x32_bf16 v[16:19], v[128:131], v[168:171], v[16:19]
	v_mfma_f32_16x16x32_bf16 v[16:19], v[140:143], v[180:183], v[16:19]
	v_mfma_f32_16x16x32_bf16 v[4:7], v[108:111], v[184:187], v[4:7]
	v_mfma_f32_16x16x32_bf16 v[4:7], v[116:119], v[188:191], v[4:7]
	v_mfma_f32_16x16x32_bf16 v[0:3], v[128:131], v[184:187], v[0:3]
	v_mfma_f32_16x16x32_bf16 v[0:3], v[140:143], v[188:191], v[0:3]
	s_barrier
	s_add_i32 s20, s20, 2
	s_add_u32 s90, s90, 0x100
	s_addc_u32 s91, s91, 0
	s_add_u32 s89, s89, 0x100
	s_addc_u32 s14, s14, 0
	s_cmp_gt_u32 s20, 29
	s_cbranch_scc0 .LBB0_595
	s_and_b64 vcc, exec, s[74:75]
	s_cbranch_vccz .LBB0_598
	s_barrier

.LBB0_638:
	s_ashr_i32 s87, s86, 31
	s_lshl_b64 s[40:41], s[86:87], 20
	s_add_u32 s88, s14, s40
	s_addc_u32 s89, s15, s41
	s_and_b64 s[40:41], s[4:5], exec
	s_cselect_b32 s7, s89, s11
	s_cselect_b32 s9, s88, s10
	s_ashr_i32 s85, s84, 31
	s_lshl_b64 s[40:41], s[84:85], 20
	s_add_u32 s90, s24, s40
	s_addc_u32 s91, s26, s41
	s_and_b64 s[40:41], s[4:5], exec
	s_cselect_b32 s40, s91, s93
	s_cselect_b32 s41, s90, s92
	s_add_u32 s10, s10, 0x80080
	s_addc_u32 s11, s11, 0
	s_add_u32 s54, s92, 0x100
	s_addc_u32 s55, s93, 0
	s_mov_b32 s85, -2
	s_add_u32 s67, s10, 0xfff80080
	s_addc_u32 s87, s11, -1
	s_add_i32 s96, 0, 0x10000
	s_cmp_eq_u32 s85, 28
	s_cselect_b32 s95, s7, s87
	s_cselect_b32 s94, s9, s67
	s_cselect_b32 s93, s40, s55
	s_cselect_b32 s92, s41, s54
	s_add_i32 s67, 0, 0x14000
	v_add_u32_e32 v52, s96, v194
	v_add_u32_e32 v124, s67, v194
	ds_read_b128 v[40:43], v52
	ds_read_b128 v[44:47], v52 offset:1024
	ds_read_b128 v[48:51], v52 offset:2048
	ds_read_b128 v[52:55], v52 offset:3072
	ds_read_b128 v[64:67], v124
	ds_read_b128 v[100:103], v124 offset:1024
	ds_read_b128 v[120:123], v124 offset:2048
	ds_read_b128 v[124:127], v124 offset:3072
	v_lshl_add_u64 v[208:209], s[10:11], 0, v[186:187]
	s_add_i32 m0, s57, 0xc000
	ds_read_b128 v[136:139], v195
	ds_read_b128 v[140:143], v195 offset:1024
	ds_read_b128 v[144:147], v195 offset:2048
	ds_read_b128 v[172:175], v195 offset:3072
	ds_read_b128 v[190:193], v195 offset:4096
	ds_read_b128 v[196:199], v195 offset:5120
	ds_read_b128 v[200:203], v195 offset:6144
	ds_read_b128 v[204:207], v195 offset:7168
	global_load_lds_dwordx4 v[208:209], off
	v_lshl_add_u64 v[208:209], s[10:11], 0, v[188:189]
	s_add_i32 m0, s57, 0xe000
	s_nop 0
	global_load_lds_dwordx4 v[208:209], off
	s_waitcnt vmcnt(8)
	s_waitcnt lgkmcnt(0)
	s_barrier
	s_waitcnt lgkmcnt(0)
	v_mfma_f32_16x16x32_bf16 v[168:171], v[40:43], v[136:139], 0
	v_mfma_f32_16x16x32_bf16 v[168:171], v[44:47], v[140:143], v[168:171]
	v_mfma_f32_16x16x32_bf16 v[164:167], v[48:51], v[136:139], 0
	v_mfma_f32_16x16x32_bf16 v[164:167], v[52:55], v[140:143], v[164:167]
	v_mfma_f32_16x16x32_bf16 v[152:155], v[40:43], v[144:147], 0
	v_mfma_f32_16x16x32_bf16 v[152:155], v[44:47], v[172:175], v[152:155]
	v_mfma_f32_16x16x32_bf16 v[148:151], v[48:51], v[144:147], 0
	v_mfma_f32_16x16x32_bf16 v[148:151], v[52:55], v[172:175], v[148:151]
	v_mfma_f32_16x16x32_bf16 v[116:119], v[40:43], v[190:193], 0
	v_mfma_f32_16x16x32_bf16 v[116:119], v[44:47], v[196:199], v[116:119]
	v_mfma_f32_16x16x32_bf16 v[112:115], v[48:51], v[190:193], 0
	v_mfma_f32_16x16x32_bf16 v[112:115], v[52:55], v[196:199], v[112:115]
	v_mfma_f32_16x16x32_bf16 v[96:99], v[40:43], v[200:203], 0
	v_mfma_f32_16x16x32_bf16 v[96:99], v[44:47], v[204:207], v[96:99]
	v_mfma_f32_16x16x32_bf16 v[92:95], v[48:51], v[200:203], 0
	v_mfma_f32_16x16x32_bf16 v[92:95], v[52:55], v[204:207], v[92:95]
	v_mfma_f32_16x16x32_bf16 v[160:163], v[64:67], v[136:139], 0
	v_mfma_f32_16x16x32_bf16 v[160:163], v[100:103], v[140:143], v[160:163]
	v_mfma_f32_16x16x32_bf16 v[132:135], v[64:67], v[144:147], 0
	v_mfma_f32_16x16x32_bf16 v[132:135], v[100:103], v[172:175], v[132:135]
	v_mfma_f32_16x16x32_bf16 v[128:131], v[120:123], v[144:147], 0
	v_mfma_f32_16x16x32_bf16 v[128:131], v[124:127], v[172:175], v[128:131]
	v_mfma_f32_16x16x32_bf16 v[108:111], v[64:67], v[190:193], 0
	v_mfma_f32_16x16x32_bf16 v[108:111], v[100:103], v[196:199], v[108:111]
	v_mfma_f32_16x16x32_bf16 v[104:107], v[120:123], v[190:193], 0
	v_mfma_f32_16x16x32_bf16 v[104:107], v[124:127], v[196:199], v[104:107]
	v_mfma_f32_16x16x32_bf16 v[88:91], v[64:67], v[200:203], 0
	v_mfma_f32_16x16x32_bf16 v[88:91], v[100:103], v[204:207], v[88:91]
	v_mfma_f32_16x16x32_bf16 v[84:87], v[120:123], v[200:203], 0
	v_mfma_f32_16x16x32_bf16 v[84:87], v[124:127], v[204:207], v[84:87]
	v_mfma_f32_16x16x32_bf16 v[136:139], v[120:123], v[136:139], 0
	v_mfma_f32_16x16x32_bf16 v[136:139], v[124:127], v[140:143], v[136:139]
	s_barrier
	s_add_i32 s87, s96, s56
	v_lshl_add_u64 v[212:213], s[92:93], 0, v[178:179]
	s_mov_b32 m0, s87
	ds_read_b128 v[140:143], v195 offset:16384
	ds_read_b128 v[144:147], v195 offset:17408
	ds_read_b128 v[156:159], v195 offset:18432
	ds_read_b128 v[172:175], v195 offset:19456
	ds_read_b128 v[190:193], v195 offset:20480
	ds_read_b128 v[196:199], v195 offset:21504
	ds_read_b128 v[200:203], v195 offset:22528
	ds_read_b128 v[204:207], v195 offset:23552
	global_load_lds_dwordx4 v[212:213], off
	s_add_i32 m0, s87, 0x2000
	s_add_u32 vcc_lo, s92, 0x80000
	v_lshl_add_u64 v[214:215], s[92:93], 0, v[182:183]
	s_addc_u32 vcc_hi, s93, 0
	s_add_i32 s67, s67, s56
	global_load_lds_dwordx4 v[214:215], off
	v_lshl_add_u64 v[208:209], vcc, 0, v[178:179]
	s_mov_b32 m0, s67
	v_lshl_add_u64 v[224:225], s[94:95], 0, v[176:177]
	global_load_lds_dwordx4 v[208:209], off
	v_lshl_add_u64 v[208:209], vcc, 0, v[182:183]
	s_add_i32 m0, s67, 0x2000
	v_lshl_add_u64 v[226:227], s[94:95], 0, v[180:181]
	global_load_lds_dwordx4 v[208:209], off
	s_mov_b32 m0, s57
	s_nop 0
	global_load_lds_dwordx4 v[224:225], off
	s_mov_b32 m0, s61
	s_nop 0
	global_load_lds_dwordx4 v[226:227], off
	s_waitcnt vmcnt(8)
	s_waitcnt lgkmcnt(0)
	s_barrier
	s_waitcnt lgkmcnt(0)
	v_mfma_f32_16x16x32_bf16 v[80:83], v[40:43], v[140:143], 0
	v_mfma_f32_16x16x32_bf16 v[80:83], v[44:47], v[144:147], v[80:83]
	v_mfma_f32_16x16x32_bf16 v[76:79], v[48:51], v[140:143], 0
	v_mfma_f32_16x16x32_bf16 v[76:79], v[52:55], v[144:147], v[76:79]
	v_mfma_f32_16x16x32_bf16 v[60:63], v[40:43], v[156:159], 0
	v_mfma_f32_16x16x32_bf16 v[60:63], v[44:47], v[172:175], v[60:63]
	v_mfma_f32_16x16x32_bf16 v[56:59], v[48:51], v[156:159], 0
	v_mfma_f32_16x16x32_bf16 v[56:59], v[52:55], v[172:175], v[56:59]
	v_mfma_f32_16x16x32_bf16 v[28:31], v[40:43], v[190:193], 0
	v_mfma_f32_16x16x32_bf16 v[28:31], v[44:47], v[196:199], v[28:31]
	v_mfma_f32_16x16x32_bf16 v[24:27], v[48:51], v[190:193], 0
	v_mfma_f32_16x16x32_bf16 v[24:27], v[52:55], v[196:199], v[24:27]
	v_mfma_f32_16x16x32_bf16 v[12:15], v[40:43], v[200:203], 0
	v_mfma_f32_16x16x32_bf16 v[12:15], v[44:47], v[204:207], v[12:15]
	v_mfma_f32_16x16x32_bf16 v[8:11], v[48:51], v[200:203], 0
	v_mfma_f32_16x16x32_bf16 v[8:11], v[52:55], v[204:207], v[8:11]
	v_mfma_f32_16x16x32_bf16 v[36:39], v[64:67], v[156:159], 0
	v_mfma_f32_16x16x32_bf16 v[36:39], v[100:103], v[172:175], v[36:39]
	v_mfma_f32_16x16x32_bf16 v[32:35], v[120:123], v[156:159], 0
	v_mfma_f32_16x16x32_bf16 v[32:35], v[124:127], v[172:175], v[32:35]
	v_mfma_f32_16x16x32_bf16 v[20:23], v[64:67], v[190:193], 0
	v_mfma_f32_16x16x32_bf16 v[20:23], v[100:103], v[196:199], v[20:23]
	v_mfma_f32_16x16x32_bf16 v[16:19], v[120:123], v[190:193], 0
	v_mfma_f32_16x16x32_bf16 v[16:19], v[124:127], v[196:199], v[16:19]
	v_mfma_f32_16x16x32_bf16 v[4:7], v[64:67], v[200:203], 0
	v_mfma_f32_16x16x32_bf16 v[4:7], v[100:103], v[204:207], v[4:7]
	v_mfma_f32_16x16x32_bf16 v[0:3], v[120:123], v[200:203], 0
	v_mfma_f32_16x16x32_bf16 v[0:3], v[124:127], v[204:207], v[0:3]
	v_mfma_f32_16x16x32_bf16 v[40:43], v[64:67], v[140:143], 0
	v_mfma_f32_16x16x32_bf16 v[40:43], v[100:103], v[144:147], v[40:43]
	v_mfma_f32_16x16x32_bf16 v[44:47], v[120:123], v[140:143], 0
	v_mfma_f32_16x16x32_bf16 v[44:47], v[124:127], v[144:147], v[44:47]
	s_barrier
	s_add_i32 s67, 0, 0x18000
	s_add_i32 s87, 0, 0x1c000
	v_add_u32_e32 v68, s67, v194
	v_add_u32_e32 v72, s87, v194
	ds_read_b128 v[48:51], v68
	ds_read_b128 v[52:55], v68 offset:1024
	ds_read_b128 v[64:67], v68 offset:2048
	ds_read_b128 v[68:71], v68 offset:3072
	ds_read_b128 v[100:103], v72
	ds_read_b128 v[120:123], v72 offset:1024
	ds_read_b128 v[124:127], v72 offset:2048
	ds_read_b128 v[140:143], v72 offset:3072
	s_add_u32 s94, s94, 0x80000
	s_addc_u32 s95, s95, 0
	s_mov_b32 m0, s68
	v_lshl_add_u64 v[156:157], s[94:95], 0, v[176:177]
	ds_read_b128 v[72:75], v195 offset:32768
	ds_read_b128 v[144:147], v195 offset:33792
	ds_read_b128 v[172:175], v195 offset:34816
	ds_read_b128 v[190:193], v195 offset:35840
	ds_read_b128 v[196:199], v195 offset:36864
	ds_read_b128 v[200:203], v195 offset:37888
	ds_read_b128 v[204:207], v195 offset:38912
	ds_read_b128 v[208:211], v195 offset:39936
	global_load_lds_dwordx4 v[156:157], off
	v_lshl_add_u64 v[156:157], s[94:95], 0, v[180:181]
	s_mov_b32 m0, s69
	s_nop 0
	global_load_lds_dwordx4 v[156:157], off
	s_waitcnt vmcnt(8)
	s_waitcnt lgkmcnt(0)
	s_barrier
	s_waitcnt lgkmcnt(0)
	v_mfma_f32_16x16x32_bf16 v[156:159], v[48:51], v[72:75], v[168:171]
	v_mfma_f32_16x16x32_bf16 v[168:171], v[52:55], v[144:147], v[156:159]
	v_mfma_f32_16x16x32_bf16 v[156:159], v[64:67], v[72:75], v[164:167]
	v_mfma_f32_16x16x32_bf16 v[152:155], v[48:51], v[172:175], v[152:155]
	v_mfma_f32_16x16x32_bf16 v[148:151], v[64:67], v[172:175], v[148:151]
	v_mfma_f32_16x16x32_bf16 v[116:119], v[48:51], v[196:199], v[116:119]
	v_mfma_f32_16x16x32_bf16 v[112:115], v[64:67], v[196:199], v[112:115]
	v_mfma_f32_16x16x32_bf16 v[96:99], v[48:51], v[204:207], v[96:99]
	v_mfma_f32_16x16x32_bf16 v[92:95], v[64:67], v[204:207], v[92:95]
	v_mfma_f32_16x16x32_bf16 v[164:167], v[68:71], v[144:147], v[156:159]
	v_mfma_f32_16x16x32_bf16 v[152:155], v[52:55], v[190:193], v[152:155]
	v_mfma_f32_16x16x32_bf16 v[148:151], v[68:71], v[190:193], v[148:151]
	v_mfma_f32_16x16x32_bf16 v[116:119], v[52:55], v[200:203], v[116:119]
	v_mfma_f32_16x16x32_bf16 v[112:115], v[68:71], v[200:203], v[112:115]
	v_mfma_f32_16x16x32_bf16 v[96:99], v[52:55], v[208:211], v[96:99]
	v_mfma_f32_16x16x32_bf16 v[92:95], v[68:71], v[208:211], v[92:95]
	v_mfma_f32_16x16x32_bf16 v[156:159], v[100:103], v[72:75], v[160:163]
	v_mfma_f32_16x16x32_bf16 v[72:75], v[124:127], v[72:75], v[136:139]
	v_mfma_f32_16x16x32_bf16 v[160:163], v[120:123], v[144:147], v[156:159]
	v_mfma_f32_16x16x32_bf16 v[156:159], v[140:143], v[144:147], v[72:75]
	v_mfma_f32_16x16x32_bf16 v[72:75], v[100:103], v[172:175], v[132:135]
	v_mfma_f32_16x16x32_bf16 v[132:135], v[120:123], v[190:193], v[72:75]
	v_mfma_f32_16x16x32_bf16 v[72:75], v[124:127], v[172:175], v[128:131]
	v_mfma_f32_16x16x32_bf16 v[128:131], v[140:143], v[190:193], v[72:75]
	v_mfma_f32_16x16x32_bf16 v[72:75], v[100:103], v[196:199], v[108:111]
	v_mfma_f32_16x16x32_bf16 v[108:111], v[120:123], v[200:203], v[72:75]
	v_mfma_f32_16x16x32_bf16 v[72:75], v[124:127], v[196:199], v[104:107]
	v_mfma_f32_16x16x32_bf16 v[104:107], v[140:143], v[200:203], v[72:75]
	v_mfma_f32_16x16x32_bf16 v[72:75], v[100:103], v[204:207], v[88:91]
	v_mfma_f32_16x16x32_bf16 v[88:91], v[120:123], v[208:211], v[72:75]
	v_mfma_f32_16x16x32_bf16 v[72:75], v[124:127], v[204:207], v[84:87]
	v_mfma_f32_16x16x32_bf16 v[84:87], v[140:143], v[208:211], v[72:75]
	s_barrier
	s_add_i32 s67, s67, s56
	s_nop 3
	v_lshl_add_u64 v[72:73], v[212:213], 0, s[30:31]
	s_mov_b32 m0, s67
	ds_read_b128 v[136:139], v195 offset:49152
	ds_read_b128 v[144:147], v195 offset:50176
	ds_read_b128 v[172:175], v195 offset:51200
	ds_read_b128 v[190:193], v195 offset:52224
	ds_read_b128 v[196:199], v195 offset:53248
	ds_read_b128 v[200:203], v195 offset:54272
	ds_read_b128 v[204:207], v195 offset:55296
	ds_read_b128 v[208:211], v195 offset:56320
	global_load_lds_dwordx4 v[72:73], off
	s_add_i32 m0, s67, 0x2000
	s_add_u32 s92, s92, 0x80080
	v_lshl_add_u64 v[72:73], v[214:215], 0, s[30:31]
	s_addc_u32 s93, s93, 0
	s_add_i32 s67, s87, s56
	global_load_lds_dwordx4 v[72:73], off
	v_lshl_add_u64 v[72:73], s[92:93], 0, v[178:179]
	s_mov_b32 m0, s67
	s_nop 0
	global_load_lds_dwordx4 v[72:73], off
	v_lshl_add_u64 v[72:73], s[92:93], 0, v[182:183]
	s_add_i32 m0, s67, 0x2000
	s_nop 0
	global_load_lds_dwordx4 v[72:73], off
	v_lshl_add_u64 v[72:73], v[224:225], 0, s[30:31]
	s_mov_b32 m0, s2
	s_nop 0
	global_load_lds_dwordx4 v[72:73], off
	v_lshl_add_u64 v[72:73], v[226:227], 0, s[30:31]
	s_mov_b32 m0, s28
	s_nop 0
	global_load_lds_dwordx4 v[72:73], off
	s_waitcnt vmcnt(8)
	s_waitcnt lgkmcnt(0)
	s_barrier
	s_waitcnt lgkmcnt(0)
	v_mfma_f32_16x16x32_bf16 v[72:75], v[48:51], v[136:139], v[80:83]
	v_mfma_f32_16x16x32_bf16 v[80:83], v[52:55], v[144:147], v[72:75]
	v_mfma_f32_16x16x32_bf16 v[72:75], v[64:67], v[136:139], v[76:79]
	v_mfma_f32_16x16x32_bf16 v[60:63], v[48:51], v[172:175], v[60:63]
	v_mfma_f32_16x16x32_bf16 v[56:59], v[64:67], v[172:175], v[56:59]
	v_mfma_f32_16x16x32_bf16 v[28:31], v[48:51], v[196:199], v[28:31]
	v_mfma_f32_16x16x32_bf16 v[24:27], v[64:67], v[196:199], v[24:27]
	v_mfma_f32_16x16x32_bf16 v[12:15], v[48:51], v[204:207], v[12:15]
	v_mfma_f32_16x16x32_bf16 v[8:11], v[64:67], v[204:207], v[8:11]
	v_mfma_f32_16x16x32_bf16 v[76:79], v[68:71], v[144:147], v[72:75]
	v_mfma_f32_16x16x32_bf16 v[60:63], v[52:55], v[190:193], v[60:63]
	v_mfma_f32_16x16x32_bf16 v[56:59], v[68:71], v[190:193], v[56:59]
	v_mfma_f32_16x16x32_bf16 v[28:31], v[52:55], v[200:203], v[28:31]
	v_mfma_f32_16x16x32_bf16 v[24:27], v[68:71], v[200:203], v[24:27]
	v_mfma_f32_16x16x32_bf16 v[12:15], v[52:55], v[208:211], v[12:15]
	v_mfma_f32_16x16x32_bf16 v[8:11], v[68:71], v[208:211], v[8:11]
	v_mfma_f32_16x16x32_bf16 v[40:43], v[100:103], v[136:139], v[40:43]
	v_mfma_f32_16x16x32_bf16 v[72:75], v[120:123], v[144:147], v[40:43]
	v_mfma_f32_16x16x32_bf16 v[40:43], v[124:127], v[136:139], v[44:47]
	v_mfma_f32_16x16x32_bf16 v[36:39], v[100:103], v[172:175], v[36:39]
	v_mfma_f32_16x16x32_bf16 v[32:35], v[124:127], v[172:175], v[32:35]
	v_mfma_f32_16x16x32_bf16 v[20:23], v[100:103], v[196:199], v[20:23]
	v_mfma_f32_16x16x32_bf16 v[16:19], v[124:127], v[196:199], v[16:19]
	v_mfma_f32_16x16x32_bf16 v[4:7], v[100:103], v[204:207], v[4:7]
	v_mfma_f32_16x16x32_bf16 v[0:3], v[124:127], v[204:207], v[0:3]
	v_mfma_f32_16x16x32_bf16 v[68:71], v[140:143], v[144:147], v[40:43]
	v_mfma_f32_16x16x32_bf16 v[36:39], v[120:123], v[190:193], v[36:39]
	v_mfma_f32_16x16x32_bf16 v[32:35], v[140:143], v[190:193], v[32:35]
	v_mfma_f32_16x16x32_bf16 v[20:23], v[120:123], v[200:203], v[20:23]
	v_mfma_f32_16x16x32_bf16 v[16:19], v[140:143], v[200:203], v[16:19]
	v_mfma_f32_16x16x32_bf16 v[4:7], v[120:123], v[208:211], v[4:7]
	v_mfma_f32_16x16x32_bf16 v[0:3], v[140:143], v[208:211], v[0:3]
	s_barrier
	s_add_i32 s85, s85, 2
	s_add_u32 s10, s10, 0x100
	s_addc_u32 s11, s11, 0
	s_add_u32 s54, s54, 0x100
	s_addc_u32 s55, s55, 0
.LBB0_639:
	s_add_u32 s67, s10, 0xfff80080
	s_addc_u32 s87, s11, -1
	s_add_i32 s96, 0, 0x10000
	s_cmp_eq_u32 s85, 28
	s_cselect_b32 s95, s7, s87
	s_cselect_b32 s94, s9, s67
	s_cselect_b32 s93, s40, s55
	s_cselect_b32 s92, s41, s54
	s_add_i32 s67, 0, 0x14000
	v_add_u32_e32 v52, s96, v194
	v_add_u32_e32 v124, s67, v194
	ds_read_b128 v[40:43], v52
	ds_read_b128 v[44:47], v52 offset:1024
	ds_read_b128 v[48:51], v52 offset:2048
	ds_read_b128 v[52:55], v52 offset:3072
	ds_read_b128 v[64:67], v124
	ds_read_b128 v[100:103], v124 offset:1024
	ds_read_b128 v[120:123], v124 offset:2048
	ds_read_b128 v[124:127], v124 offset:3072
	v_lshl_add_u64 v[208:209], s[10:11], 0, v[186:187]
	s_add_i32 m0, s57, 0xc000
	ds_read_b128 v[136:139], v195
	ds_read_b128 v[140:143], v195 offset:1024
	ds_read_b128 v[144:147], v195 offset:2048
	ds_read_b128 v[172:175], v195 offset:3072
	ds_read_b128 v[190:193], v195 offset:4096
	ds_read_b128 v[196:199], v195 offset:5120
	ds_read_b128 v[200:203], v195 offset:6144
	ds_read_b128 v[204:207], v195 offset:7168
	global_load_lds_dwordx4 v[208:209], off
	v_lshl_add_u64 v[208:209], s[10:11], 0, v[188:189]
	s_add_i32 m0, s57, 0xe000
	s_nop 0
	global_load_lds_dwordx4 v[208:209], off
	s_waitcnt vmcnt(8)
	s_waitcnt lgkmcnt(0)
	s_barrier
	s_waitcnt lgkmcnt(0)
	v_mfma_f32_16x16x32_bf16 v[168:171], v[40:43], v[136:139], v[168:171]
	v_mfma_f32_16x16x32_bf16 v[168:171], v[44:47], v[140:143], v[168:171]
	v_mfma_f32_16x16x32_bf16 v[164:167], v[48:51], v[136:139], v[164:167]
	v_mfma_f32_16x16x32_bf16 v[164:167], v[52:55], v[140:143], v[164:167]
	v_mfma_f32_16x16x32_bf16 v[152:155], v[40:43], v[144:147], v[152:155]
	v_mfma_f32_16x16x32_bf16 v[152:155], v[44:47], v[172:175], v[152:155]
	v_mfma_f32_16x16x32_bf16 v[148:151], v[48:51], v[144:147], v[148:151]
	v_mfma_f32_16x16x32_bf16 v[148:151], v[52:55], v[172:175], v[148:151]
	v_mfma_f32_16x16x32_bf16 v[116:119], v[40:43], v[190:193], v[116:119]
	v_mfma_f32_16x16x32_bf16 v[116:119], v[44:47], v[196:199], v[116:119]
	v_mfma_f32_16x16x32_bf16 v[112:115], v[48:51], v[190:193], v[112:115]
	v_mfma_f32_16x16x32_bf16 v[112:115], v[52:55], v[196:199], v[112:115]
	v_mfma_f32_16x16x32_bf16 v[96:99], v[40:43], v[200:203], v[96:99]
	v_mfma_f32_16x16x32_bf16 v[96:99], v[44:47], v[204:207], v[96:99]
	v_mfma_f32_16x16x32_bf16 v[92:95], v[48:51], v[200:203], v[92:95]
	v_mfma_f32_16x16x32_bf16 v[92:95], v[52:55], v[204:207], v[92:95]
	v_mfma_f32_16x16x32_bf16 v[160:163], v[64:67], v[136:139], v[160:163]
	v_mfma_f32_16x16x32_bf16 v[160:163], v[100:103], v[140:143], v[160:163]
	v_mfma_f32_16x16x32_bf16 v[132:135], v[64:67], v[144:147], v[132:135]
	v_mfma_f32_16x16x32_bf16 v[132:135], v[100:103], v[172:175], v[132:135]
	v_mfma_f32_16x16x32_bf16 v[128:131], v[120:123], v[144:147], v[128:131]
	v_mfma_f32_16x16x32_bf16 v[128:131], v[124:127], v[172:175], v[128:131]
	v_mfma_f32_16x16x32_bf16 v[108:111], v[64:67], v[190:193], v[108:111]
	v_mfma_f32_16x16x32_bf16 v[108:111], v[100:103], v[196:199], v[108:111]
	v_mfma_f32_16x16x32_bf16 v[104:107], v[120:123], v[190:193], v[104:107]
	v_mfma_f32_16x16x32_bf16 v[104:107], v[124:127], v[196:199], v[104:107]
	v_mfma_f32_16x16x32_bf16 v[88:91], v[64:67], v[200:203], v[88:91]
	v_mfma_f32_16x16x32_bf16 v[88:91], v[100:103], v[204:207], v[88:91]
	v_mfma_f32_16x16x32_bf16 v[84:87], v[120:123], v[200:203], v[84:87]
	v_mfma_f32_16x16x32_bf16 v[84:87], v[124:127], v[204:207], v[84:87]
	v_mfma_f32_16x16x32_bf16 v[136:139], v[120:123], v[136:139], v[156:159]
	v_mfma_f32_16x16x32_bf16 v[136:139], v[124:127], v[140:143], v[136:139]
	s_barrier
	s_add_i32 s87, s96, s56
	v_lshl_add_u64 v[212:213], s[92:93], 0, v[178:179]
	s_mov_b32 m0, s87
	ds_read_b128 v[140:143], v195 offset:16384
	ds_read_b128 v[144:147], v195 offset:17408
	ds_read_b128 v[156:159], v195 offset:18432
	ds_read_b128 v[172:175], v195 offset:19456
	ds_read_b128 v[190:193], v195 offset:20480
	ds_read_b128 v[196:199], v195 offset:21504
	ds_read_b128 v[200:203], v195 offset:22528
	ds_read_b128 v[204:207], v195 offset:23552
	global_load_lds_dwordx4 v[212:213], off
	s_add_i32 m0, s87, 0x2000
	s_add_u32 vcc_lo, s92, 0x80000
	v_lshl_add_u64 v[214:215], s[92:93], 0, v[182:183]
	s_addc_u32 vcc_hi, s93, 0
	s_add_i32 s67, s67, s56
	global_load_lds_dwordx4 v[214:215], off
	v_lshl_add_u64 v[208:209], vcc, 0, v[178:179]
	s_mov_b32 m0, s67
	v_lshl_add_u64 v[224:225], s[94:95], 0, v[176:177]
	global_load_lds_dwordx4 v[208:209], off
	v_lshl_add_u64 v[208:209], vcc, 0, v[182:183]
	s_add_i32 m0, s67, 0x2000
	v_lshl_add_u64 v[226:227], s[94:95], 0, v[180:181]
	global_load_lds_dwordx4 v[208:209], off
	s_mov_b32 m0, s57
	s_nop 0
	global_load_lds_dwordx4 v[224:225], off
	s_mov_b32 m0, s61
	s_nop 0
	global_load_lds_dwordx4 v[226:227], off
	s_waitcnt vmcnt(8)
	s_waitcnt lgkmcnt(0)
	s_barrier
	s_waitcnt lgkmcnt(0)
	v_mfma_f32_16x16x32_bf16 v[80:83], v[40:43], v[140:143], v[80:83]
	v_mfma_f32_16x16x32_bf16 v[80:83], v[44:47], v[144:147], v[80:83]
	v_mfma_f32_16x16x32_bf16 v[76:79], v[48:51], v[140:143], v[76:79]
	v_mfma_f32_16x16x32_bf16 v[76:79], v[52:55], v[144:147], v[76:79]
	v_mfma_f32_16x16x32_bf16 v[60:63], v[40:43], v[156:159], v[60:63]
	v_mfma_f32_16x16x32_bf16 v[60:63], v[44:47], v[172:175], v[60:63]
	v_mfma_f32_16x16x32_bf16 v[56:59], v[48:51], v[156:159], v[56:59]
	v_mfma_f32_16x16x32_bf16 v[56:59], v[52:55], v[172:175], v[56:59]
	v_mfma_f32_16x16x32_bf16 v[28:31], v[40:43], v[190:193], v[28:31]
	v_mfma_f32_16x16x32_bf16 v[28:31], v[44:47], v[196:199], v[28:31]
	v_mfma_f32_16x16x32_bf16 v[24:27], v[48:51], v[190:193], v[24:27]
	v_mfma_f32_16x16x32_bf16 v[24:27], v[52:55], v[196:199], v[24:27]
	v_mfma_f32_16x16x32_bf16 v[12:15], v[40:43], v[200:203], v[12:15]
	v_mfma_f32_16x16x32_bf16 v[12:15], v[44:47], v[204:207], v[12:15]
	v_mfma_f32_16x16x32_bf16 v[8:11], v[48:51], v[200:203], v[8:11]
	v_mfma_f32_16x16x32_bf16 v[8:11], v[52:55], v[204:207], v[8:11]
	v_mfma_f32_16x16x32_bf16 v[36:39], v[64:67], v[156:159], v[36:39]
	v_mfma_f32_16x16x32_bf16 v[36:39], v[100:103], v[172:175], v[36:39]
	v_mfma_f32_16x16x32_bf16 v[32:35], v[120:123], v[156:159], v[32:35]
	v_mfma_f32_16x16x32_bf16 v[32:35], v[124:127], v[172:175], v[32:35]
	v_mfma_f32_16x16x32_bf16 v[20:23], v[64:67], v[190:193], v[20:23]
	v_mfma_f32_16x16x32_bf16 v[20:23], v[100:103], v[196:199], v[20:23]
	v_mfma_f32_16x16x32_bf16 v[16:19], v[120:123], v[190:193], v[16:19]
	v_mfma_f32_16x16x32_bf16 v[16:19], v[124:127], v[196:199], v[16:19]
	v_mfma_f32_16x16x32_bf16 v[4:7], v[64:67], v[200:203], v[4:7]
	v_mfma_f32_16x16x32_bf16 v[4:7], v[100:103], v[204:207], v[4:7]
	v_mfma_f32_16x16x32_bf16 v[0:3], v[120:123], v[200:203], v[0:3]
	v_mfma_f32_16x16x32_bf16 v[0:3], v[124:127], v[204:207], v[0:3]
	v_mfma_f32_16x16x32_bf16 v[40:43], v[64:67], v[140:143], v[72:75]
	v_mfma_f32_16x16x32_bf16 v[40:43], v[100:103], v[144:147], v[40:43]
	v_mfma_f32_16x16x32_bf16 v[44:47], v[120:123], v[140:143], v[68:71]
	v_mfma_f32_16x16x32_bf16 v[44:47], v[124:127], v[144:147], v[44:47]
	s_barrier
	s_add_i32 s67, 0, 0x18000
	s_add_i32 s87, 0, 0x1c000
	v_add_u32_e32 v68, s67, v194
	v_add_u32_e32 v72, s87, v194
	ds_read_b128 v[48:51], v68
	ds_read_b128 v[52:55], v68 offset:1024
	ds_read_b128 v[64:67], v68 offset:2048
	ds_read_b128 v[68:71], v68 offset:3072
	ds_read_b128 v[100:103], v72
	ds_read_b128 v[120:123], v72 offset:1024
	ds_read_b128 v[124:127], v72 offset:2048
	ds_read_b128 v[140:143], v72 offset:3072
	s_add_u32 s94, s94, 0x80000
	s_addc_u32 s95, s95, 0
	s_mov_b32 m0, s68
	v_lshl_add_u64 v[156:157], s[94:95], 0, v[176:177]
	ds_read_b128 v[72:75], v195 offset:32768
	ds_read_b128 v[144:147], v195 offset:33792
	ds_read_b128 v[172:175], v195 offset:34816
	ds_read_b128 v[190:193], v195 offset:35840
	ds_read_b128 v[196:199], v195 offset:36864
	ds_read_b128 v[200:203], v195 offset:37888
	ds_read_b128 v[204:207], v195 offset:38912
	ds_read_b128 v[208:211], v195 offset:39936
	global_load_lds_dwordx4 v[156:157], off
	v_lshl_add_u64 v[156:157], s[94:95], 0, v[180:181]
	s_mov_b32 m0, s69
	s_nop 0
	global_load_lds_dwordx4 v[156:157], off
	s_waitcnt vmcnt(8)
	s_waitcnt lgkmcnt(0)
	s_barrier
	s_waitcnt lgkmcnt(0)
	v_mfma_f32_16x16x32_bf16 v[156:159], v[48:51], v[72:75], v[168:171]
	v_mfma_f32_16x16x32_bf16 v[168:171], v[52:55], v[144:147], v[156:159]
	v_mfma_f32_16x16x32_bf16 v[156:159], v[64:67], v[72:75], v[164:167]
	v_mfma_f32_16x16x32_bf16 v[152:155], v[48:51], v[172:175], v[152:155]
	v_mfma_f32_16x16x32_bf16 v[148:151], v[64:67], v[172:175], v[148:151]
	v_mfma_f32_16x16x32_bf16 v[116:119], v[48:51], v[196:199], v[116:119]
	v_mfma_f32_16x16x32_bf16 v[112:115], v[64:67], v[196:199], v[112:115]
	v_mfma_f32_16x16x32_bf16 v[96:99], v[48:51], v[204:207], v[96:99]
	v_mfma_f32_16x16x32_bf16 v[92:95], v[64:67], v[204:207], v[92:95]
	v_mfma_f32_16x16x32_bf16 v[164:167], v[68:71], v[144:147], v[156:159]
	v_mfma_f32_16x16x32_bf16 v[152:155], v[52:55], v[190:193], v[152:155]
	v_mfma_f32_16x16x32_bf16 v[148:151], v[68:71], v[190:193], v[148:151]
	v_mfma_f32_16x16x32_bf16 v[116:119], v[52:55], v[200:203], v[116:119]
	v_mfma_f32_16x16x32_bf16 v[112:115], v[68:71], v[200:203], v[112:115]
	v_mfma_f32_16x16x32_bf16 v[96:99], v[52:55], v[208:211], v[96:99]
	v_mfma_f32_16x16x32_bf16 v[92:95], v[68:71], v[208:211], v[92:95]
	v_mfma_f32_16x16x32_bf16 v[156:159], v[100:103], v[72:75], v[160:163]
	v_mfma_f32_16x16x32_bf16 v[72:75], v[124:127], v[72:75], v[136:139]
	v_mfma_f32_16x16x32_bf16 v[160:163], v[120:123], v[144:147], v[156:159]
	v_mfma_f32_16x16x32_bf16 v[156:159], v[140:143], v[144:147], v[72:75]
	v_mfma_f32_16x16x32_bf16 v[72:75], v[100:103], v[172:175], v[132:135]
	v_mfma_f32_16x16x32_bf16 v[132:135], v[120:123], v[190:193], v[72:75]
	v_mfma_f32_16x16x32_bf16 v[72:75], v[124:127], v[172:175], v[128:131]
	v_mfma_f32_16x16x32_bf16 v[128:131], v[140:143], v[190:193], v[72:75]
	v_mfma_f32_16x16x32_bf16 v[72:75], v[100:103], v[196:199], v[108:111]
	v_mfma_f32_16x16x32_bf16 v[108:111], v[120:123], v[200:203], v[72:75]
	v_mfma_f32_16x16x32_bf16 v[72:75], v[124:127], v[196:199], v[104:107]
	v_mfma_f32_16x16x32_bf16 v[104:107], v[140:143], v[200:203], v[72:75]
	v_mfma_f32_16x16x32_bf16 v[72:75], v[100:103], v[204:207], v[88:91]
	v_mfma_f32_16x16x32_bf16 v[88:91], v[120:123], v[208:211], v[72:75]
	v_mfma_f32_16x16x32_bf16 v[72:75], v[124:127], v[204:207], v[84:87]
	v_mfma_f32_16x16x32_bf16 v[84:87], v[140:143], v[208:211], v[72:75]
	s_barrier
	s_add_i32 s67, s67, s56
	s_nop 3
	v_lshl_add_u64 v[72:73], v[212:213], 0, s[30:31]
	s_mov_b32 m0, s67
	ds_read_b128 v[136:139], v195 offset:49152
	ds_read_b128 v[144:147], v195 offset:50176
	ds_read_b128 v[172:175], v195 offset:51200
	ds_read_b128 v[190:193], v195 offset:52224
	ds_read_b128 v[196:199], v195 offset:53248
	ds_read_b128 v[200:203], v195 offset:54272
	ds_read_b128 v[204:207], v195 offset:55296
	ds_read_b128 v[208:211], v195 offset:56320
	global_load_lds_dwordx4 v[72:73], off
	s_add_i32 m0, s67, 0x2000
	s_add_u32 s92, s92, 0x80080
	v_lshl_add_u64 v[72:73], v[214:215], 0, s[30:31]
	s_addc_u32 s93, s93, 0
	s_add_i32 s67, s87, s56
	global_load_lds_dwordx4 v[72:73], off
	v_lshl_add_u64 v[72:73], s[92:93], 0, v[178:179]
	s_mov_b32 m0, s67
	s_nop 0
	global_load_lds_dwordx4 v[72:73], off
	v_lshl_add_u64 v[72:73], s[92:93], 0, v[182:183]
	s_add_i32 m0, s67, 0x2000
	s_nop 0
	global_load_lds_dwordx4 v[72:73], off
	v_lshl_add_u64 v[72:73], v[224:225], 0, s[30:31]
	s_mov_b32 m0, s2
	s_nop 0
	global_load_lds_dwordx4 v[72:73], off
	v_lshl_add_u64 v[72:73], v[226:227], 0, s[30:31]
	s_mov_b32 m0, s28
	s_nop 0
	global_load_lds_dwordx4 v[72:73], off
	s_waitcnt vmcnt(8)
	s_waitcnt lgkmcnt(0)
	s_barrier
	s_waitcnt lgkmcnt(0)
	v_mfma_f32_16x16x32_bf16 v[72:75], v[48:51], v[136:139], v[80:83]
	v_mfma_f32_16x16x32_bf16 v[80:83], v[52:55], v[144:147], v[72:75]
	v_mfma_f32_16x16x32_bf16 v[72:75], v[64:67], v[136:139], v[76:79]
	v_mfma_f32_16x16x32_bf16 v[60:63], v[48:51], v[172:175], v[60:63]
	v_mfma_f32_16x16x32_bf16 v[56:59], v[64:67], v[172:175], v[56:59]
	v_mfma_f32_16x16x32_bf16 v[28:31], v[48:51], v[196:199], v[28:31]
	v_mfma_f32_16x16x32_bf16 v[24:27], v[64:67], v[196:199], v[24:27]
	v_mfma_f32_16x16x32_bf16 v[12:15], v[48:51], v[204:207], v[12:15]
	v_mfma_f32_16x16x32_bf16 v[8:11], v[64:67], v[204:207], v[8:11]
	v_mfma_f32_16x16x32_bf16 v[76:79], v[68:71], v[144:147], v[72:75]
	v_mfma_f32_16x16x32_bf16 v[60:63], v[52:55], v[190:193], v[60:63]
	v_mfma_f32_16x16x32_bf16 v[56:59], v[68:71], v[190:193], v[56:59]
	v_mfma_f32_16x16x32_bf16 v[28:31], v[52:55], v[200:203], v[28:31]
	v_mfma_f32_16x16x32_bf16 v[24:27], v[68:71], v[200:203], v[24:27]
	v_mfma_f32_16x16x32_bf16 v[12:15], v[52:55], v[208:211], v[12:15]
	v_mfma_f32_16x16x32_bf16 v[8:11], v[68:71], v[208:211], v[8:11]
	v_mfma_f32_16x16x32_bf16 v[40:43], v[100:103], v[136:139], v[40:43]
	v_mfma_f32_16x16x32_bf16 v[72:75], v[120:123], v[144:147], v[40:43]
	v_mfma_f32_16x16x32_bf16 v[40:43], v[124:127], v[136:139], v[44:47]
	v_mfma_f32_16x16x32_bf16 v[36:39], v[100:103], v[172:175], v[36:39]
	v_mfma_f32_16x16x32_bf16 v[32:35], v[124:127], v[172:175], v[32:35]
	v_mfma_f32_16x16x32_bf16 v[20:23], v[100:103], v[196:199], v[20:23]
	v_mfma_f32_16x16x32_bf16 v[16:19], v[124:127], v[196:199], v[16:19]
	v_mfma_f32_16x16x32_bf16 v[4:7], v[100:103], v[204:207], v[4:7]
	v_mfma_f32_16x16x32_bf16 v[0:3], v[124:127], v[204:207], v[0:3]
	v_mfma_f32_16x16x32_bf16 v[68:71], v[140:143], v[144:147], v[40:43]
	v_mfma_f32_16x16x32_bf16 v[36:39], v[120:123], v[190:193], v[36:39]
	v_mfma_f32_16x16x32_bf16 v[32:35], v[140:143], v[190:193], v[32:35]
	v_mfma_f32_16x16x32_bf16 v[20:23], v[120:123], v[200:203], v[20:23]
	v_mfma_f32_16x16x32_bf16 v[16:19], v[140:143], v[200:203], v[16:19]
	v_mfma_f32_16x16x32_bf16 v[4:7], v[120:123], v[208:211], v[4:7]
	v_mfma_f32_16x16x32_bf16 v[0:3], v[140:143], v[208:211], v[0:3]
	s_barrier
	s_add_i32 s85, s85, 2
	s_add_u32 s10, s10, 0x100
	s_addc_u32 s11, s11, 0
	s_add_u32 s54, s54, 0x100
	s_addc_u32 s55, s55, 0
	s_cmp_gt_u32 s85, 29
	s_cbranch_scc0 .LBB0_639
	s_and_b64 vcc, exec, s[80:81]
	s_cbranch_vccz .LBB0_642
	s_barrier

.LBB0_964:
	s_ashr_i32 s79, s78, 31
	s_lshl_b64 s[82:83], s[78:79], 20
	s_add_u32 s82, s14, s82
	s_addc_u32 s83, s15, s83
	s_and_b64 s[84:85], s[80:81], exec
	s_cselect_b32 s79, s83, s93
	s_cselect_b32 s96, s82, s92
	s_ashr_i32 s77, s76, 31
	s_lshl_b64 s[84:85], s[76:77], 20
	s_add_u32 s84, s24, s84
	s_addc_u32 s85, s26, s85
	s_and_b64 vcc, s[80:81], exec
	s_cselect_b32 s77, s85, s91
	s_cselect_b32 vcc_lo, s84, s90
	s_lshl_b32 s86, s86, 8
	s_ashr_i32 s87, s86, 31
	s_lshl_b64 s[74:75], s[86:87], 2
	s_add_u32 s74, s88, s74
	s_addc_u32 s75, s89, s75
	s_add_i32 m0, s71, s40
	s_add_u32 s88, s92, 0x80080
	global_load_lds_dwordx4 v239, s[74:75]
	s_addc_u32 s89, s93, 0
	s_add_u32 s87, s90, 0x100
	s_addc_u32 vcc_hi, s91, 0
	s_mov_b32 s71, -2
	s_waitcnt vmcnt(0)
	s_add_u32 s67, s88, 0xfff80080
	s_addc_u32 s74, s89, -1
	s_add_i32 s75, 0, 0x10000
	s_cmp_eq_u32 s71, 28
	s_cselect_b32 s93, s79, s74
	s_cselect_b32 s92, s96, s67
	s_cselect_b32 s91, s77, vcc_hi
	s_cselect_b32 s90, vcc_lo, s87
	s_add_i32 s67, 0, 0x14000
	v_add_u32_e32 v96, s75, v238
	v_add_u32_e32 v140, s67, v238
	ds_read_b128 v[64:67], v96
	ds_read_b128 v[72:75], v96 offset:1024
	ds_read_b128 v[88:91], v96 offset:2048
	ds_read_b128 v[96:99], v96 offset:3072
	ds_read_b128 v[108:111], v140
	ds_read_b128 v[116:119], v140 offset:1024
	ds_read_b128 v[128:131], v140 offset:2048
	ds_read_b128 v[140:143], v140 offset:3072
	v_lshl_add_u64 v[192:193], s[88:89], 0, v[230:231]
	s_add_i32 m0, s28, 0xc000
	ds_read_b128 v[152:155], v240
	ds_read_b128 v[156:159], v240 offset:1024
	ds_read_b128 v[160:163], v240 offset:2048
	ds_read_b128 v[164:167], v240 offset:3072
	ds_read_b128 v[168:171], v240 offset:4096
	ds_read_b128 v[180:183], v240 offset:5120
	ds_read_b128 v[184:187], v240 offset:6144
	ds_read_b128 v[188:191], v240 offset:7168
	global_load_lds_dwordx4 v[192:193], off
	v_lshl_add_u64 v[192:193], s[88:89], 0, v[232:233]
	s_add_i32 m0, s28, 0xe000
	s_nop 0
	global_load_lds_dwordx4 v[192:193], off
	s_waitcnt vmcnt(8)
	s_waitcnt lgkmcnt(0)
	s_barrier
	s_waitcnt lgkmcnt(0)
	v_mfma_f32_16x16x32_bf16 v[176:179], v[64:67], v[152:155], 0
	v_mfma_f32_16x16x32_bf16 v[176:179], v[72:75], v[156:159], v[176:179]
	v_mfma_f32_16x16x32_bf16 v[172:175], v[88:91], v[152:155], 0
	v_mfma_f32_16x16x32_bf16 v[172:175], v[96:99], v[156:159], v[172:175]
	v_mfma_f32_16x16x32_bf16 v[136:139], v[64:67], v[160:163], 0
	v_mfma_f32_16x16x32_bf16 v[136:139], v[72:75], v[164:167], v[136:139]
	v_mfma_f32_16x16x32_bf16 v[132:135], v[88:91], v[160:163], 0
	v_mfma_f32_16x16x32_bf16 v[132:135], v[96:99], v[164:167], v[132:135]
	v_mfma_f32_16x16x32_bf16 v[112:115], v[64:67], v[168:171], 0
	v_mfma_f32_16x16x32_bf16 v[112:115], v[72:75], v[180:183], v[112:115]
	v_mfma_f32_16x16x32_bf16 v[104:107], v[88:91], v[168:171], 0
	v_mfma_f32_16x16x32_bf16 v[104:107], v[96:99], v[180:183], v[104:107]
	v_mfma_f32_16x16x32_bf16 v[84:87], v[64:67], v[184:187], 0
	v_mfma_f32_16x16x32_bf16 v[84:87], v[72:75], v[188:191], v[84:87]
	v_mfma_f32_16x16x32_bf16 v[80:83], v[88:91], v[184:187], 0
	v_mfma_f32_16x16x32_bf16 v[80:83], v[96:99], v[188:191], v[80:83]
	v_mfma_f32_16x16x32_bf16 v[148:151], v[108:111], v[152:155], 0
	v_mfma_f32_16x16x32_bf16 v[148:151], v[116:119], v[156:159], v[148:151]
	v_mfma_f32_16x16x32_bf16 v[144:147], v[128:131], v[152:155], 0
	v_mfma_f32_16x16x32_bf16 v[144:147], v[140:143], v[156:159], v[144:147]
	v_mfma_f32_16x16x32_bf16 v[124:127], v[108:111], v[160:163], 0
	v_mfma_f32_16x16x32_bf16 v[124:127], v[116:119], v[164:167], v[124:127]
	v_mfma_f32_16x16x32_bf16 v[120:123], v[128:131], v[160:163], 0
	v_mfma_f32_16x16x32_bf16 v[120:123], v[140:143], v[164:167], v[120:123]
	v_mfma_f32_16x16x32_bf16 v[100:103], v[108:111], v[168:171], 0
	v_mfma_f32_16x16x32_bf16 v[100:103], v[116:119], v[180:183], v[100:103]
	v_mfma_f32_16x16x32_bf16 v[92:95], v[128:131], v[168:171], 0
	v_mfma_f32_16x16x32_bf16 v[92:95], v[140:143], v[180:183], v[92:95]
	v_mfma_f32_16x16x32_bf16 v[76:79], v[108:111], v[184:187], 0
	v_mfma_f32_16x16x32_bf16 v[76:79], v[116:119], v[188:191], v[76:79]
	v_mfma_f32_16x16x32_bf16 v[68:71], v[128:131], v[184:187], 0
	v_mfma_f32_16x16x32_bf16 v[68:71], v[140:143], v[188:191], v[68:71]
	s_barrier
	s_add_i32 s74, s75, s2
	v_lshl_add_u64 v[192:193], s[90:91], 0, v[216:217]
	s_mov_b32 m0, s74
	ds_read_b128 v[152:155], v240 offset:16384
	ds_read_b128 v[156:159], v240 offset:17408
	ds_read_b128 v[160:163], v240 offset:18432
	ds_read_b128 v[164:167], v240 offset:19456
	ds_read_b128 v[168:171], v240 offset:20480
	ds_read_b128 v[180:183], v240 offset:21504
	ds_read_b128 v[184:187], v240 offset:22528
	ds_read_b128 v[188:191], v240 offset:23552
	global_load_lds_dwordx4 v[192:193], off
	s_add_i32 m0, s74, 0x2000
	s_add_u32 s74, s90, 0x80000
	v_lshl_add_u64 v[194:195], s[90:91], 0, v[228:229]
	s_addc_u32 s75, s91, 0
	s_add_i32 s67, s67, s2
	global_load_lds_dwordx4 v[194:195], off
	v_lshl_add_u64 v[196:197], s[74:75], 0, v[216:217]
	s_mov_b32 m0, s67
	v_lshl_add_u64 v[198:199], s[92:93], 0, v[226:227]
	global_load_lds_dwordx4 v[196:197], off
	v_lshl_add_u64 v[196:197], s[74:75], 0, v[228:229]
	s_add_i32 m0, s67, 0x2000
	s_nop 0
	global_load_lds_dwordx4 v[196:197], off
	v_lshl_add_u64 v[196:197], s[92:93], 0, v[224:225]
	s_mov_b32 m0, s28
	s_nop 0
	global_load_lds_dwordx4 v[196:197], off
	s_mov_b32 m0, s29
	s_nop 0
	global_load_lds_dwordx4 v[198:199], off
	s_waitcnt vmcnt(8)
	s_waitcnt lgkmcnt(0)
	s_barrier
	s_waitcnt lgkmcnt(0)
	v_mfma_f32_16x16x32_bf16 v[60:63], v[64:67], v[152:155], 0
	v_mfma_f32_16x16x32_bf16 v[60:63], v[72:75], v[156:159], v[60:63]
	v_mfma_f32_16x16x32_bf16 v[56:59], v[88:91], v[152:155], 0
	v_mfma_f32_16x16x32_bf16 v[56:59], v[96:99], v[156:159], v[56:59]
	v_mfma_f32_16x16x32_bf16 v[44:47], v[64:67], v[160:163], 0
	v_mfma_f32_16x16x32_bf16 v[44:47], v[72:75], v[164:167], v[44:47]
	v_mfma_f32_16x16x32_bf16 v[40:43], v[88:91], v[160:163], 0
	v_mfma_f32_16x16x32_bf16 v[40:43], v[96:99], v[164:167], v[40:43]
	v_mfma_f32_16x16x32_bf16 v[28:31], v[64:67], v[168:171], 0
	v_mfma_f32_16x16x32_bf16 v[28:31], v[72:75], v[180:183], v[28:31]
	v_mfma_f32_16x16x32_bf16 v[24:27], v[88:91], v[168:171], 0
	v_mfma_f32_16x16x32_bf16 v[24:27], v[96:99], v[180:183], v[24:27]
	v_mfma_f32_16x16x32_bf16 v[12:15], v[64:67], v[184:187], 0
	v_mfma_f32_16x16x32_bf16 v[12:15], v[72:75], v[188:191], v[12:15]
	v_mfma_f32_16x16x32_bf16 v[8:11], v[88:91], v[184:187], 0
	v_mfma_f32_16x16x32_bf16 v[8:11], v[96:99], v[188:191], v[8:11]
	v_mfma_f32_16x16x32_bf16 v[52:55], v[108:111], v[152:155], 0
	v_mfma_f32_16x16x32_bf16 v[52:55], v[116:119], v[156:159], v[52:55]
	v_mfma_f32_16x16x32_bf16 v[48:51], v[128:131], v[152:155], 0
	v_mfma_f32_16x16x32_bf16 v[48:51], v[140:143], v[156:159], v[48:51]
	v_mfma_f32_16x16x32_bf16 v[36:39], v[108:111], v[160:163], 0
	v_mfma_f32_16x16x32_bf16 v[36:39], v[116:119], v[164:167], v[36:39]
	v_mfma_f32_16x16x32_bf16 v[32:35], v[128:131], v[160:163], 0
	v_mfma_f32_16x16x32_bf16 v[32:35], v[140:143], v[164:167], v[32:35]
	v_mfma_f32_16x16x32_bf16 v[20:23], v[108:111], v[168:171], 0
	v_mfma_f32_16x16x32_bf16 v[20:23], v[116:119], v[180:183], v[20:23]
	v_mfma_f32_16x16x32_bf16 v[16:19], v[128:131], v[168:171], 0
	v_mfma_f32_16x16x32_bf16 v[16:19], v[140:143], v[180:183], v[16:19]
	v_mfma_f32_16x16x32_bf16 v[4:7], v[108:111], v[184:187], 0
	v_mfma_f32_16x16x32_bf16 v[4:7], v[116:119], v[188:191], v[4:7]
	v_mfma_f32_16x16x32_bf16 v[0:3], v[128:131], v[184:187], 0
	v_mfma_f32_16x16x32_bf16 v[0:3], v[140:143], v[188:191], v[0:3]
	s_barrier
	s_add_i32 s67, 0, 0x18000
	s_add_i32 s3, 0, 0x1c000
	v_add_u32_e32 v96, s67, v238
	v_add_u32_e32 v140, s3, v238
	ds_read_b128 v[64:67], v96
	ds_read_b128 v[72:75], v96 offset:1024
	ds_read_b128 v[88:91], v96 offset:2048
	ds_read_b128 v[96:99], v96 offset:3072
	ds_read_b128 v[108:111], v140
	ds_read_b128 v[116:119], v140 offset:1024
	ds_read_b128 v[128:131], v140 offset:2048
	ds_read_b128 v[140:143], v140 offset:3072
	s_add_u32 s74, s92, 0x80000
	s_addc_u32 s75, s93, 0
	s_mov_b32 m0, s34
	v_lshl_add_u64 v[200:201], s[74:75], 0, v[224:225]
	ds_read_b128 v[152:155], v240 offset:32768
	ds_read_b128 v[156:159], v240 offset:33792
	ds_read_b128 v[160:163], v240 offset:34816
	ds_read_b128 v[164:167], v240 offset:35840
	ds_read_b128 v[168:171], v240 offset:36864
	ds_read_b128 v[180:183], v240 offset:37888
	ds_read_b128 v[184:187], v240 offset:38912
	ds_read_b128 v[188:191], v240 offset:39936
	global_load_lds_dwordx4 v[200:201], off
	v_lshl_add_u64 v[200:201], s[74:75], 0, v[226:227]
	s_mov_b32 m0, s35
	s_nop 0
	global_load_lds_dwordx4 v[200:201], off
	s_waitcnt vmcnt(8)
	s_waitcnt lgkmcnt(0)
	s_barrier
	s_waitcnt lgkmcnt(0)
	v_mfma_f32_16x16x32_bf16 v[176:179], v[64:67], v[152:155], v[176:179]
	v_mfma_f32_16x16x32_bf16 v[176:179], v[72:75], v[156:159], v[176:179]
	v_mfma_f32_16x16x32_bf16 v[172:175], v[88:91], v[152:155], v[172:175]
	v_mfma_f32_16x16x32_bf16 v[172:175], v[96:99], v[156:159], v[172:175]
	v_mfma_f32_16x16x32_bf16 v[136:139], v[64:67], v[160:163], v[136:139]
	v_mfma_f32_16x16x32_bf16 v[136:139], v[72:75], v[164:167], v[136:139]
	v_mfma_f32_16x16x32_bf16 v[132:135], v[88:91], v[160:163], v[132:135]
	v_mfma_f32_16x16x32_bf16 v[132:135], v[96:99], v[164:167], v[132:135]
	v_mfma_f32_16x16x32_bf16 v[112:115], v[64:67], v[168:171], v[112:115]
	v_mfma_f32_16x16x32_bf16 v[112:115], v[72:75], v[180:183], v[112:115]
	v_mfma_f32_16x16x32_bf16 v[104:107], v[88:91], v[168:171], v[104:107]
	v_mfma_f32_16x16x32_bf16 v[104:107], v[96:99], v[180:183], v[104:107]
	v_mfma_f32_16x16x32_bf16 v[84:87], v[64:67], v[184:187], v[84:87]
	v_mfma_f32_16x16x32_bf16 v[84:87], v[72:75], v[188:191], v[84:87]
	v_mfma_f32_16x16x32_bf16 v[80:83], v[88:91], v[184:187], v[80:83]
	v_mfma_f32_16x16x32_bf16 v[80:83], v[96:99], v[188:191], v[80:83]
	v_mfma_f32_16x16x32_bf16 v[148:151], v[108:111], v[152:155], v[148:151]
	v_mfma_f32_16x16x32_bf16 v[148:151], v[116:119], v[156:159], v[148:151]
	v_mfma_f32_16x16x32_bf16 v[144:147], v[128:131], v[152:155], v[144:147]
	v_mfma_f32_16x16x32_bf16 v[144:147], v[140:143], v[156:159], v[144:147]
	v_mfma_f32_16x16x32_bf16 v[124:127], v[108:111], v[160:163], v[124:127]
	v_mfma_f32_16x16x32_bf16 v[124:127], v[116:119], v[164:167], v[124:127]
	v_mfma_f32_16x16x32_bf16 v[120:123], v[128:131], v[160:163], v[120:123]
	v_mfma_f32_16x16x32_bf16 v[120:123], v[140:143], v[164:167], v[120:123]
	v_mfma_f32_16x16x32_bf16 v[100:103], v[108:111], v[168:171], v[100:103]
	v_mfma_f32_16x16x32_bf16 v[100:103], v[116:119], v[180:183], v[100:103]
	v_mfma_f32_16x16x32_bf16 v[92:95], v[128:131], v[168:171], v[92:95]
	v_mfma_f32_16x16x32_bf16 v[92:95], v[140:143], v[180:183], v[92:95]
	v_mfma_f32_16x16x32_bf16 v[76:79], v[108:111], v[184:187], v[76:79]
	v_mfma_f32_16x16x32_bf16 v[76:79], v[116:119], v[188:191], v[76:79]
	v_mfma_f32_16x16x32_bf16 v[68:71], v[128:131], v[184:187], v[68:71]
	v_mfma_f32_16x16x32_bf16 v[68:71], v[140:143], v[188:191], v[68:71]
	s_barrier
	s_add_i32 s67, s67, s2
	v_lshl_add_u64 v[192:193], v[192:193], 0, s[30:31]
	s_mov_b32 m0, s67
	ds_read_b128 v[152:155], v240 offset:49152
	ds_read_b128 v[156:159], v240 offset:50176
	ds_read_b128 v[160:163], v240 offset:51200
	ds_read_b128 v[164:167], v240 offset:52224
	ds_read_b128 v[168:171], v240 offset:53248
	ds_read_b128 v[180:183], v240 offset:54272
	ds_read_b128 v[184:187], v240 offset:55296
	ds_read_b128 v[188:191], v240 offset:56320
	global_load_lds_dwordx4 v[192:193], off
	s_add_i32 m0, s67, 0x2000
	s_add_u32 s74, s90, 0x80080
	v_lshl_add_u64 v[192:193], v[194:195], 0, s[30:31]
	s_addc_u32 s75, s91, 0
	s_add_i32 s3, s3, s2
	global_load_lds_dwordx4 v[192:193], off
	v_lshl_add_u64 v[192:193], s[74:75], 0, v[216:217]
	s_mov_b32 m0, s3
	s_nop 0
	global_load_lds_dwordx4 v[192:193], off
	v_lshl_add_u64 v[192:193], s[74:75], 0, v[228:229]
	s_add_i32 m0, s3, 0x2000
	s_nop 0
	global_load_lds_dwordx4 v[192:193], off
	v_lshl_add_u64 v[192:193], v[196:197], 0, s[30:31]
	s_mov_b32 m0, s60
	s_nop 0
	global_load_lds_dwordx4 v[192:193], off
	v_lshl_add_u64 v[192:193], v[198:199], 0, s[30:31]
	s_mov_b32 m0, s61
	s_nop 0
	global_load_lds_dwordx4 v[192:193], off
	s_waitcnt vmcnt(8)
	s_waitcnt lgkmcnt(0)
	s_barrier
	s_waitcnt lgkmcnt(0)
	v_mfma_f32_16x16x32_bf16 v[60:63], v[64:67], v[152:155], v[60:63]
	v_mfma_f32_16x16x32_bf16 v[60:63], v[72:75], v[156:159], v[60:63]
	v_mfma_f32_16x16x32_bf16 v[56:59], v[88:91], v[152:155], v[56:59]
	v_mfma_f32_16x16x32_bf16 v[56:59], v[96:99], v[156:159], v[56:59]
	v_mfma_f32_16x16x32_bf16 v[44:47], v[64:67], v[160:163], v[44:47]
	v_mfma_f32_16x16x32_bf16 v[44:47], v[72:75], v[164:167], v[44:47]
	v_mfma_f32_16x16x32_bf16 v[40:43], v[88:91], v[160:163], v[40:43]
	v_mfma_f32_16x16x32_bf16 v[40:43], v[96:99], v[164:167], v[40:43]
	v_mfma_f32_16x16x32_bf16 v[28:31], v[64:67], v[168:171], v[28:31]
	v_mfma_f32_16x16x32_bf16 v[28:31], v[72:75], v[180:183], v[28:31]
	v_mfma_f32_16x16x32_bf16 v[24:27], v[88:91], v[168:171], v[24:27]
	v_mfma_f32_16x16x32_bf16 v[24:27], v[96:99], v[180:183], v[24:27]
	v_mfma_f32_16x16x32_bf16 v[12:15], v[64:67], v[184:187], v[12:15]
	v_mfma_f32_16x16x32_bf16 v[12:15], v[72:75], v[188:191], v[12:15]
	v_mfma_f32_16x16x32_bf16 v[8:11], v[88:91], v[184:187], v[8:11]
	v_mfma_f32_16x16x32_bf16 v[8:11], v[96:99], v[188:191], v[8:11]
	v_mfma_f32_16x16x32_bf16 v[52:55], v[108:111], v[152:155], v[52:55]
	v_mfma_f32_16x16x32_bf16 v[52:55], v[116:119], v[156:159], v[52:55]
	v_mfma_f32_16x16x32_bf16 v[48:51], v[128:131], v[152:155], v[48:51]
	v_mfma_f32_16x16x32_bf16 v[48:51], v[140:143], v[156:159], v[48:51]
	v_mfma_f32_16x16x32_bf16 v[36:39], v[108:111], v[160:163], v[36:39]
	v_mfma_f32_16x16x32_bf16 v[36:39], v[116:119], v[164:167], v[36:39]
	v_mfma_f32_16x16x32_bf16 v[32:35], v[128:131], v[160:163], v[32:35]
	v_mfma_f32_16x16x32_bf16 v[32:35], v[140:143], v[164:167], v[32:35]
	v_mfma_f32_16x16x32_bf16 v[20:23], v[108:111], v[168:171], v[20:23]
	v_mfma_f32_16x16x32_bf16 v[20:23], v[116:119], v[180:183], v[20:23]
	v_mfma_f32_16x16x32_bf16 v[16:19], v[128:131], v[168:171], v[16:19]
	v_mfma_f32_16x16x32_bf16 v[16:19], v[140:143], v[180:183], v[16:19]
	v_mfma_f32_16x16x32_bf16 v[4:7], v[108:111], v[184:187], v[4:7]
	v_mfma_f32_16x16x32_bf16 v[4:7], v[116:119], v[188:191], v[4:7]
	v_mfma_f32_16x16x32_bf16 v[0:3], v[128:131], v[184:187], v[0:3]
	v_mfma_f32_16x16x32_bf16 v[0:3], v[140:143], v[188:191], v[0:3]
	s_barrier
	s_add_i32 s71, s71, 2
	s_add_u32 s88, s88, 0x100
	s_addc_u32 s89, s89, 0
	s_add_u32 s87, s87, 0x100
	s_addc_u32 vcc_hi, vcc_hi, 0
.LBB0_965:
	s_add_u32 s67, s88, 0xfff80080
	s_addc_u32 s74, s89, -1
	s_add_i32 s75, 0, 0x10000
	s_cmp_eq_u32 s71, 28
	s_cselect_b32 s93, s79, s74
	s_cselect_b32 s92, s96, s67
	s_cselect_b32 s91, s77, vcc_hi
	s_cselect_b32 s90, vcc_lo, s87
	s_add_i32 s67, 0, 0x14000
	v_add_u32_e32 v96, s75, v238
	v_add_u32_e32 v140, s67, v238
	ds_read_b128 v[64:67], v96
	ds_read_b128 v[72:75], v96 offset:1024
	ds_read_b128 v[88:91], v96 offset:2048
	ds_read_b128 v[96:99], v96 offset:3072
	ds_read_b128 v[108:111], v140
	ds_read_b128 v[116:119], v140 offset:1024
	ds_read_b128 v[128:131], v140 offset:2048
	ds_read_b128 v[140:143], v140 offset:3072
	v_lshl_add_u64 v[192:193], s[88:89], 0, v[230:231]
	s_add_i32 m0, s28, 0xc000
	ds_read_b128 v[152:155], v240
	ds_read_b128 v[156:159], v240 offset:1024
	ds_read_b128 v[160:163], v240 offset:2048
	ds_read_b128 v[164:167], v240 offset:3072
	ds_read_b128 v[168:171], v240 offset:4096
	ds_read_b128 v[180:183], v240 offset:5120
	ds_read_b128 v[184:187], v240 offset:6144
	ds_read_b128 v[188:191], v240 offset:7168
	global_load_lds_dwordx4 v[192:193], off
	v_lshl_add_u64 v[192:193], s[88:89], 0, v[232:233]
	s_add_i32 m0, s28, 0xe000
	s_nop 0
	global_load_lds_dwordx4 v[192:193], off
	s_waitcnt vmcnt(8)
	s_waitcnt lgkmcnt(0)
	s_barrier
	s_waitcnt lgkmcnt(0)
	v_mfma_f32_16x16x32_bf16 v[176:179], v[64:67], v[152:155], v[176:179]
	v_mfma_f32_16x16x32_bf16 v[176:179], v[72:75], v[156:159], v[176:179]
	v_mfma_f32_16x16x32_bf16 v[172:175], v[88:91], v[152:155], v[172:175]
	v_mfma_f32_16x16x32_bf16 v[172:175], v[96:99], v[156:159], v[172:175]
	v_mfma_f32_16x16x32_bf16 v[136:139], v[64:67], v[160:163], v[136:139]
	v_mfma_f32_16x16x32_bf16 v[136:139], v[72:75], v[164:167], v[136:139]
	v_mfma_f32_16x16x32_bf16 v[132:135], v[88:91], v[160:163], v[132:135]
	v_mfma_f32_16x16x32_bf16 v[132:135], v[96:99], v[164:167], v[132:135]
	v_mfma_f32_16x16x32_bf16 v[112:115], v[64:67], v[168:171], v[112:115]
	v_mfma_f32_16x16x32_bf16 v[112:115], v[72:75], v[180:183], v[112:115]
	v_mfma_f32_16x16x32_bf16 v[104:107], v[88:91], v[168:171], v[104:107]
	v_mfma_f32_16x16x32_bf16 v[104:107], v[96:99], v[180:183], v[104:107]
	v_mfma_f32_16x16x32_bf16 v[84:87], v[64:67], v[184:187], v[84:87]
	v_mfma_f32_16x16x32_bf16 v[84:87], v[72:75], v[188:191], v[84:87]
	v_mfma_f32_16x16x32_bf16 v[80:83], v[88:91], v[184:187], v[80:83]
	v_mfma_f32_16x16x32_bf16 v[80:83], v[96:99], v[188:191], v[80:83]
	v_mfma_f32_16x16x32_bf16 v[148:151], v[108:111], v[152:155], v[148:151]
	v_mfma_f32_16x16x32_bf16 v[148:151], v[116:119], v[156:159], v[148:151]
	v_mfma_f32_16x16x32_bf16 v[144:147], v[128:131], v[152:155], v[144:147]
	v_mfma_f32_16x16x32_bf16 v[144:147], v[140:143], v[156:159], v[144:147]
	v_mfma_f32_16x16x32_bf16 v[124:127], v[108:111], v[160:163], v[124:127]
	v_mfma_f32_16x16x32_bf16 v[124:127], v[116:119], v[164:167], v[124:127]
	v_mfma_f32_16x16x32_bf16 v[120:123], v[128:131], v[160:163], v[120:123]
	v_mfma_f32_16x16x32_bf16 v[120:123], v[140:143], v[164:167], v[120:123]
	v_mfma_f32_16x16x32_bf16 v[100:103], v[108:111], v[168:171], v[100:103]
	v_mfma_f32_16x16x32_bf16 v[100:103], v[116:119], v[180:183], v[100:103]
	v_mfma_f32_16x16x32_bf16 v[92:95], v[128:131], v[168:171], v[92:95]
	v_mfma_f32_16x16x32_bf16 v[92:95], v[140:143], v[180:183], v[92:95]
	v_mfma_f32_16x16x32_bf16 v[76:79], v[108:111], v[184:187], v[76:79]
	v_mfma_f32_16x16x32_bf16 v[76:79], v[116:119], v[188:191], v[76:79]
	v_mfma_f32_16x16x32_bf16 v[68:71], v[128:131], v[184:187], v[68:71]
	v_mfma_f32_16x16x32_bf16 v[68:71], v[140:143], v[188:191], v[68:71]
	s_barrier
	s_add_i32 s74, s75, s2
	v_lshl_add_u64 v[192:193], s[90:91], 0, v[216:217]
	s_mov_b32 m0, s74
	ds_read_b128 v[152:155], v240 offset:16384
	ds_read_b128 v[156:159], v240 offset:17408
	ds_read_b128 v[160:163], v240 offset:18432
	ds_read_b128 v[164:167], v240 offset:19456
	ds_read_b128 v[168:171], v240 offset:20480
	ds_read_b128 v[180:183], v240 offset:21504
	ds_read_b128 v[184:187], v240 offset:22528
	ds_read_b128 v[188:191], v240 offset:23552
	global_load_lds_dwordx4 v[192:193], off
	s_add_i32 m0, s74, 0x2000
	s_add_u32 s74, s90, 0x80000
	v_lshl_add_u64 v[194:195], s[90:91], 0, v[228:229]
	s_addc_u32 s75, s91, 0
	s_add_i32 s67, s67, s2
	global_load_lds_dwordx4 v[194:195], off
	v_lshl_add_u64 v[196:197], s[74:75], 0, v[216:217]
	s_mov_b32 m0, s67
	v_lshl_add_u64 v[198:199], s[92:93], 0, v[226:227]
	global_load_lds_dwordx4 v[196:197], off
	v_lshl_add_u64 v[196:197], s[74:75], 0, v[228:229]
	s_add_i32 m0, s67, 0x2000
	s_nop 0
	global_load_lds_dwordx4 v[196:197], off
	v_lshl_add_u64 v[196:197], s[92:93], 0, v[224:225]
	s_mov_b32 m0, s28
	s_nop 0
	global_load_lds_dwordx4 v[196:197], off
	s_mov_b32 m0, s29
	s_nop 0
	global_load_lds_dwordx4 v[198:199], off
	s_waitcnt vmcnt(8)
	s_waitcnt lgkmcnt(0)
	s_barrier
	s_waitcnt lgkmcnt(0)
	v_mfma_f32_16x16x32_bf16 v[60:63], v[64:67], v[152:155], v[60:63]
	v_mfma_f32_16x16x32_bf16 v[60:63], v[72:75], v[156:159], v[60:63]
	v_mfma_f32_16x16x32_bf16 v[56:59], v[88:91], v[152:155], v[56:59]
	v_mfma_f32_16x16x32_bf16 v[56:59], v[96:99], v[156:159], v[56:59]
	v_mfma_f32_16x16x32_bf16 v[44:47], v[64:67], v[160:163], v[44:47]
	v_mfma_f32_16x16x32_bf16 v[44:47], v[72:75], v[164:167], v[44:47]
	v_mfma_f32_16x16x32_bf16 v[40:43], v[88:91], v[160:163], v[40:43]
	v_mfma_f32_16x16x32_bf16 v[40:43], v[96:99], v[164:167], v[40:43]
	v_mfma_f32_16x16x32_bf16 v[28:31], v[64:67], v[168:171], v[28:31]
	v_mfma_f32_16x16x32_bf16 v[28:31], v[72:75], v[180:183], v[28:31]
	v_mfma_f32_16x16x32_bf16 v[24:27], v[88:91], v[168:171], v[24:27]
	v_mfma_f32_16x16x32_bf16 v[24:27], v[96:99], v[180:183], v[24:27]
	v_mfma_f32_16x16x32_bf16 v[12:15], v[64:67], v[184:187], v[12:15]
	v_mfma_f32_16x16x32_bf16 v[12:15], v[72:75], v[188:191], v[12:15]
	v_mfma_f32_16x16x32_bf16 v[8:11], v[88:91], v[184:187], v[8:11]
	v_mfma_f32_16x16x32_bf16 v[8:11], v[96:99], v[188:191], v[8:11]
	v_mfma_f32_16x16x32_bf16 v[52:55], v[108:111], v[152:155], v[52:55]
	v_mfma_f32_16x16x32_bf16 v[52:55], v[116:119], v[156:159], v[52:55]
	v_mfma_f32_16x16x32_bf16 v[48:51], v[128:131], v[152:155], v[48:51]
	v_mfma_f32_16x16x32_bf16 v[48:51], v[140:143], v[156:159], v[48:51]
	v_mfma_f32_16x16x32_bf16 v[36:39], v[108:111], v[160:163], v[36:39]
	v_mfma_f32_16x16x32_bf16 v[36:39], v[116:119], v[164:167], v[36:39]
	v_mfma_f32_16x16x32_bf16 v[32:35], v[128:131], v[160:163], v[32:35]
	v_mfma_f32_16x16x32_bf16 v[32:35], v[140:143], v[164:167], v[32:35]
	v_mfma_f32_16x16x32_bf16 v[20:23], v[108:111], v[168:171], v[20:23]
	v_mfma_f32_16x16x32_bf16 v[20:23], v[116:119], v[180:183], v[20:23]
	v_mfma_f32_16x16x32_bf16 v[16:19], v[128:131], v[168:171], v[16:19]
	v_mfma_f32_16x16x32_bf16 v[16:19], v[140:143], v[180:183], v[16:19]
	v_mfma_f32_16x16x32_bf16 v[4:7], v[108:111], v[184:187], v[4:7]
	v_mfma_f32_16x16x32_bf16 v[4:7], v[116:119], v[188:191], v[4:7]
	v_mfma_f32_16x16x32_bf16 v[0:3], v[128:131], v[184:187], v[0:3]
	v_mfma_f32_16x16x32_bf16 v[0:3], v[140:143], v[188:191], v[0:3]
	s_barrier
	s_add_i32 s67, 0, 0x18000
	s_add_i32 s3, 0, 0x1c000
	v_add_u32_e32 v96, s67, v238
	v_add_u32_e32 v140, s3, v238
	ds_read_b128 v[64:67], v96
	ds_read_b128 v[72:75], v96 offset:1024
	ds_read_b128 v[88:91], v96 offset:2048
	ds_read_b128 v[96:99], v96 offset:3072
	ds_read_b128 v[108:111], v140
	ds_read_b128 v[116:119], v140 offset:1024
	ds_read_b128 v[128:131], v140 offset:2048
	ds_read_b128 v[140:143], v140 offset:3072
	s_add_u32 s74, s92, 0x80000
	s_addc_u32 s75, s93, 0
	s_mov_b32 m0, s34
	v_lshl_add_u64 v[200:201], s[74:75], 0, v[224:225]
	ds_read_b128 v[152:155], v240 offset:32768
	ds_read_b128 v[156:159], v240 offset:33792
	ds_read_b128 v[160:163], v240 offset:34816
	ds_read_b128 v[164:167], v240 offset:35840
	ds_read_b128 v[168:171], v240 offset:36864
	ds_read_b128 v[180:183], v240 offset:37888
	ds_read_b128 v[184:187], v240 offset:38912
	ds_read_b128 v[188:191], v240 offset:39936
	global_load_lds_dwordx4 v[200:201], off
	v_lshl_add_u64 v[200:201], s[74:75], 0, v[226:227]
	s_mov_b32 m0, s35
	s_nop 0
	global_load_lds_dwordx4 v[200:201], off
	s_waitcnt vmcnt(8)
	s_waitcnt lgkmcnt(0)
	s_barrier
	s_waitcnt lgkmcnt(0)
	v_mfma_f32_16x16x32_bf16 v[176:179], v[64:67], v[152:155], v[176:179]
	v_mfma_f32_16x16x32_bf16 v[176:179], v[72:75], v[156:159], v[176:179]
	v_mfma_f32_16x16x32_bf16 v[172:175], v[88:91], v[152:155], v[172:175]
	v_mfma_f32_16x16x32_bf16 v[172:175], v[96:99], v[156:159], v[172:175]
	v_mfma_f32_16x16x32_bf16 v[136:139], v[64:67], v[160:163], v[136:139]
	v_mfma_f32_16x16x32_bf16 v[136:139], v[72:75], v[164:167], v[136:139]
	v_mfma_f32_16x16x32_bf16 v[132:135], v[88:91], v[160:163], v[132:135]
	v_mfma_f32_16x16x32_bf16 v[132:135], v[96:99], v[164:167], v[132:135]
	v_mfma_f32_16x16x32_bf16 v[112:115], v[64:67], v[168:171], v[112:115]
	v_mfma_f32_16x16x32_bf16 v[112:115], v[72:75], v[180:183], v[112:115]
	v_mfma_f32_16x16x32_bf16 v[104:107], v[88:91], v[168:171], v[104:107]
	v_mfma_f32_16x16x32_bf16 v[104:107], v[96:99], v[180:183], v[104:107]
	v_mfma_f32_16x16x32_bf16 v[84:87], v[64:67], v[184:187], v[84:87]
	v_mfma_f32_16x16x32_bf16 v[84:87], v[72:75], v[188:191], v[84:87]
	v_mfma_f32_16x16x32_bf16 v[80:83], v[88:91], v[184:187], v[80:83]
	v_mfma_f32_16x16x32_bf16 v[80:83], v[96:99], v[188:191], v[80:83]
	v_mfma_f32_16x16x32_bf16 v[148:151], v[108:111], v[152:155], v[148:151]
	v_mfma_f32_16x16x32_bf16 v[148:151], v[116:119], v[156:159], v[148:151]
	v_mfma_f32_16x16x32_bf16 v[144:147], v[128:131], v[152:155], v[144:147]
	v_mfma_f32_16x16x32_bf16 v[144:147], v[140:143], v[156:159], v[144:147]
	v_mfma_f32_16x16x32_bf16 v[124:127], v[108:111], v[160:163], v[124:127]
	v_mfma_f32_16x16x32_bf16 v[124:127], v[116:119], v[164:167], v[124:127]
	v_mfma_f32_16x16x32_bf16 v[120:123], v[128:131], v[160:163], v[120:123]
	v_mfma_f32_16x16x32_bf16 v[120:123], v[140:143], v[164:167], v[120:123]
	v_mfma_f32_16x16x32_bf16 v[100:103], v[108:111], v[168:171], v[100:103]
	v_mfma_f32_16x16x32_bf16 v[100:103], v[116:119], v[180:183], v[100:103]
	v_mfma_f32_16x16x32_bf16 v[92:95], v[128:131], v[168:171], v[92:95]
	v_mfma_f32_16x16x32_bf16 v[92:95], v[140:143], v[180:183], v[92:95]
	v_mfma_f32_16x16x32_bf16 v[76:79], v[108:111], v[184:187], v[76:79]
	v_mfma_f32_16x16x32_bf16 v[76:79], v[116:119], v[188:191], v[76:79]
	v_mfma_f32_16x16x32_bf16 v[68:71], v[128:131], v[184:187], v[68:71]
	v_mfma_f32_16x16x32_bf16 v[68:71], v[140:143], v[188:191], v[68:71]
	s_barrier
	s_add_i32 s67, s67, s2
	v_lshl_add_u64 v[192:193], v[192:193], 0, s[30:31]
	s_mov_b32 m0, s67
	ds_read_b128 v[152:155], v240 offset:49152
	ds_read_b128 v[156:159], v240 offset:50176
	ds_read_b128 v[160:163], v240 offset:51200
	ds_read_b128 v[164:167], v240 offset:52224
	ds_read_b128 v[168:171], v240 offset:53248
	ds_read_b128 v[180:183], v240 offset:54272
	ds_read_b128 v[184:187], v240 offset:55296
	ds_read_b128 v[188:191], v240 offset:56320
	global_load_lds_dwordx4 v[192:193], off
	s_add_i32 m0, s67, 0x2000
	s_add_u32 s74, s90, 0x80080
	v_lshl_add_u64 v[192:193], v[194:195], 0, s[30:31]
	s_addc_u32 s75, s91, 0
	s_add_i32 s3, s3, s2
	global_load_lds_dwordx4 v[192:193], off
	v_lshl_add_u64 v[192:193], s[74:75], 0, v[216:217]
	s_mov_b32 m0, s3
	s_nop 0
	global_load_lds_dwordx4 v[192:193], off
	v_lshl_add_u64 v[192:193], s[74:75], 0, v[228:229]
	s_add_i32 m0, s3, 0x2000
	s_nop 0
	global_load_lds_dwordx4 v[192:193], off
	v_lshl_add_u64 v[192:193], v[196:197], 0, s[30:31]
	s_mov_b32 m0, s60
	s_nop 0
	global_load_lds_dwordx4 v[192:193], off
	v_lshl_add_u64 v[192:193], v[198:199], 0, s[30:31]
	s_mov_b32 m0, s61
	s_nop 0
	global_load_lds_dwordx4 v[192:193], off
	s_waitcnt vmcnt(8)
	s_waitcnt lgkmcnt(0)
	s_barrier
	s_waitcnt lgkmcnt(0)
	v_mfma_f32_16x16x32_bf16 v[60:63], v[64:67], v[152:155], v[60:63]
	v_mfma_f32_16x16x32_bf16 v[60:63], v[72:75], v[156:159], v[60:63]
	v_mfma_f32_16x16x32_bf16 v[56:59], v[88:91], v[152:155], v[56:59]
	v_mfma_f32_16x16x32_bf16 v[56:59], v[96:99], v[156:159], v[56:59]
	v_mfma_f32_16x16x32_bf16 v[44:47], v[64:67], v[160:163], v[44:47]
	v_mfma_f32_16x16x32_bf16 v[44:47], v[72:75], v[164:167], v[44:47]
	v_mfma_f32_16x16x32_bf16 v[40:43], v[88:91], v[160:163], v[40:43]
	v_mfma_f32_16x16x32_bf16 v[40:43], v[96:99], v[164:167], v[40:43]
	v_mfma_f32_16x16x32_bf16 v[28:31], v[64:67], v[168:171], v[28:31]
	v_mfma_f32_16x16x32_bf16 v[28:31], v[72:75], v[180:183], v[28:31]
	v_mfma_f32_16x16x32_bf16 v[24:27], v[88:91], v[168:171], v[24:27]
	v_mfma_f32_16x16x32_bf16 v[24:27], v[96:99], v[180:183], v[24:27]
	v_mfma_f32_16x16x32_bf16 v[12:15], v[64:67], v[184:187], v[12:15]
	v_mfma_f32_16x16x32_bf16 v[12:15], v[72:75], v[188:191], v[12:15]
	v_mfma_f32_16x16x32_bf16 v[8:11], v[88:91], v[184:187], v[8:11]
	v_mfma_f32_16x16x32_bf16 v[8:11], v[96:99], v[188:191], v[8:11]
	v_mfma_f32_16x16x32_bf16 v[52:55], v[108:111], v[152:155], v[52:55]
	v_mfma_f32_16x16x32_bf16 v[52:55], v[116:119], v[156:159], v[52:55]
	v_mfma_f32_16x16x32_bf16 v[48:51], v[128:131], v[152:155], v[48:51]
	v_mfma_f32_16x16x32_bf16 v[48:51], v[140:143], v[156:159], v[48:51]
	v_mfma_f32_16x16x32_bf16 v[36:39], v[108:111], v[160:163], v[36:39]
	v_mfma_f32_16x16x32_bf16 v[36:39], v[116:119], v[164:167], v[36:39]
	v_mfma_f32_16x16x32_bf16 v[32:35], v[128:131], v[160:163], v[32:35]
	v_mfma_f32_16x16x32_bf16 v[32:35], v[140:143], v[164:167], v[32:35]
	v_mfma_f32_16x16x32_bf16 v[20:23], v[108:111], v[168:171], v[20:23]
	v_mfma_f32_16x16x32_bf16 v[20:23], v[116:119], v[180:183], v[20:23]
	v_mfma_f32_16x16x32_bf16 v[16:19], v[128:131], v[168:171], v[16:19]
	v_mfma_f32_16x16x32_bf16 v[16:19], v[140:143], v[180:183], v[16:19]
	v_mfma_f32_16x16x32_bf16 v[4:7], v[108:111], v[184:187], v[4:7]
	v_mfma_f32_16x16x32_bf16 v[4:7], v[116:119], v[188:191], v[4:7]
	v_mfma_f32_16x16x32_bf16 v[0:3], v[128:131], v[184:187], v[0:3]
	v_mfma_f32_16x16x32_bf16 v[0:3], v[140:143], v[188:191], v[0:3]
	s_barrier
	s_add_i32 s71, s71, 2
	s_add_u32 s88, s88, 0x100
	s_addc_u32 s89, s89, 0
	s_add_u32 s87, s87, 0x100
	s_addc_u32 vcc_hi, vcc_hi, 0
	s_cmp_gt_u32 s71, 29
	s_cbranch_scc0 .LBB0_965
	s_and_b64 vcc, exec, s[22:23]
	s_cbranch_vccz .LBB0_968
	s_barrier

.LBB0_1189:
	s_ashr_i32 s75, s74, 31
	s_lshl_b64 s[72:73], s[74:75], 20
	s_add_u32 s76, s2, s72
	s_addc_u32 s77, s3, s73
	s_and_b64 s[72:73], s[4:5], exec
	s_cselect_b32 s71, s77, s83
	s_cselect_b32 s72, s76, s82
	s_ashr_i32 s23, s22, 31
	s_lshl_b64 s[78:79], s[22:23], 20
	s_add_u32 s78, s14, s78
	s_addc_u32 s79, s15, s79
	s_and_b64 s[86:87], s[4:5], exec
	s_cselect_b32 s23, s79, s85
	s_cselect_b32 s73, s78, s84
	s_add_u32 s82, s82, 0x80080
	s_addc_u32 s83, s83, 0
	s_add_u32 s75, s84, 0x100
	s_addc_u32 s81, s85, 0
	s_mov_b32 s88, -2
	s_add_u32 s67, s82, 0xfff80080
	s_addc_u32 s84, s83, -1
	s_add_i32 s89, 0, 0x10000
	s_cmp_eq_u32 s88, 28
	s_cselect_b32 s87, s71, s84
	s_cselect_b32 s86, s72, s67
	s_cselect_b32 s85, s23, s81
	s_cselect_b32 s84, s73, s75
	s_add_i32 s67, 0, 0x14000
	v_add_u32_e32 v76, s89, v192
	v_add_u32_e32 v156, s67, v192
	ds_read_b128 v[64:67], v76
	ds_read_b128 v[68:71], v76 offset:1024
	ds_read_b128 v[72:75], v76 offset:2048
	ds_read_b128 v[76:79], v76 offset:3072
	ds_read_b128 v[80:83], v156
	ds_read_b128 v[116:119], v156 offset:1024
	ds_read_b128 v[152:155], v156 offset:2048
	ds_read_b128 v[156:159], v156 offset:3072
	v_lshl_add_u64 v[190:191], s[82:83], 0, v[186:187]
	s_add_i32 m0, s28, 0xc000
	ds_read_b128 v[160:163], v193
	ds_read_b128 v[164:167], v193 offset:1024
	ds_read_b128 v[168:171], v193 offset:2048
	ds_read_b128 v[172:175], v193 offset:3072
	ds_read_b128 v[194:197], v193 offset:4096
	ds_read_b128 v[198:201], v193 offset:5120
	ds_read_b128 v[202:205], v193 offset:6144
	ds_read_b128 v[206:209], v193 offset:7168
	global_load_lds_dwordx4 v[190:191], off
	v_lshl_add_u64 v[190:191], s[82:83], 0, v[188:189]
	s_add_i32 m0, s28, 0xe000
	s_nop 0
	global_load_lds_dwordx4 v[190:191], off
	s_waitcnt vmcnt(8)
	s_waitcnt lgkmcnt(0)
	s_barrier
	s_waitcnt lgkmcnt(0)
	v_mfma_f32_16x16x32_bf16 v[148:151], v[64:67], v[160:163], 0
	v_mfma_f32_16x16x32_bf16 v[148:151], v[68:71], v[164:167], v[148:151]
	v_mfma_f32_16x16x32_bf16 v[144:147], v[72:75], v[160:163], 0
	v_mfma_f32_16x16x32_bf16 v[144:147], v[76:79], v[164:167], v[144:147]
	v_mfma_f32_16x16x32_bf16 v[132:135], v[64:67], v[168:171], 0
	v_mfma_f32_16x16x32_bf16 v[132:135], v[68:71], v[172:175], v[132:135]
	v_mfma_f32_16x16x32_bf16 v[128:131], v[72:75], v[168:171], 0
	v_mfma_f32_16x16x32_bf16 v[128:131], v[76:79], v[172:175], v[128:131]
	v_mfma_f32_16x16x32_bf16 v[112:115], v[64:67], v[194:197], 0
	v_mfma_f32_16x16x32_bf16 v[112:115], v[68:71], v[198:201], v[112:115]
	v_mfma_f32_16x16x32_bf16 v[108:111], v[72:75], v[194:197], 0
	v_mfma_f32_16x16x32_bf16 v[108:111], v[76:79], v[198:201], v[108:111]
	v_mfma_f32_16x16x32_bf16 v[96:99], v[64:67], v[202:205], 0
	v_mfma_f32_16x16x32_bf16 v[96:99], v[68:71], v[206:209], v[96:99]
	v_mfma_f32_16x16x32_bf16 v[92:95], v[72:75], v[202:205], 0
	v_mfma_f32_16x16x32_bf16 v[92:95], v[76:79], v[206:209], v[92:95]
	v_mfma_f32_16x16x32_bf16 v[140:143], v[80:83], v[160:163], 0
	v_mfma_f32_16x16x32_bf16 v[140:143], v[116:119], v[164:167], v[140:143]
	v_mfma_f32_16x16x32_bf16 v[136:139], v[152:155], v[160:163], 0
	v_mfma_f32_16x16x32_bf16 v[136:139], v[156:159], v[164:167], v[136:139]
	v_mfma_f32_16x16x32_bf16 v[124:127], v[80:83], v[168:171], 0
	v_mfma_f32_16x16x32_bf16 v[124:127], v[116:119], v[172:175], v[124:127]
	v_mfma_f32_16x16x32_bf16 v[120:123], v[152:155], v[168:171], 0
	v_mfma_f32_16x16x32_bf16 v[120:123], v[156:159], v[172:175], v[120:123]
	v_mfma_f32_16x16x32_bf16 v[104:107], v[80:83], v[194:197], 0
	v_mfma_f32_16x16x32_bf16 v[104:107], v[116:119], v[198:201], v[104:107]
	v_mfma_f32_16x16x32_bf16 v[100:103], v[152:155], v[194:197], 0
	v_mfma_f32_16x16x32_bf16 v[100:103], v[156:159], v[198:201], v[100:103]
	v_mfma_f32_16x16x32_bf16 v[88:91], v[80:83], v[202:205], 0
	v_mfma_f32_16x16x32_bf16 v[88:91], v[116:119], v[206:209], v[88:91]
	v_mfma_f32_16x16x32_bf16 v[84:87], v[152:155], v[202:205], 0
	v_mfma_f32_16x16x32_bf16 v[84:87], v[156:159], v[206:209], v[84:87]
	s_barrier
	s_add_i32 s89, s89, s24
	v_lshl_add_u64 v[190:191], s[84:85], 0, v[180:181]
	s_mov_b32 m0, s89
	ds_read_b128 v[160:163], v193 offset:16384
	ds_read_b128 v[164:167], v193 offset:17408
	ds_read_b128 v[168:171], v193 offset:18432
	ds_read_b128 v[172:175], v193 offset:19456
	ds_read_b128 v[194:197], v193 offset:20480
	ds_read_b128 v[198:201], v193 offset:21504
	ds_read_b128 v[202:205], v193 offset:22528
	ds_read_b128 v[206:209], v193 offset:23552
	global_load_lds_dwordx4 v[190:191], off
	s_add_i32 m0, s89, 0x2000
	s_add_u32 s90, s84, 0x80000
	v_lshl_add_u64 v[210:211], s[84:85], 0, v[176:177]
	s_addc_u32 s91, s85, 0
	s_add_i32 s67, s67, s24
	global_load_lds_dwordx4 v[210:211], off
	v_lshl_add_u64 v[212:213], s[90:91], 0, v[180:181]
	s_mov_b32 m0, s67
	v_lshl_add_u64 v[214:215], s[86:87], 0, v[178:179]
	global_load_lds_dwordx4 v[212:213], off
	v_lshl_add_u64 v[212:213], s[90:91], 0, v[176:177]
	s_add_i32 m0, s67, 0x2000
	s_nop 0
	global_load_lds_dwordx4 v[212:213], off
	v_lshl_add_u64 v[212:213], s[86:87], 0, v[182:183]
	s_mov_b32 m0, s28
	s_nop 0
	global_load_lds_dwordx4 v[212:213], off
	s_mov_b32 m0, s29
	s_nop 0
	global_load_lds_dwordx4 v[214:215], off
	s_waitcnt vmcnt(8)
	s_waitcnt lgkmcnt(0)
	s_barrier
	s_waitcnt lgkmcnt(0)
	v_mfma_f32_16x16x32_bf16 v[60:63], v[64:67], v[160:163], 0
	v_mfma_f32_16x16x32_bf16 v[60:63], v[68:71], v[164:167], v[60:63]
	v_mfma_f32_16x16x32_bf16 v[56:59], v[72:75], v[160:163], 0
	v_mfma_f32_16x16x32_bf16 v[56:59], v[76:79], v[164:167], v[56:59]
	v_mfma_f32_16x16x32_bf16 v[44:47], v[64:67], v[168:171], 0
	v_mfma_f32_16x16x32_bf16 v[44:47], v[68:71], v[172:175], v[44:47]
	v_mfma_f32_16x16x32_bf16 v[40:43], v[72:75], v[168:171], 0
	v_mfma_f32_16x16x32_bf16 v[40:43], v[76:79], v[172:175], v[40:43]
	v_mfma_f32_16x16x32_bf16 v[28:31], v[64:67], v[194:197], 0
	v_mfma_f32_16x16x32_bf16 v[28:31], v[68:71], v[198:201], v[28:31]
	v_mfma_f32_16x16x32_bf16 v[24:27], v[72:75], v[194:197], 0
	v_mfma_f32_16x16x32_bf16 v[24:27], v[76:79], v[198:201], v[24:27]
	v_mfma_f32_16x16x32_bf16 v[12:15], v[64:67], v[202:205], 0
	v_mfma_f32_16x16x32_bf16 v[12:15], v[68:71], v[206:209], v[12:15]
	v_mfma_f32_16x16x32_bf16 v[8:11], v[72:75], v[202:205], 0
	v_mfma_f32_16x16x32_bf16 v[8:11], v[76:79], v[206:209], v[8:11]
	v_mfma_f32_16x16x32_bf16 v[52:55], v[80:83], v[160:163], 0
	v_mfma_f32_16x16x32_bf16 v[52:55], v[116:119], v[164:167], v[52:55]
	v_mfma_f32_16x16x32_bf16 v[48:51], v[152:155], v[160:163], 0
	v_mfma_f32_16x16x32_bf16 v[48:51], v[156:159], v[164:167], v[48:51]
	v_mfma_f32_16x16x32_bf16 v[36:39], v[80:83], v[168:171], 0
	v_mfma_f32_16x16x32_bf16 v[36:39], v[116:119], v[172:175], v[36:39]
	v_mfma_f32_16x16x32_bf16 v[32:35], v[152:155], v[168:171], 0
	v_mfma_f32_16x16x32_bf16 v[32:35], v[156:159], v[172:175], v[32:35]
	v_mfma_f32_16x16x32_bf16 v[20:23], v[80:83], v[194:197], 0
	v_mfma_f32_16x16x32_bf16 v[20:23], v[116:119], v[198:201], v[20:23]
	v_mfma_f32_16x16x32_bf16 v[16:19], v[152:155], v[194:197], 0
	v_mfma_f32_16x16x32_bf16 v[16:19], v[156:159], v[198:201], v[16:19]
	v_mfma_f32_16x16x32_bf16 v[4:7], v[80:83], v[202:205], 0
	v_mfma_f32_16x16x32_bf16 v[4:7], v[116:119], v[206:209], v[4:7]
	v_mfma_f32_16x16x32_bf16 v[0:3], v[152:155], v[202:205], 0
	v_mfma_f32_16x16x32_bf16 v[0:3], v[156:159], v[206:209], v[0:3]
	s_barrier
	s_add_i32 s67, 0, 0x18000
	s_add_i32 s89, 0, 0x1c000
	v_add_u32_e32 v76, s67, v192
	v_add_u32_e32 v156, s89, v192
	ds_read_b128 v[64:67], v76
	ds_read_b128 v[68:71], v76 offset:1024
	ds_read_b128 v[72:75], v76 offset:2048
	ds_read_b128 v[76:79], v76 offset:3072
	ds_read_b128 v[80:83], v156
	ds_read_b128 v[116:119], v156 offset:1024
	ds_read_b128 v[152:155], v156 offset:2048
	ds_read_b128 v[156:159], v156 offset:3072
	s_add_u32 s86, s86, 0x80000
	s_addc_u32 s87, s87, 0
	s_mov_b32 m0, s34
	v_lshl_add_u64 v[218:219], s[86:87], 0, v[182:183]
	ds_read_b128 v[160:163], v193 offset:32768
	ds_read_b128 v[164:167], v193 offset:33792
	ds_read_b128 v[168:171], v193 offset:34816
	ds_read_b128 v[172:175], v193 offset:35840
	ds_read_b128 v[194:197], v193 offset:36864
	ds_read_b128 v[198:201], v193 offset:37888
	ds_read_b128 v[202:205], v193 offset:38912
	ds_read_b128 v[206:209], v193 offset:39936
	global_load_lds_dwordx4 v[218:219], off
	v_lshl_add_u64 v[218:219], s[86:87], 0, v[178:179]
	s_mov_b32 m0, s35
	s_nop 0
	global_load_lds_dwordx4 v[218:219], off
	s_waitcnt vmcnt(8)
	s_waitcnt lgkmcnt(0)
	s_barrier
	s_waitcnt lgkmcnt(0)
	v_mfma_f32_16x16x32_bf16 v[148:151], v[64:67], v[160:163], v[148:151]
	v_mfma_f32_16x16x32_bf16 v[148:151], v[68:71], v[164:167], v[148:151]
	v_mfma_f32_16x16x32_bf16 v[144:147], v[72:75], v[160:163], v[144:147]
	v_mfma_f32_16x16x32_bf16 v[144:147], v[76:79], v[164:167], v[144:147]
	v_mfma_f32_16x16x32_bf16 v[132:135], v[64:67], v[168:171], v[132:135]
	v_mfma_f32_16x16x32_bf16 v[132:135], v[68:71], v[172:175], v[132:135]
	v_mfma_f32_16x16x32_bf16 v[128:131], v[72:75], v[168:171], v[128:131]
	v_mfma_f32_16x16x32_bf16 v[128:131], v[76:79], v[172:175], v[128:131]
	v_mfma_f32_16x16x32_bf16 v[112:115], v[64:67], v[194:197], v[112:115]
	v_mfma_f32_16x16x32_bf16 v[112:115], v[68:71], v[198:201], v[112:115]
	v_mfma_f32_16x16x32_bf16 v[108:111], v[72:75], v[194:197], v[108:111]
	v_mfma_f32_16x16x32_bf16 v[108:111], v[76:79], v[198:201], v[108:111]
	v_mfma_f32_16x16x32_bf16 v[96:99], v[64:67], v[202:205], v[96:99]
	v_mfma_f32_16x16x32_bf16 v[96:99], v[68:71], v[206:209], v[96:99]
	v_mfma_f32_16x16x32_bf16 v[92:95], v[72:75], v[202:205], v[92:95]
	v_mfma_f32_16x16x32_bf16 v[92:95], v[76:79], v[206:209], v[92:95]
	v_mfma_f32_16x16x32_bf16 v[140:143], v[80:83], v[160:163], v[140:143]
	v_mfma_f32_16x16x32_bf16 v[140:143], v[116:119], v[164:167], v[140:143]
	v_mfma_f32_16x16x32_bf16 v[136:139], v[152:155], v[160:163], v[136:139]
	v_mfma_f32_16x16x32_bf16 v[136:139], v[156:159], v[164:167], v[136:139]
	v_mfma_f32_16x16x32_bf16 v[124:127], v[80:83], v[168:171], v[124:127]
	v_mfma_f32_16x16x32_bf16 v[124:127], v[116:119], v[172:175], v[124:127]
	v_mfma_f32_16x16x32_bf16 v[120:123], v[152:155], v[168:171], v[120:123]
	v_mfma_f32_16x16x32_bf16 v[120:123], v[156:159], v[172:175], v[120:123]
	v_mfma_f32_16x16x32_bf16 v[104:107], v[80:83], v[194:197], v[104:107]
	v_mfma_f32_16x16x32_bf16 v[104:107], v[116:119], v[198:201], v[104:107]
	v_mfma_f32_16x16x32_bf16 v[100:103], v[152:155], v[194:197], v[100:103]
	v_mfma_f32_16x16x32_bf16 v[100:103], v[156:159], v[198:201], v[100:103]
	v_mfma_f32_16x16x32_bf16 v[88:91], v[80:83], v[202:205], v[88:91]
	v_mfma_f32_16x16x32_bf16 v[88:91], v[116:119], v[206:209], v[88:91]
	v_mfma_f32_16x16x32_bf16 v[84:87], v[152:155], v[202:205], v[84:87]
	v_mfma_f32_16x16x32_bf16 v[84:87], v[156:159], v[206:209], v[84:87]
	s_barrier
	s_add_i32 s67, s67, s24
	v_lshl_add_u64 v[190:191], v[190:191], 0, s[30:31]
	s_mov_b32 m0, s67
	ds_read_b128 v[160:163], v193 offset:49152
	ds_read_b128 v[164:167], v193 offset:50176
	ds_read_b128 v[168:171], v193 offset:51200
	ds_read_b128 v[172:175], v193 offset:52224
	ds_read_b128 v[194:197], v193 offset:53248
	ds_read_b128 v[198:201], v193 offset:54272
	ds_read_b128 v[202:205], v193 offset:55296
	ds_read_b128 v[206:209], v193 offset:56320
	global_load_lds_dwordx4 v[190:191], off
	s_add_i32 m0, s67, 0x2000
	s_add_u32 s84, s84, 0x80080
	v_lshl_add_u64 v[190:191], v[210:211], 0, s[30:31]
	s_addc_u32 s85, s85, 0
	s_add_i32 s67, s89, s24
	global_load_lds_dwordx4 v[190:191], off
	v_lshl_add_u64 v[190:191], s[84:85], 0, v[180:181]
	s_mov_b32 m0, s67
	s_nop 0
	global_load_lds_dwordx4 v[190:191], off
	v_lshl_add_u64 v[190:191], s[84:85], 0, v[176:177]
	s_add_i32 m0, s67, 0x2000
	s_nop 0
	global_load_lds_dwordx4 v[190:191], off
	v_lshl_add_u64 v[190:191], v[212:213], 0, s[30:31]
	s_mov_b32 m0, s53
	s_nop 0
	global_load_lds_dwordx4 v[190:191], off
	v_lshl_add_u64 v[190:191], v[214:215], 0, s[30:31]
	s_mov_b32 m0, s54
	s_nop 0
	global_load_lds_dwordx4 v[190:191], off
	s_waitcnt vmcnt(8)
	s_waitcnt lgkmcnt(0)
	s_barrier
	s_waitcnt lgkmcnt(0)
	v_mfma_f32_16x16x32_bf16 v[60:63], v[64:67], v[160:163], v[60:63]
	v_mfma_f32_16x16x32_bf16 v[60:63], v[68:71], v[164:167], v[60:63]
	v_mfma_f32_16x16x32_bf16 v[56:59], v[72:75], v[160:163], v[56:59]
	v_mfma_f32_16x16x32_bf16 v[56:59], v[76:79], v[164:167], v[56:59]
	v_mfma_f32_16x16x32_bf16 v[44:47], v[64:67], v[168:171], v[44:47]
	v_mfma_f32_16x16x32_bf16 v[44:47], v[68:71], v[172:175], v[44:47]
	v_mfma_f32_16x16x32_bf16 v[40:43], v[72:75], v[168:171], v[40:43]
	v_mfma_f32_16x16x32_bf16 v[40:43], v[76:79], v[172:175], v[40:43]
	v_mfma_f32_16x16x32_bf16 v[28:31], v[64:67], v[194:197], v[28:31]
	v_mfma_f32_16x16x32_bf16 v[28:31], v[68:71], v[198:201], v[28:31]
	v_mfma_f32_16x16x32_bf16 v[24:27], v[72:75], v[194:197], v[24:27]
	v_mfma_f32_16x16x32_bf16 v[24:27], v[76:79], v[198:201], v[24:27]
	v_mfma_f32_16x16x32_bf16 v[12:15], v[64:67], v[202:205], v[12:15]
	v_mfma_f32_16x16x32_bf16 v[12:15], v[68:71], v[206:209], v[12:15]
	v_mfma_f32_16x16x32_bf16 v[8:11], v[72:75], v[202:205], v[8:11]
	v_mfma_f32_16x16x32_bf16 v[8:11], v[76:79], v[206:209], v[8:11]
	v_mfma_f32_16x16x32_bf16 v[52:55], v[80:83], v[160:163], v[52:55]
	v_mfma_f32_16x16x32_bf16 v[52:55], v[116:119], v[164:167], v[52:55]
	v_mfma_f32_16x16x32_bf16 v[48:51], v[152:155], v[160:163], v[48:51]
	v_mfma_f32_16x16x32_bf16 v[48:51], v[156:159], v[164:167], v[48:51]
	v_mfma_f32_16x16x32_bf16 v[36:39], v[80:83], v[168:171], v[36:39]
	v_mfma_f32_16x16x32_bf16 v[36:39], v[116:119], v[172:175], v[36:39]
	v_mfma_f32_16x16x32_bf16 v[32:35], v[152:155], v[168:171], v[32:35]
	v_mfma_f32_16x16x32_bf16 v[32:35], v[156:159], v[172:175], v[32:35]
	v_mfma_f32_16x16x32_bf16 v[20:23], v[80:83], v[194:197], v[20:23]
	v_mfma_f32_16x16x32_bf16 v[20:23], v[116:119], v[198:201], v[20:23]
	v_mfma_f32_16x16x32_bf16 v[16:19], v[152:155], v[194:197], v[16:19]
	v_mfma_f32_16x16x32_bf16 v[16:19], v[156:159], v[198:201], v[16:19]
	v_mfma_f32_16x16x32_bf16 v[4:7], v[80:83], v[202:205], v[4:7]
	v_mfma_f32_16x16x32_bf16 v[4:7], v[116:119], v[206:209], v[4:7]
	v_mfma_f32_16x16x32_bf16 v[0:3], v[152:155], v[202:205], v[0:3]
	v_mfma_f32_16x16x32_bf16 v[0:3], v[156:159], v[206:209], v[0:3]
	s_barrier
	s_add_i32 s88, s88, 2
	s_add_u32 s82, s82, 0x100
	s_addc_u32 s83, s83, 0
	s_add_u32 s75, s75, 0x100
	s_addc_u32 s81, s81, 0
.LBB0_1190:
	s_add_u32 s67, s82, 0xfff80080
	s_addc_u32 s84, s83, -1
	s_add_i32 s89, 0, 0x10000
	s_cmp_eq_u32 s88, 28
	s_cselect_b32 s87, s71, s84
	s_cselect_b32 s86, s72, s67
	s_cselect_b32 s85, s23, s81
	s_cselect_b32 s84, s73, s75
	s_add_i32 s67, 0, 0x14000
	v_add_u32_e32 v76, s89, v192
	v_add_u32_e32 v156, s67, v192
	ds_read_b128 v[64:67], v76
	ds_read_b128 v[68:71], v76 offset:1024
	ds_read_b128 v[72:75], v76 offset:2048
	ds_read_b128 v[76:79], v76 offset:3072
	ds_read_b128 v[80:83], v156
	ds_read_b128 v[116:119], v156 offset:1024
	ds_read_b128 v[152:155], v156 offset:2048
	ds_read_b128 v[156:159], v156 offset:3072
	v_lshl_add_u64 v[190:191], s[82:83], 0, v[186:187]
	s_add_i32 m0, s28, 0xc000
	ds_read_b128 v[160:163], v193
	ds_read_b128 v[164:167], v193 offset:1024
	ds_read_b128 v[168:171], v193 offset:2048
	ds_read_b128 v[172:175], v193 offset:3072
	ds_read_b128 v[194:197], v193 offset:4096
	ds_read_b128 v[198:201], v193 offset:5120
	ds_read_b128 v[202:205], v193 offset:6144
	ds_read_b128 v[206:209], v193 offset:7168
	global_load_lds_dwordx4 v[190:191], off
	v_lshl_add_u64 v[190:191], s[82:83], 0, v[188:189]
	s_add_i32 m0, s28, 0xe000
	s_nop 0
	global_load_lds_dwordx4 v[190:191], off
	s_waitcnt vmcnt(8)
	s_waitcnt lgkmcnt(0)
	s_barrier
	s_waitcnt lgkmcnt(0)
	v_mfma_f32_16x16x32_bf16 v[148:151], v[64:67], v[160:163], v[148:151]
	v_mfma_f32_16x16x32_bf16 v[148:151], v[68:71], v[164:167], v[148:151]
	v_mfma_f32_16x16x32_bf16 v[144:147], v[72:75], v[160:163], v[144:147]
	v_mfma_f32_16x16x32_bf16 v[144:147], v[76:79], v[164:167], v[144:147]
	v_mfma_f32_16x16x32_bf16 v[132:135], v[64:67], v[168:171], v[132:135]
	v_mfma_f32_16x16x32_bf16 v[132:135], v[68:71], v[172:175], v[132:135]
	v_mfma_f32_16x16x32_bf16 v[128:131], v[72:75], v[168:171], v[128:131]
	v_mfma_f32_16x16x32_bf16 v[128:131], v[76:79], v[172:175], v[128:131]
	v_mfma_f32_16x16x32_bf16 v[112:115], v[64:67], v[194:197], v[112:115]
	v_mfma_f32_16x16x32_bf16 v[112:115], v[68:71], v[198:201], v[112:115]
	v_mfma_f32_16x16x32_bf16 v[108:111], v[72:75], v[194:197], v[108:111]
	v_mfma_f32_16x16x32_bf16 v[108:111], v[76:79], v[198:201], v[108:111]
	v_mfma_f32_16x16x32_bf16 v[96:99], v[64:67], v[202:205], v[96:99]
	v_mfma_f32_16x16x32_bf16 v[96:99], v[68:71], v[206:209], v[96:99]
	v_mfma_f32_16x16x32_bf16 v[92:95], v[72:75], v[202:205], v[92:95]
	v_mfma_f32_16x16x32_bf16 v[92:95], v[76:79], v[206:209], v[92:95]
	v_mfma_f32_16x16x32_bf16 v[140:143], v[80:83], v[160:163], v[140:143]
	v_mfma_f32_16x16x32_bf16 v[140:143], v[116:119], v[164:167], v[140:143]
	v_mfma_f32_16x16x32_bf16 v[136:139], v[152:155], v[160:163], v[136:139]
	v_mfma_f32_16x16x32_bf16 v[136:139], v[156:159], v[164:167], v[136:139]
	v_mfma_f32_16x16x32_bf16 v[124:127], v[80:83], v[168:171], v[124:127]
	v_mfma_f32_16x16x32_bf16 v[124:127], v[116:119], v[172:175], v[124:127]
	v_mfma_f32_16x16x32_bf16 v[120:123], v[152:155], v[168:171], v[120:123]
	v_mfma_f32_16x16x32_bf16 v[120:123], v[156:159], v[172:175], v[120:123]
	v_mfma_f32_16x16x32_bf16 v[104:107], v[80:83], v[194:197], v[104:107]
	v_mfma_f32_16x16x32_bf16 v[104:107], v[116:119], v[198:201], v[104:107]
	v_mfma_f32_16x16x32_bf16 v[100:103], v[152:155], v[194:197], v[100:103]
	v_mfma_f32_16x16x32_bf16 v[100:103], v[156:159], v[198:201], v[100:103]
	v_mfma_f32_16x16x32_bf16 v[88:91], v[80:83], v[202:205], v[88:91]
	v_mfma_f32_16x16x32_bf16 v[88:91], v[116:119], v[206:209], v[88:91]
	v_mfma_f32_16x16x32_bf16 v[84:87], v[152:155], v[202:205], v[84:87]
	v_mfma_f32_16x16x32_bf16 v[84:87], v[156:159], v[206:209], v[84:87]
	s_barrier
	s_add_i32 s89, s89, s24
	v_lshl_add_u64 v[190:191], s[84:85], 0, v[180:181]
	s_mov_b32 m0, s89
	ds_read_b128 v[160:163], v193 offset:16384
	ds_read_b128 v[164:167], v193 offset:17408
	ds_read_b128 v[168:171], v193 offset:18432
	ds_read_b128 v[172:175], v193 offset:19456
	ds_read_b128 v[194:197], v193 offset:20480
	ds_read_b128 v[198:201], v193 offset:21504
	ds_read_b128 v[202:205], v193 offset:22528
	ds_read_b128 v[206:209], v193 offset:23552
	global_load_lds_dwordx4 v[190:191], off
	s_add_i32 m0, s89, 0x2000
	s_add_u32 s90, s84, 0x80000
	v_lshl_add_u64 v[210:211], s[84:85], 0, v[176:177]
	s_addc_u32 s91, s85, 0
	s_add_i32 s67, s67, s24
	global_load_lds_dwordx4 v[210:211], off
	v_lshl_add_u64 v[212:213], s[90:91], 0, v[180:181]
	s_mov_b32 m0, s67
	v_lshl_add_u64 v[214:215], s[86:87], 0, v[178:179]
	global_load_lds_dwordx4 v[212:213], off
	v_lshl_add_u64 v[212:213], s[90:91], 0, v[176:177]
	s_add_i32 m0, s67, 0x2000
	s_nop 0
	global_load_lds_dwordx4 v[212:213], off
	v_lshl_add_u64 v[212:213], s[86:87], 0, v[182:183]
	s_mov_b32 m0, s28
	s_nop 0
	global_load_lds_dwordx4 v[212:213], off
	s_mov_b32 m0, s29
	s_nop 0
	global_load_lds_dwordx4 v[214:215], off
	s_waitcnt vmcnt(8)
	s_waitcnt lgkmcnt(0)
	s_barrier
	s_waitcnt lgkmcnt(0)
	v_mfma_f32_16x16x32_bf16 v[60:63], v[64:67], v[160:163], v[60:63]
	v_mfma_f32_16x16x32_bf16 v[60:63], v[68:71], v[164:167], v[60:63]
	v_mfma_f32_16x16x32_bf16 v[56:59], v[72:75], v[160:163], v[56:59]
	v_mfma_f32_16x16x32_bf16 v[56:59], v[76:79], v[164:167], v[56:59]
	v_mfma_f32_16x16x32_bf16 v[44:47], v[64:67], v[168:171], v[44:47]
	v_mfma_f32_16x16x32_bf16 v[44:47], v[68:71], v[172:175], v[44:47]
	v_mfma_f32_16x16x32_bf16 v[40:43], v[72:75], v[168:171], v[40:43]
	v_mfma_f32_16x16x32_bf16 v[40:43], v[76:79], v[172:175], v[40:43]
	v_mfma_f32_16x16x32_bf16 v[28:31], v[64:67], v[194:197], v[28:31]
	v_mfma_f32_16x16x32_bf16 v[28:31], v[68:71], v[198:201], v[28:31]
	v_mfma_f32_16x16x32_bf16 v[24:27], v[72:75], v[194:197], v[24:27]
	v_mfma_f32_16x16x32_bf16 v[24:27], v[76:79], v[198:201], v[24:27]
	v_mfma_f32_16x16x32_bf16 v[12:15], v[64:67], v[202:205], v[12:15]
	v_mfma_f32_16x16x32_bf16 v[12:15], v[68:71], v[206:209], v[12:15]
	v_mfma_f32_16x16x32_bf16 v[8:11], v[72:75], v[202:205], v[8:11]
	v_mfma_f32_16x16x32_bf16 v[8:11], v[76:79], v[206:209], v[8:11]
	v_mfma_f32_16x16x32_bf16 v[52:55], v[80:83], v[160:163], v[52:55]
	v_mfma_f32_16x16x32_bf16 v[52:55], v[116:119], v[164:167], v[52:55]
	v_mfma_f32_16x16x32_bf16 v[48:51], v[152:155], v[160:163], v[48:51]
	v_mfma_f32_16x16x32_bf16 v[48:51], v[156:159], v[164:167], v[48:51]
	v_mfma_f32_16x16x32_bf16 v[36:39], v[80:83], v[168:171], v[36:39]
	v_mfma_f32_16x16x32_bf16 v[36:39], v[116:119], v[172:175], v[36:39]
	v_mfma_f32_16x16x32_bf16 v[32:35], v[152:155], v[168:171], v[32:35]
	v_mfma_f32_16x16x32_bf16 v[32:35], v[156:159], v[172:175], v[32:35]
	v_mfma_f32_16x16x32_bf16 v[20:23], v[80:83], v[194:197], v[20:23]
	v_mfma_f32_16x16x32_bf16 v[20:23], v[116:119], v[198:201], v[20:23]
	v_mfma_f32_16x16x32_bf16 v[16:19], v[152:155], v[194:197], v[16:19]
	v_mfma_f32_16x16x32_bf16 v[16:19], v[156:159], v[198:201], v[16:19]
	v_mfma_f32_16x16x32_bf16 v[4:7], v[80:83], v[202:205], v[4:7]
	v_mfma_f32_16x16x32_bf16 v[4:7], v[116:119], v[206:209], v[4:7]
	v_mfma_f32_16x16x32_bf16 v[0:3], v[152:155], v[202:205], v[0:3]
	v_mfma_f32_16x16x32_bf16 v[0:3], v[156:159], v[206:209], v[0:3]
	s_barrier
	s_add_i32 s67, 0, 0x18000
	s_add_i32 s89, 0, 0x1c000
	v_add_u32_e32 v76, s67, v192
	v_add_u32_e32 v156, s89, v192
	ds_read_b128 v[64:67], v76
	ds_read_b128 v[68:71], v76 offset:1024
	ds_read_b128 v[72:75], v76 offset:2048
	ds_read_b128 v[76:79], v76 offset:3072
	ds_read_b128 v[80:83], v156
	ds_read_b128 v[116:119], v156 offset:1024
	ds_read_b128 v[152:155], v156 offset:2048
	ds_read_b128 v[156:159], v156 offset:3072
	s_add_u32 s86, s86, 0x80000
	s_addc_u32 s87, s87, 0
	s_mov_b32 m0, s34
	v_lshl_add_u64 v[218:219], s[86:87], 0, v[182:183]
	ds_read_b128 v[160:163], v193 offset:32768
	ds_read_b128 v[164:167], v193 offset:33792
	ds_read_b128 v[168:171], v193 offset:34816
	ds_read_b128 v[172:175], v193 offset:35840
	ds_read_b128 v[194:197], v193 offset:36864
	ds_read_b128 v[198:201], v193 offset:37888
	ds_read_b128 v[202:205], v193 offset:38912
	ds_read_b128 v[206:209], v193 offset:39936
	global_load_lds_dwordx4 v[218:219], off
	v_lshl_add_u64 v[218:219], s[86:87], 0, v[178:179]
	s_mov_b32 m0, s35
	s_nop 0
	global_load_lds_dwordx4 v[218:219], off
	s_waitcnt vmcnt(8)
	s_waitcnt lgkmcnt(0)
	s_barrier
	s_waitcnt lgkmcnt(0)
	v_mfma_f32_16x16x32_bf16 v[148:151], v[64:67], v[160:163], v[148:151]
	v_mfma_f32_16x16x32_bf16 v[148:151], v[68:71], v[164:167], v[148:151]
	v_mfma_f32_16x16x32_bf16 v[144:147], v[72:75], v[160:163], v[144:147]
	v_mfma_f32_16x16x32_bf16 v[144:147], v[76:79], v[164:167], v[144:147]
	v_mfma_f32_16x16x32_bf16 v[132:135], v[64:67], v[168:171], v[132:135]
	v_mfma_f32_16x16x32_bf16 v[132:135], v[68:71], v[172:175], v[132:135]
	v_mfma_f32_16x16x32_bf16 v[128:131], v[72:75], v[168:171], v[128:131]
	v_mfma_f32_16x16x32_bf16 v[128:131], v[76:79], v[172:175], v[128:131]
	v_mfma_f32_16x16x32_bf16 v[112:115], v[64:67], v[194:197], v[112:115]
	v_mfma_f32_16x16x32_bf16 v[112:115], v[68:71], v[198:201], v[112:115]
	v_mfma_f32_16x16x32_bf16 v[108:111], v[72:75], v[194:197], v[108:111]
	v_mfma_f32_16x16x32_bf16 v[108:111], v[76:79], v[198:201], v[108:111]
	v_mfma_f32_16x16x32_bf16 v[96:99], v[64:67], v[202:205], v[96:99]
	v_mfma_f32_16x16x32_bf16 v[96:99], v[68:71], v[206:209], v[96:99]
	v_mfma_f32_16x16x32_bf16 v[92:95], v[72:75], v[202:205], v[92:95]
	v_mfma_f32_16x16x32_bf16 v[92:95], v[76:79], v[206:209], v[92:95]
	v_mfma_f32_16x16x32_bf16 v[140:143], v[80:83], v[160:163], v[140:143]
	v_mfma_f32_16x16x32_bf16 v[140:143], v[116:119], v[164:167], v[140:143]
	v_mfma_f32_16x16x32_bf16 v[136:139], v[152:155], v[160:163], v[136:139]
	v_mfma_f32_16x16x32_bf16 v[136:139], v[156:159], v[164:167], v[136:139]
	v_mfma_f32_16x16x32_bf16 v[124:127], v[80:83], v[168:171], v[124:127]
	v_mfma_f32_16x16x32_bf16 v[124:127], v[116:119], v[172:175], v[124:127]
	v_mfma_f32_16x16x32_bf16 v[120:123], v[152:155], v[168:171], v[120:123]
	v_mfma_f32_16x16x32_bf16 v[120:123], v[156:159], v[172:175], v[120:123]
	v_mfma_f32_16x16x32_bf16 v[104:107], v[80:83], v[194:197], v[104:107]
	v_mfma_f32_16x16x32_bf16 v[104:107], v[116:119], v[198:201], v[104:107]
	v_mfma_f32_16x16x32_bf16 v[100:103], v[152:155], v[194:197], v[100:103]
	v_mfma_f32_16x16x32_bf16 v[100:103], v[156:159], v[198:201], v[100:103]
	v_mfma_f32_16x16x32_bf16 v[88:91], v[80:83], v[202:205], v[88:91]
	v_mfma_f32_16x16x32_bf16 v[88:91], v[116:119], v[206:209], v[88:91]
	v_mfma_f32_16x16x32_bf16 v[84:87], v[152:155], v[202:205], v[84:87]
	v_mfma_f32_16x16x32_bf16 v[84:87], v[156:159], v[206:209], v[84:87]
	s_barrier
	s_add_i32 s67, s67, s24
	v_lshl_add_u64 v[190:191], v[190:191], 0, s[30:31]
	s_mov_b32 m0, s67
	ds_read_b128 v[160:163], v193 offset:49152
	ds_read_b128 v[164:167], v193 offset:50176
	ds_read_b128 v[168:171], v193 offset:51200
	ds_read_b128 v[172:175], v193 offset:52224
	ds_read_b128 v[194:197], v193 offset:53248
	ds_read_b128 v[198:201], v193 offset:54272
	ds_read_b128 v[202:205], v193 offset:55296
	ds_read_b128 v[206:209], v193 offset:56320
	global_load_lds_dwordx4 v[190:191], off
	s_add_i32 m0, s67, 0x2000
	s_add_u32 s84, s84, 0x80080
	v_lshl_add_u64 v[190:191], v[210:211], 0, s[30:31]
	s_addc_u32 s85, s85, 0
	s_add_i32 s67, s89, s24
	global_load_lds_dwordx4 v[190:191], off
	v_lshl_add_u64 v[190:191], s[84:85], 0, v[180:181]
	s_mov_b32 m0, s67
	s_nop 0
	global_load_lds_dwordx4 v[190:191], off
	v_lshl_add_u64 v[190:191], s[84:85], 0, v[176:177]
	s_add_i32 m0, s67, 0x2000
	s_nop 0
	global_load_lds_dwordx4 v[190:191], off
	v_lshl_add_u64 v[190:191], v[212:213], 0, s[30:31]
	s_mov_b32 m0, s53
	s_nop 0
	global_load_lds_dwordx4 v[190:191], off
	v_lshl_add_u64 v[190:191], v[214:215], 0, s[30:31]
	s_mov_b32 m0, s54
	s_nop 0
	global_load_lds_dwordx4 v[190:191], off
	s_waitcnt vmcnt(8)
	s_waitcnt lgkmcnt(0)
	s_barrier
	s_waitcnt lgkmcnt(0)
	v_mfma_f32_16x16x32_bf16 v[60:63], v[64:67], v[160:163], v[60:63]
	v_mfma_f32_16x16x32_bf16 v[60:63], v[68:71], v[164:167], v[60:63]
	v_mfma_f32_16x16x32_bf16 v[56:59], v[72:75], v[160:163], v[56:59]
	v_mfma_f32_16x16x32_bf16 v[56:59], v[76:79], v[164:167], v[56:59]
	v_mfma_f32_16x16x32_bf16 v[44:47], v[64:67], v[168:171], v[44:47]
	v_mfma_f32_16x16x32_bf16 v[44:47], v[68:71], v[172:175], v[44:47]
	v_mfma_f32_16x16x32_bf16 v[40:43], v[72:75], v[168:171], v[40:43]
	v_mfma_f32_16x16x32_bf16 v[40:43], v[76:79], v[172:175], v[40:43]
	v_mfma_f32_16x16x32_bf16 v[28:31], v[64:67], v[194:197], v[28:31]
	v_mfma_f32_16x16x32_bf16 v[28:31], v[68:71], v[198:201], v[28:31]
	v_mfma_f32_16x16x32_bf16 v[24:27], v[72:75], v[194:197], v[24:27]
	v_mfma_f32_16x16x32_bf16 v[24:27], v[76:79], v[198:201], v[24:27]
	v_mfma_f32_16x16x32_bf16 v[12:15], v[64:67], v[202:205], v[12:15]
	v_mfma_f32_16x16x32_bf16 v[12:15], v[68:71], v[206:209], v[12:15]
	v_mfma_f32_16x16x32_bf16 v[8:11], v[72:75], v[202:205], v[8:11]
	v_mfma_f32_16x16x32_bf16 v[8:11], v[76:79], v[206:209], v[8:11]
	v_mfma_f32_16x16x32_bf16 v[52:55], v[80:83], v[160:163], v[52:55]
	v_mfma_f32_16x16x32_bf16 v[52:55], v[116:119], v[164:167], v[52:55]
	v_mfma_f32_16x16x32_bf16 v[48:51], v[152:155], v[160:163], v[48:51]
	v_mfma_f32_16x16x32_bf16 v[48:51], v[156:159], v[164:167], v[48:51]
	v_mfma_f32_16x16x32_bf16 v[36:39], v[80:83], v[168:171], v[36:39]
	v_mfma_f32_16x16x32_bf16 v[36:39], v[116:119], v[172:175], v[36:39]
	v_mfma_f32_16x16x32_bf16 v[32:35], v[152:155], v[168:171], v[32:35]
	v_mfma_f32_16x16x32_bf16 v[32:35], v[156:159], v[172:175], v[32:35]
	v_mfma_f32_16x16x32_bf16 v[20:23], v[80:83], v[194:197], v[20:23]
	v_mfma_f32_16x16x32_bf16 v[20:23], v[116:119], v[198:201], v[20:23]
	v_mfma_f32_16x16x32_bf16 v[16:19], v[152:155], v[194:197], v[16:19]
	v_mfma_f32_16x16x32_bf16 v[16:19], v[156:159], v[198:201], v[16:19]
	v_mfma_f32_16x16x32_bf16 v[4:7], v[80:83], v[202:205], v[4:7]
	v_mfma_f32_16x16x32_bf16 v[4:7], v[116:119], v[206:209], v[4:7]
	v_mfma_f32_16x16x32_bf16 v[0:3], v[152:155], v[202:205], v[0:3]
	v_mfma_f32_16x16x32_bf16 v[0:3], v[156:159], v[206:209], v[0:3]
	s_barrier
	s_add_i32 s88, s88, 2
	s_add_u32 s82, s82, 0x100
	s_addc_u32 s83, s83, 0
	s_add_u32 s75, s75, 0x100
	s_addc_u32 s81, s81, 0
	s_cmp_gt_u32 s88, 29
	s_cbranch_scc0 .LBB0_1190
	s_and_b64 vcc, exec, s[18:19]
	s_cbranch_vccz .LBB0_1193
	s_barrier

.LBB0_1289:
	s_lshl_b32 s80, s96, 8
	s_ashr_i32 s81, s80, 31
	s_lshl_b64 s[86:87], s[80:81], 2
	s_add_u32 s84, s84, s86
	s_addc_u32 s85, s85, s87
	s_add_i32 m0, s94, s41
	s_add_u32 s81, s82, 0x100
	global_load_lds_dwordx4 v239, s[84:85]
	s_addc_u32 s96, s83, 0
	s_cmp_eq_u32 s54, 5
	s_cselect_b32 vcc_lo, 66, -2
	s_bfe_u32 s86, s1, 0x20003
	s_cmp_eq_u32 s86, 3
	s_cselect_b32 s86, -8, 0
	s_cmp_eq_u32 s54, 5
	s_cselect_b32 s86, s86, 0
	s_add_i32 vcc_lo, vcc_lo, s86
	s_add_u32 s82, s78, 0x100
	s_addc_u32 s83, s79, 0
	s_add_i32 s94, 0, 0x10000
	s_cmpk_eq_i32 vcc_lo, 0x54
	s_cselect_b32 s87, s75, s83
	s_cselect_b32 s86, s74, s82
	s_cselect_b32 s85, s77, s96
	s_cselect_b32 s84, s76, s81
	s_add_i32 vcc_hi, 0, 0x14000
	v_add_u32_e32 v96, s94, v238
	v_add_u32_e32 v140, vcc_hi, v238
	ds_read_b128 v[64:67], v96
	ds_read_b128 v[72:75], v96 offset:1024
	ds_read_b128 v[88:91], v96 offset:2048
	ds_read_b128 v[96:99], v96 offset:3072
	ds_read_b128 v[108:111], v140
	ds_read_b128 v[116:119], v140 offset:1024
	ds_read_b128 v[128:131], v140 offset:2048
	ds_read_b128 v[140:143], v140 offset:3072
	v_lshl_add_u64 v[192:193], s[78:79], 0, v[230:231]
	s_add_i32 m0, s29, 0xc000
	ds_read_b128 v[152:155], v240
	ds_read_b128 v[156:159], v240 offset:1024
	ds_read_b128 v[160:163], v240 offset:2048
	ds_read_b128 v[164:167], v240 offset:3072
	ds_read_b128 v[168:171], v240 offset:4096
	ds_read_b128 v[180:183], v240 offset:5120
	ds_read_b128 v[184:187], v240 offset:6144
	ds_read_b128 v[188:191], v240 offset:7168
	global_load_lds_dwordx4 v[192:193], off
	v_lshl_add_u64 v[192:193], s[78:79], 0, v[232:233]
	s_add_i32 m0, s29, 0xe000
	s_nop 0
	global_load_lds_dwordx4 v[192:193], off
	s_waitcnt vmcnt(8)
	s_waitcnt lgkmcnt(0)
	s_barrier
	s_waitcnt lgkmcnt(0)
	v_mfma_f32_16x16x32_bf16 v[176:179], v[64:67], v[152:155], 0
	v_mfma_f32_16x16x32_bf16 v[176:179], v[72:75], v[156:159], v[176:179]
	v_mfma_f32_16x16x32_bf16 v[172:175], v[88:91], v[152:155], 0
	v_mfma_f32_16x16x32_bf16 v[172:175], v[96:99], v[156:159], v[172:175]
	v_mfma_f32_16x16x32_bf16 v[136:139], v[64:67], v[160:163], 0
	v_mfma_f32_16x16x32_bf16 v[136:139], v[72:75], v[164:167], v[136:139]
	v_mfma_f32_16x16x32_bf16 v[132:135], v[88:91], v[160:163], 0
	v_mfma_f32_16x16x32_bf16 v[132:135], v[96:99], v[164:167], v[132:135]
	v_mfma_f32_16x16x32_bf16 v[112:115], v[64:67], v[168:171], 0
	v_mfma_f32_16x16x32_bf16 v[112:115], v[72:75], v[180:183], v[112:115]
	v_mfma_f32_16x16x32_bf16 v[104:107], v[88:91], v[168:171], 0
	v_mfma_f32_16x16x32_bf16 v[104:107], v[96:99], v[180:183], v[104:107]
	v_mfma_f32_16x16x32_bf16 v[84:87], v[64:67], v[184:187], 0
	v_mfma_f32_16x16x32_bf16 v[84:87], v[72:75], v[188:191], v[84:87]
	v_mfma_f32_16x16x32_bf16 v[80:83], v[88:91], v[184:187], 0
	v_mfma_f32_16x16x32_bf16 v[80:83], v[96:99], v[188:191], v[80:83]
	v_mfma_f32_16x16x32_bf16 v[148:151], v[108:111], v[152:155], 0
	v_mfma_f32_16x16x32_bf16 v[148:151], v[116:119], v[156:159], v[148:151]
	v_mfma_f32_16x16x32_bf16 v[144:147], v[128:131], v[152:155], 0
	v_mfma_f32_16x16x32_bf16 v[144:147], v[140:143], v[156:159], v[144:147]
	v_mfma_f32_16x16x32_bf16 v[124:127], v[108:111], v[160:163], 0
	v_mfma_f32_16x16x32_bf16 v[124:127], v[116:119], v[164:167], v[124:127]
	v_mfma_f32_16x16x32_bf16 v[120:123], v[128:131], v[160:163], 0
	v_mfma_f32_16x16x32_bf16 v[120:123], v[140:143], v[164:167], v[120:123]
	v_mfma_f32_16x16x32_bf16 v[100:103], v[108:111], v[168:171], 0
	v_mfma_f32_16x16x32_bf16 v[100:103], v[116:119], v[180:183], v[100:103]
	v_mfma_f32_16x16x32_bf16 v[92:95], v[128:131], v[168:171], 0
	v_mfma_f32_16x16x32_bf16 v[92:95], v[140:143], v[180:183], v[92:95]
	v_mfma_f32_16x16x32_bf16 v[76:79], v[108:111], v[184:187], 0
	v_mfma_f32_16x16x32_bf16 v[76:79], v[116:119], v[188:191], v[76:79]
	v_mfma_f32_16x16x32_bf16 v[68:71], v[128:131], v[184:187], 0
	v_mfma_f32_16x16x32_bf16 v[68:71], v[140:143], v[188:191], v[68:71]
	s_barrier
	s_add_i32 s78, s94, s2
	v_lshl_add_u64 v[192:193], s[84:85], 0, v[216:217]
	s_mov_b32 m0, s78
	ds_read_b128 v[152:155], v240 offset:16384
	ds_read_b128 v[156:159], v240 offset:17408
	ds_read_b128 v[160:163], v240 offset:18432
	ds_read_b128 v[164:167], v240 offset:19456
	ds_read_b128 v[168:171], v240 offset:20480
	ds_read_b128 v[180:183], v240 offset:21504
	ds_read_b128 v[184:187], v240 offset:22528
	ds_read_b128 v[188:191], v240 offset:23552
	global_load_lds_dwordx4 v[192:193], off
	s_add_i32 m0, s78, 0x2000
	s_add_u32 s78, s84, 0x160000
	v_lshl_add_u64 v[194:195], s[84:85], 0, v[228:229]
	s_addc_u32 s79, s85, 0
	s_add_i32 s94, vcc_hi, s2
	global_load_lds_dwordx4 v[194:195], off
	v_lshl_add_u64 v[196:197], s[78:79], 0, v[216:217]
	s_mov_b32 m0, s94
	v_lshl_add_u64 v[198:199], s[86:87], 0, v[226:227]
	global_load_lds_dwordx4 v[196:197], off
	v_lshl_add_u64 v[196:197], s[78:79], 0, v[228:229]
	s_add_i32 m0, s94, 0x2000
	s_nop 0
	global_load_lds_dwordx4 v[196:197], off
	v_lshl_add_u64 v[196:197], s[86:87], 0, v[224:225]
	s_mov_b32 m0, s29
	s_nop 0
	global_load_lds_dwordx4 v[196:197], off
	s_mov_b32 m0, s34
	s_nop 0
	global_load_lds_dwordx4 v[198:199], off
	s_waitcnt vmcnt(8)
	s_waitcnt lgkmcnt(0)
	s_barrier
	s_waitcnt lgkmcnt(0)
	v_mfma_f32_16x16x32_bf16 v[60:63], v[64:67], v[152:155], 0
	v_mfma_f32_16x16x32_bf16 v[60:63], v[72:75], v[156:159], v[60:63]
	v_mfma_f32_16x16x32_bf16 v[56:59], v[88:91], v[152:155], 0
	v_mfma_f32_16x16x32_bf16 v[56:59], v[96:99], v[156:159], v[56:59]
	v_mfma_f32_16x16x32_bf16 v[44:47], v[64:67], v[160:163], 0
	v_mfma_f32_16x16x32_bf16 v[44:47], v[72:75], v[164:167], v[44:47]
	v_mfma_f32_16x16x32_bf16 v[40:43], v[88:91], v[160:163], 0
	v_mfma_f32_16x16x32_bf16 v[40:43], v[96:99], v[164:167], v[40:43]
	v_mfma_f32_16x16x32_bf16 v[28:31], v[64:67], v[168:171], 0
	v_mfma_f32_16x16x32_bf16 v[28:31], v[72:75], v[180:183], v[28:31]
	v_mfma_f32_16x16x32_bf16 v[24:27], v[88:91], v[168:171], 0
	v_mfma_f32_16x16x32_bf16 v[24:27], v[96:99], v[180:183], v[24:27]
	v_mfma_f32_16x16x32_bf16 v[12:15], v[64:67], v[184:187], 0
	v_mfma_f32_16x16x32_bf16 v[12:15], v[72:75], v[188:191], v[12:15]
	v_mfma_f32_16x16x32_bf16 v[8:11], v[88:91], v[184:187], 0
	v_mfma_f32_16x16x32_bf16 v[8:11], v[96:99], v[188:191], v[8:11]
	v_mfma_f32_16x16x32_bf16 v[52:55], v[108:111], v[152:155], 0
	v_mfma_f32_16x16x32_bf16 v[52:55], v[116:119], v[156:159], v[52:55]
	v_mfma_f32_16x16x32_bf16 v[48:51], v[128:131], v[152:155], 0
	v_mfma_f32_16x16x32_bf16 v[48:51], v[140:143], v[156:159], v[48:51]
	v_mfma_f32_16x16x32_bf16 v[36:39], v[108:111], v[160:163], 0
	v_mfma_f32_16x16x32_bf16 v[36:39], v[116:119], v[164:167], v[36:39]
	v_mfma_f32_16x16x32_bf16 v[32:35], v[128:131], v[160:163], 0
	v_mfma_f32_16x16x32_bf16 v[32:35], v[140:143], v[164:167], v[32:35]
	v_mfma_f32_16x16x32_bf16 v[20:23], v[108:111], v[168:171], 0
	v_mfma_f32_16x16x32_bf16 v[20:23], v[116:119], v[180:183], v[20:23]
	v_mfma_f32_16x16x32_bf16 v[16:19], v[128:131], v[168:171], 0
	v_mfma_f32_16x16x32_bf16 v[16:19], v[140:143], v[180:183], v[16:19]
	v_mfma_f32_16x16x32_bf16 v[4:7], v[108:111], v[184:187], 0
	v_mfma_f32_16x16x32_bf16 v[4:7], v[116:119], v[188:191], v[4:7]
	v_mfma_f32_16x16x32_bf16 v[0:3], v[128:131], v[184:187], 0
	v_mfma_f32_16x16x32_bf16 v[0:3], v[140:143], v[188:191], v[0:3]
	s_barrier
	s_add_i32 s94, 0, 0x18000
	s_add_i32 vcc_hi, 0, 0x1c000
	v_add_u32_e32 v96, s94, v238
	v_add_u32_e32 v140, vcc_hi, v238
	ds_read_b128 v[64:67], v96
	ds_read_b128 v[72:75], v96 offset:1024
	ds_read_b128 v[88:91], v96 offset:2048
	ds_read_b128 v[96:99], v96 offset:3072
	ds_read_b128 v[108:111], v140
	ds_read_b128 v[116:119], v140 offset:1024
	ds_read_b128 v[128:131], v140 offset:2048
	ds_read_b128 v[140:143], v140 offset:3072
	s_add_u32 s78, s86, 0x160000
	s_addc_u32 s79, s87, 0
	s_mov_b32 m0, s35
	v_lshl_add_u64 v[200:201], s[78:79], 0, v[224:225]
	ds_read_b128 v[152:155], v240 offset:32768
	ds_read_b128 v[156:159], v240 offset:33792
	ds_read_b128 v[160:163], v240 offset:34816
	ds_read_b128 v[164:167], v240 offset:35840
	ds_read_b128 v[168:171], v240 offset:36864
	ds_read_b128 v[180:183], v240 offset:37888
	ds_read_b128 v[184:187], v240 offset:38912
	ds_read_b128 v[188:191], v240 offset:39936
	global_load_lds_dwordx4 v[200:201], off
	v_lshl_add_u64 v[200:201], s[78:79], 0, v[226:227]
	s_mov_b32 m0, s38
	s_nop 0
	global_load_lds_dwordx4 v[200:201], off
	s_waitcnt vmcnt(8)
	s_waitcnt lgkmcnt(0)
	s_barrier
	s_waitcnt lgkmcnt(0)
	v_mfma_f32_16x16x32_bf16 v[176:179], v[64:67], v[152:155], v[176:179]
	v_mfma_f32_16x16x32_bf16 v[176:179], v[72:75], v[156:159], v[176:179]
	v_mfma_f32_16x16x32_bf16 v[172:175], v[88:91], v[152:155], v[172:175]
	v_mfma_f32_16x16x32_bf16 v[172:175], v[96:99], v[156:159], v[172:175]
	v_mfma_f32_16x16x32_bf16 v[136:139], v[64:67], v[160:163], v[136:139]
	v_mfma_f32_16x16x32_bf16 v[136:139], v[72:75], v[164:167], v[136:139]
	v_mfma_f32_16x16x32_bf16 v[132:135], v[88:91], v[160:163], v[132:135]
	v_mfma_f32_16x16x32_bf16 v[132:135], v[96:99], v[164:167], v[132:135]
	v_mfma_f32_16x16x32_bf16 v[112:115], v[64:67], v[168:171], v[112:115]
	v_mfma_f32_16x16x32_bf16 v[112:115], v[72:75], v[180:183], v[112:115]
	v_mfma_f32_16x16x32_bf16 v[104:107], v[88:91], v[168:171], v[104:107]
	v_mfma_f32_16x16x32_bf16 v[104:107], v[96:99], v[180:183], v[104:107]
	v_mfma_f32_16x16x32_bf16 v[84:87], v[64:67], v[184:187], v[84:87]
	v_mfma_f32_16x16x32_bf16 v[84:87], v[72:75], v[188:191], v[84:87]
	v_mfma_f32_16x16x32_bf16 v[80:83], v[88:91], v[184:187], v[80:83]
	v_mfma_f32_16x16x32_bf16 v[80:83], v[96:99], v[188:191], v[80:83]
	v_mfma_f32_16x16x32_bf16 v[148:151], v[108:111], v[152:155], v[148:151]
	v_mfma_f32_16x16x32_bf16 v[148:151], v[116:119], v[156:159], v[148:151]
	v_mfma_f32_16x16x32_bf16 v[144:147], v[128:131], v[152:155], v[144:147]
	v_mfma_f32_16x16x32_bf16 v[144:147], v[140:143], v[156:159], v[144:147]
	v_mfma_f32_16x16x32_bf16 v[124:127], v[108:111], v[160:163], v[124:127]
	v_mfma_f32_16x16x32_bf16 v[124:127], v[116:119], v[164:167], v[124:127]
	v_mfma_f32_16x16x32_bf16 v[120:123], v[128:131], v[160:163], v[120:123]
	v_mfma_f32_16x16x32_bf16 v[120:123], v[140:143], v[164:167], v[120:123]
	v_mfma_f32_16x16x32_bf16 v[100:103], v[108:111], v[168:171], v[100:103]
	v_mfma_f32_16x16x32_bf16 v[100:103], v[116:119], v[180:183], v[100:103]
	v_mfma_f32_16x16x32_bf16 v[92:95], v[128:131], v[168:171], v[92:95]
	v_mfma_f32_16x16x32_bf16 v[92:95], v[140:143], v[180:183], v[92:95]
	v_mfma_f32_16x16x32_bf16 v[76:79], v[108:111], v[184:187], v[76:79]
	v_mfma_f32_16x16x32_bf16 v[76:79], v[116:119], v[188:191], v[76:79]
	v_mfma_f32_16x16x32_bf16 v[68:71], v[128:131], v[184:187], v[68:71]
	v_mfma_f32_16x16x32_bf16 v[68:71], v[140:143], v[188:191], v[68:71]
	s_barrier
	s_add_i32 s78, s94, s2
	v_lshl_add_u64 v[192:193], v[192:193], 0, s[30:31]
	s_mov_b32 m0, s78
	ds_read_b128 v[152:155], v240 offset:49152
	ds_read_b128 v[156:159], v240 offset:50176
	ds_read_b128 v[160:163], v240 offset:51200
	ds_read_b128 v[164:167], v240 offset:52224
	ds_read_b128 v[168:171], v240 offset:53248
	ds_read_b128 v[180:183], v240 offset:54272
	ds_read_b128 v[184:187], v240 offset:55296
	ds_read_b128 v[188:191], v240 offset:56320
	global_load_lds_dwordx4 v[192:193], off
	s_add_i32 m0, s78, 0x2000
	s_add_u32 s78, s84, 0x160080
	v_lshl_add_u64 v[192:193], v[194:195], 0, s[30:31]
	s_addc_u32 s79, s85, 0
	s_add_i32 s84, vcc_hi, s2
	global_load_lds_dwordx4 v[192:193], off
	v_lshl_add_u64 v[192:193], s[78:79], 0, v[216:217]
	s_mov_b32 m0, s84
	s_nop 0
	global_load_lds_dwordx4 v[192:193], off
	v_lshl_add_u64 v[192:193], s[78:79], 0, v[228:229]
	s_add_i32 m0, s84, 0x2000
	s_nop 0
	global_load_lds_dwordx4 v[192:193], off
	v_lshl_add_u64 v[192:193], v[196:197], 0, s[30:31]
	s_mov_b32 m0, s60
	s_nop 0
	global_load_lds_dwordx4 v[192:193], off
	v_lshl_add_u64 v[192:193], v[198:199], 0, s[30:31]
	s_mov_b32 m0, s61
	s_nop 0
	global_load_lds_dwordx4 v[192:193], off
	s_waitcnt vmcnt(8)
	s_waitcnt lgkmcnt(0)
	s_barrier
	s_waitcnt lgkmcnt(0)
	v_mfma_f32_16x16x32_bf16 v[60:63], v[64:67], v[152:155], v[60:63]
	v_mfma_f32_16x16x32_bf16 v[60:63], v[72:75], v[156:159], v[60:63]
	v_mfma_f32_16x16x32_bf16 v[56:59], v[88:91], v[152:155], v[56:59]
	v_mfma_f32_16x16x32_bf16 v[56:59], v[96:99], v[156:159], v[56:59]
	v_mfma_f32_16x16x32_bf16 v[44:47], v[64:67], v[160:163], v[44:47]
	v_mfma_f32_16x16x32_bf16 v[44:47], v[72:75], v[164:167], v[44:47]
	v_mfma_f32_16x16x32_bf16 v[40:43], v[88:91], v[160:163], v[40:43]
	v_mfma_f32_16x16x32_bf16 v[40:43], v[96:99], v[164:167], v[40:43]
	v_mfma_f32_16x16x32_bf16 v[28:31], v[64:67], v[168:171], v[28:31]
	v_mfma_f32_16x16x32_bf16 v[28:31], v[72:75], v[180:183], v[28:31]
	v_mfma_f32_16x16x32_bf16 v[24:27], v[88:91], v[168:171], v[24:27]
	v_mfma_f32_16x16x32_bf16 v[24:27], v[96:99], v[180:183], v[24:27]
	v_mfma_f32_16x16x32_bf16 v[12:15], v[64:67], v[184:187], v[12:15]
	v_mfma_f32_16x16x32_bf16 v[12:15], v[72:75], v[188:191], v[12:15]
	v_mfma_f32_16x16x32_bf16 v[8:11], v[88:91], v[184:187], v[8:11]
	v_mfma_f32_16x16x32_bf16 v[8:11], v[96:99], v[188:191], v[8:11]
	v_mfma_f32_16x16x32_bf16 v[52:55], v[108:111], v[152:155], v[52:55]
	v_mfma_f32_16x16x32_bf16 v[52:55], v[116:119], v[156:159], v[52:55]
	v_mfma_f32_16x16x32_bf16 v[48:51], v[128:131], v[152:155], v[48:51]
	v_mfma_f32_16x16x32_bf16 v[48:51], v[140:143], v[156:159], v[48:51]
	v_mfma_f32_16x16x32_bf16 v[36:39], v[108:111], v[160:163], v[36:39]
	v_mfma_f32_16x16x32_bf16 v[36:39], v[116:119], v[164:167], v[36:39]
	v_mfma_f32_16x16x32_bf16 v[32:35], v[128:131], v[160:163], v[32:35]
	v_mfma_f32_16x16x32_bf16 v[32:35], v[140:143], v[164:167], v[32:35]
	v_mfma_f32_16x16x32_bf16 v[20:23], v[108:111], v[168:171], v[20:23]
	v_mfma_f32_16x16x32_bf16 v[20:23], v[116:119], v[180:183], v[20:23]
	v_mfma_f32_16x16x32_bf16 v[16:19], v[128:131], v[168:171], v[16:19]
	v_mfma_f32_16x16x32_bf16 v[16:19], v[140:143], v[180:183], v[16:19]
	v_mfma_f32_16x16x32_bf16 v[4:7], v[108:111], v[184:187], v[4:7]
	v_mfma_f32_16x16x32_bf16 v[4:7], v[116:119], v[188:191], v[4:7]
	v_mfma_f32_16x16x32_bf16 v[0:3], v[128:131], v[184:187], v[0:3]
	v_mfma_f32_16x16x32_bf16 v[0:3], v[140:143], v[188:191], v[0:3]
	s_barrier
	s_add_i32 vcc_lo, vcc_lo, 2
	s_add_u32 s81, s81, 0x100
	s_addc_u32 s96, s96, 0
	s_mov_b64 s[78:79], s[82:83]
.LBB0_1290:
	s_add_u32 s82, s78, 0x100
	s_addc_u32 s83, s79, 0
	s_add_i32 s94, 0, 0x10000
	s_cmpk_eq_i32 vcc_lo, 0x54
	s_cselect_b32 s87, s75, s83
	s_cselect_b32 s86, s74, s82
	s_cselect_b32 s85, s77, s96
	s_cselect_b32 s84, s76, s81
	s_add_i32 vcc_hi, 0, 0x14000
	v_add_u32_e32 v96, s94, v238
	v_add_u32_e32 v140, vcc_hi, v238
	ds_read_b128 v[64:67], v96
	ds_read_b128 v[72:75], v96 offset:1024
	ds_read_b128 v[88:91], v96 offset:2048
	ds_read_b128 v[96:99], v96 offset:3072
	ds_read_b128 v[108:111], v140
	ds_read_b128 v[116:119], v140 offset:1024
	ds_read_b128 v[128:131], v140 offset:2048
	ds_read_b128 v[140:143], v140 offset:3072
	v_lshl_add_u64 v[192:193], s[78:79], 0, v[230:231]
	s_add_i32 m0, s29, 0xc000
	ds_read_b128 v[152:155], v240
	ds_read_b128 v[156:159], v240 offset:1024
	ds_read_b128 v[160:163], v240 offset:2048
	ds_read_b128 v[164:167], v240 offset:3072
	ds_read_b128 v[168:171], v240 offset:4096
	ds_read_b128 v[180:183], v240 offset:5120
	ds_read_b128 v[184:187], v240 offset:6144
	ds_read_b128 v[188:191], v240 offset:7168
	global_load_lds_dwordx4 v[192:193], off
	v_lshl_add_u64 v[192:193], s[78:79], 0, v[232:233]
	s_add_i32 m0, s29, 0xe000
	s_nop 0
	global_load_lds_dwordx4 v[192:193], off
	s_waitcnt vmcnt(8)
	s_waitcnt lgkmcnt(0)
	s_barrier
	s_waitcnt lgkmcnt(0)
	v_mfma_f32_16x16x32_bf16 v[176:179], v[64:67], v[152:155], v[176:179]
	v_mfma_f32_16x16x32_bf16 v[176:179], v[72:75], v[156:159], v[176:179]
	v_mfma_f32_16x16x32_bf16 v[172:175], v[88:91], v[152:155], v[172:175]
	v_mfma_f32_16x16x32_bf16 v[172:175], v[96:99], v[156:159], v[172:175]
	v_mfma_f32_16x16x32_bf16 v[136:139], v[64:67], v[160:163], v[136:139]
	v_mfma_f32_16x16x32_bf16 v[136:139], v[72:75], v[164:167], v[136:139]
	v_mfma_f32_16x16x32_bf16 v[132:135], v[88:91], v[160:163], v[132:135]
	v_mfma_f32_16x16x32_bf16 v[132:135], v[96:99], v[164:167], v[132:135]
	v_mfma_f32_16x16x32_bf16 v[112:115], v[64:67], v[168:171], v[112:115]
	v_mfma_f32_16x16x32_bf16 v[112:115], v[72:75], v[180:183], v[112:115]
	v_mfma_f32_16x16x32_bf16 v[104:107], v[88:91], v[168:171], v[104:107]
	v_mfma_f32_16x16x32_bf16 v[104:107], v[96:99], v[180:183], v[104:107]
	v_mfma_f32_16x16x32_bf16 v[84:87], v[64:67], v[184:187], v[84:87]
	v_mfma_f32_16x16x32_bf16 v[84:87], v[72:75], v[188:191], v[84:87]
	v_mfma_f32_16x16x32_bf16 v[80:83], v[88:91], v[184:187], v[80:83]
	v_mfma_f32_16x16x32_bf16 v[80:83], v[96:99], v[188:191], v[80:83]
	v_mfma_f32_16x16x32_bf16 v[148:151], v[108:111], v[152:155], v[148:151]
	v_mfma_f32_16x16x32_bf16 v[148:151], v[116:119], v[156:159], v[148:151]
	v_mfma_f32_16x16x32_bf16 v[144:147], v[128:131], v[152:155], v[144:147]
	v_mfma_f32_16x16x32_bf16 v[144:147], v[140:143], v[156:159], v[144:147]
	v_mfma_f32_16x16x32_bf16 v[124:127], v[108:111], v[160:163], v[124:127]
	v_mfma_f32_16x16x32_bf16 v[124:127], v[116:119], v[164:167], v[124:127]
	v_mfma_f32_16x16x32_bf16 v[120:123], v[128:131], v[160:163], v[120:123]
	v_mfma_f32_16x16x32_bf16 v[120:123], v[140:143], v[164:167], v[120:123]
	v_mfma_f32_16x16x32_bf16 v[100:103], v[108:111], v[168:171], v[100:103]
	v_mfma_f32_16x16x32_bf16 v[100:103], v[116:119], v[180:183], v[100:103]
	v_mfma_f32_16x16x32_bf16 v[92:95], v[128:131], v[168:171], v[92:95]
	v_mfma_f32_16x16x32_bf16 v[92:95], v[140:143], v[180:183], v[92:95]
	v_mfma_f32_16x16x32_bf16 v[76:79], v[108:111], v[184:187], v[76:79]
	v_mfma_f32_16x16x32_bf16 v[76:79], v[116:119], v[188:191], v[76:79]
	v_mfma_f32_16x16x32_bf16 v[68:71], v[128:131], v[184:187], v[68:71]
	v_mfma_f32_16x16x32_bf16 v[68:71], v[140:143], v[188:191], v[68:71]
	s_barrier
	s_add_i32 s78, s94, s2
	v_lshl_add_u64 v[192:193], s[84:85], 0, v[216:217]
	s_mov_b32 m0, s78
	ds_read_b128 v[152:155], v240 offset:16384
	ds_read_b128 v[156:159], v240 offset:17408
	ds_read_b128 v[160:163], v240 offset:18432
	ds_read_b128 v[164:167], v240 offset:19456
	ds_read_b128 v[168:171], v240 offset:20480
	ds_read_b128 v[180:183], v240 offset:21504
	ds_read_b128 v[184:187], v240 offset:22528
	ds_read_b128 v[188:191], v240 offset:23552
	global_load_lds_dwordx4 v[192:193], off
	s_add_i32 m0, s78, 0x2000
	s_add_u32 s78, s84, 0x160000
	v_lshl_add_u64 v[194:195], s[84:85], 0, v[228:229]
	s_addc_u32 s79, s85, 0
	s_add_i32 s94, vcc_hi, s2
	global_load_lds_dwordx4 v[194:195], off
	v_lshl_add_u64 v[196:197], s[78:79], 0, v[216:217]
	s_mov_b32 m0, s94
	v_lshl_add_u64 v[198:199], s[86:87], 0, v[226:227]
	global_load_lds_dwordx4 v[196:197], off
	v_lshl_add_u64 v[196:197], s[78:79], 0, v[228:229]
	s_add_i32 m0, s94, 0x2000
	s_nop 0
	global_load_lds_dwordx4 v[196:197], off
	v_lshl_add_u64 v[196:197], s[86:87], 0, v[224:225]
	s_mov_b32 m0, s29
	s_nop 0
	global_load_lds_dwordx4 v[196:197], off
	s_mov_b32 m0, s34
	s_nop 0
	global_load_lds_dwordx4 v[198:199], off
	s_waitcnt vmcnt(8)
	s_waitcnt lgkmcnt(0)
	s_barrier
	s_waitcnt lgkmcnt(0)
	v_mfma_f32_16x16x32_bf16 v[60:63], v[64:67], v[152:155], v[60:63]
	v_mfma_f32_16x16x32_bf16 v[60:63], v[72:75], v[156:159], v[60:63]
	v_mfma_f32_16x16x32_bf16 v[56:59], v[88:91], v[152:155], v[56:59]
	v_mfma_f32_16x16x32_bf16 v[56:59], v[96:99], v[156:159], v[56:59]
	v_mfma_f32_16x16x32_bf16 v[44:47], v[64:67], v[160:163], v[44:47]
	v_mfma_f32_16x16x32_bf16 v[44:47], v[72:75], v[164:167], v[44:47]
	v_mfma_f32_16x16x32_bf16 v[40:43], v[88:91], v[160:163], v[40:43]
	v_mfma_f32_16x16x32_bf16 v[40:43], v[96:99], v[164:167], v[40:43]
	v_mfma_f32_16x16x32_bf16 v[28:31], v[64:67], v[168:171], v[28:31]
	v_mfma_f32_16x16x32_bf16 v[28:31], v[72:75], v[180:183], v[28:31]
	v_mfma_f32_16x16x32_bf16 v[24:27], v[88:91], v[168:171], v[24:27]
	v_mfma_f32_16x16x32_bf16 v[24:27], v[96:99], v[180:183], v[24:27]
	v_mfma_f32_16x16x32_bf16 v[12:15], v[64:67], v[184:187], v[12:15]
	v_mfma_f32_16x16x32_bf16 v[12:15], v[72:75], v[188:191], v[12:15]
	v_mfma_f32_16x16x32_bf16 v[8:11], v[88:91], v[184:187], v[8:11]
	v_mfma_f32_16x16x32_bf16 v[8:11], v[96:99], v[188:191], v[8:11]
	v_mfma_f32_16x16x32_bf16 v[52:55], v[108:111], v[152:155], v[52:55]
	v_mfma_f32_16x16x32_bf16 v[52:55], v[116:119], v[156:159], v[52:55]
	v_mfma_f32_16x16x32_bf16 v[48:51], v[128:131], v[152:155], v[48:51]
	v_mfma_f32_16x16x32_bf16 v[48:51], v[140:143], v[156:159], v[48:51]
	v_mfma_f32_16x16x32_bf16 v[36:39], v[108:111], v[160:163], v[36:39]
	v_mfma_f32_16x16x32_bf16 v[36:39], v[116:119], v[164:167], v[36:39]
	v_mfma_f32_16x16x32_bf16 v[32:35], v[128:131], v[160:163], v[32:35]
	v_mfma_f32_16x16x32_bf16 v[32:35], v[140:143], v[164:167], v[32:35]
	v_mfma_f32_16x16x32_bf16 v[20:23], v[108:111], v[168:171], v[20:23]
	v_mfma_f32_16x16x32_bf16 v[20:23], v[116:119], v[180:183], v[20:23]
	v_mfma_f32_16x16x32_bf16 v[16:19], v[128:131], v[168:171], v[16:19]
	v_mfma_f32_16x16x32_bf16 v[16:19], v[140:143], v[180:183], v[16:19]
	v_mfma_f32_16x16x32_bf16 v[4:7], v[108:111], v[184:187], v[4:7]
	v_mfma_f32_16x16x32_bf16 v[4:7], v[116:119], v[188:191], v[4:7]
	v_mfma_f32_16x16x32_bf16 v[0:3], v[128:131], v[184:187], v[0:3]
	v_mfma_f32_16x16x32_bf16 v[0:3], v[140:143], v[188:191], v[0:3]
	s_barrier
	s_add_i32 s94, 0, 0x18000
	s_add_i32 vcc_hi, 0, 0x1c000
	v_add_u32_e32 v96, s94, v238
	v_add_u32_e32 v140, vcc_hi, v238
	ds_read_b128 v[64:67], v96
	ds_read_b128 v[72:75], v96 offset:1024
	ds_read_b128 v[88:91], v96 offset:2048
	ds_read_b128 v[96:99], v96 offset:3072
	ds_read_b128 v[108:111], v140
	ds_read_b128 v[116:119], v140 offset:1024
	ds_read_b128 v[128:131], v140 offset:2048
	ds_read_b128 v[140:143], v140 offset:3072
	s_add_u32 s78, s86, 0x160000
	s_addc_u32 s79, s87, 0
	s_mov_b32 m0, s35
	v_lshl_add_u64 v[200:201], s[78:79], 0, v[224:225]
	ds_read_b128 v[152:155], v240 offset:32768
	ds_read_b128 v[156:159], v240 offset:33792
	ds_read_b128 v[160:163], v240 offset:34816
	ds_read_b128 v[164:167], v240 offset:35840
	ds_read_b128 v[168:171], v240 offset:36864
	ds_read_b128 v[180:183], v240 offset:37888
	ds_read_b128 v[184:187], v240 offset:38912
	ds_read_b128 v[188:191], v240 offset:39936
	global_load_lds_dwordx4 v[200:201], off
	v_lshl_add_u64 v[200:201], s[78:79], 0, v[226:227]
	s_mov_b32 m0, s38
	s_nop 0
	global_load_lds_dwordx4 v[200:201], off
	s_waitcnt vmcnt(8)
	s_waitcnt lgkmcnt(0)
	s_barrier
	s_waitcnt lgkmcnt(0)
	v_mfma_f32_16x16x32_bf16 v[176:179], v[64:67], v[152:155], v[176:179]
	v_mfma_f32_16x16x32_bf16 v[176:179], v[72:75], v[156:159], v[176:179]
	v_mfma_f32_16x16x32_bf16 v[172:175], v[88:91], v[152:155], v[172:175]
	v_mfma_f32_16x16x32_bf16 v[172:175], v[96:99], v[156:159], v[172:175]
	v_mfma_f32_16x16x32_bf16 v[136:139], v[64:67], v[160:163], v[136:139]
	v_mfma_f32_16x16x32_bf16 v[136:139], v[72:75], v[164:167], v[136:139]
	v_mfma_f32_16x16x32_bf16 v[132:135], v[88:91], v[160:163], v[132:135]
	v_mfma_f32_16x16x32_bf16 v[132:135], v[96:99], v[164:167], v[132:135]
	v_mfma_f32_16x16x32_bf16 v[112:115], v[64:67], v[168:171], v[112:115]
	v_mfma_f32_16x16x32_bf16 v[112:115], v[72:75], v[180:183], v[112:115]
	v_mfma_f32_16x16x32_bf16 v[104:107], v[88:91], v[168:171], v[104:107]
	v_mfma_f32_16x16x32_bf16 v[104:107], v[96:99], v[180:183], v[104:107]
	v_mfma_f32_16x16x32_bf16 v[84:87], v[64:67], v[184:187], v[84:87]
	v_mfma_f32_16x16x32_bf16 v[84:87], v[72:75], v[188:191], v[84:87]
	v_mfma_f32_16x16x32_bf16 v[80:83], v[88:91], v[184:187], v[80:83]
	v_mfma_f32_16x16x32_bf16 v[80:83], v[96:99], v[188:191], v[80:83]
	v_mfma_f32_16x16x32_bf16 v[148:151], v[108:111], v[152:155], v[148:151]
	v_mfma_f32_16x16x32_bf16 v[148:151], v[116:119], v[156:159], v[148:151]
	v_mfma_f32_16x16x32_bf16 v[144:147], v[128:131], v[152:155], v[144:147]
	v_mfma_f32_16x16x32_bf16 v[144:147], v[140:143], v[156:159], v[144:147]
	v_mfma_f32_16x16x32_bf16 v[124:127], v[108:111], v[160:163], v[124:127]
	v_mfma_f32_16x16x32_bf16 v[124:127], v[116:119], v[164:167], v[124:127]
	v_mfma_f32_16x16x32_bf16 v[120:123], v[128:131], v[160:163], v[120:123]
	v_mfma_f32_16x16x32_bf16 v[120:123], v[140:143], v[164:167], v[120:123]
	v_mfma_f32_16x16x32_bf16 v[100:103], v[108:111], v[168:171], v[100:103]
	v_mfma_f32_16x16x32_bf16 v[100:103], v[116:119], v[180:183], v[100:103]
	v_mfma_f32_16x16x32_bf16 v[92:95], v[128:131], v[168:171], v[92:95]
	v_mfma_f32_16x16x32_bf16 v[92:95], v[140:143], v[180:183], v[92:95]
	v_mfma_f32_16x16x32_bf16 v[76:79], v[108:111], v[184:187], v[76:79]
	v_mfma_f32_16x16x32_bf16 v[76:79], v[116:119], v[188:191], v[76:79]
	v_mfma_f32_16x16x32_bf16 v[68:71], v[128:131], v[184:187], v[68:71]
	v_mfma_f32_16x16x32_bf16 v[68:71], v[140:143], v[188:191], v[68:71]
	s_barrier
	s_add_i32 s78, s94, s2
	v_lshl_add_u64 v[192:193], v[192:193], 0, s[30:31]
	s_mov_b32 m0, s78
	ds_read_b128 v[152:155], v240 offset:49152
	ds_read_b128 v[156:159], v240 offset:50176
	ds_read_b128 v[160:163], v240 offset:51200
	ds_read_b128 v[164:167], v240 offset:52224
	ds_read_b128 v[168:171], v240 offset:53248
	ds_read_b128 v[180:183], v240 offset:54272
	ds_read_b128 v[184:187], v240 offset:55296
	ds_read_b128 v[188:191], v240 offset:56320
	global_load_lds_dwordx4 v[192:193], off
	s_add_i32 m0, s78, 0x2000
	s_add_u32 s78, s84, 0x160080
	v_lshl_add_u64 v[192:193], v[194:195], 0, s[30:31]
	s_addc_u32 s79, s85, 0
	s_add_i32 s84, vcc_hi, s2
	global_load_lds_dwordx4 v[192:193], off
	v_lshl_add_u64 v[192:193], s[78:79], 0, v[216:217]
	s_mov_b32 m0, s84
	s_nop 0
	global_load_lds_dwordx4 v[192:193], off
	v_lshl_add_u64 v[192:193], s[78:79], 0, v[228:229]
	s_add_i32 m0, s84, 0x2000
	s_nop 0
	global_load_lds_dwordx4 v[192:193], off
	v_lshl_add_u64 v[192:193], v[196:197], 0, s[30:31]
	s_mov_b32 m0, s60
	s_nop 0
	global_load_lds_dwordx4 v[192:193], off
	v_lshl_add_u64 v[192:193], v[198:199], 0, s[30:31]
	s_mov_b32 m0, s61
	s_nop 0
	global_load_lds_dwordx4 v[192:193], off
	s_waitcnt vmcnt(8)
	s_waitcnt lgkmcnt(0)
	s_barrier
	s_waitcnt lgkmcnt(0)
	v_mfma_f32_16x16x32_bf16 v[60:63], v[64:67], v[152:155], v[60:63]
	v_mfma_f32_16x16x32_bf16 v[60:63], v[72:75], v[156:159], v[60:63]
	v_mfma_f32_16x16x32_bf16 v[56:59], v[88:91], v[152:155], v[56:59]
	v_mfma_f32_16x16x32_bf16 v[56:59], v[96:99], v[156:159], v[56:59]
	v_mfma_f32_16x16x32_bf16 v[44:47], v[64:67], v[160:163], v[44:47]
	v_mfma_f32_16x16x32_bf16 v[44:47], v[72:75], v[164:167], v[44:47]
	v_mfma_f32_16x16x32_bf16 v[40:43], v[88:91], v[160:163], v[40:43]
	v_mfma_f32_16x16x32_bf16 v[40:43], v[96:99], v[164:167], v[40:43]
	v_mfma_f32_16x16x32_bf16 v[28:31], v[64:67], v[168:171], v[28:31]
	v_mfma_f32_16x16x32_bf16 v[28:31], v[72:75], v[180:183], v[28:31]
	v_mfma_f32_16x16x32_bf16 v[24:27], v[88:91], v[168:171], v[24:27]
	v_mfma_f32_16x16x32_bf16 v[24:27], v[96:99], v[180:183], v[24:27]
	v_mfma_f32_16x16x32_bf16 v[12:15], v[64:67], v[184:187], v[12:15]
	v_mfma_f32_16x16x32_bf16 v[12:15], v[72:75], v[188:191], v[12:15]
	v_mfma_f32_16x16x32_bf16 v[8:11], v[88:91], v[184:187], v[8:11]
	v_mfma_f32_16x16x32_bf16 v[8:11], v[96:99], v[188:191], v[8:11]
	v_mfma_f32_16x16x32_bf16 v[52:55], v[108:111], v[152:155], v[52:55]
	v_mfma_f32_16x16x32_bf16 v[52:55], v[116:119], v[156:159], v[52:55]
	v_mfma_f32_16x16x32_bf16 v[48:51], v[128:131], v[152:155], v[48:51]
	v_mfma_f32_16x16x32_bf16 v[48:51], v[140:143], v[156:159], v[48:51]
	v_mfma_f32_16x16x32_bf16 v[36:39], v[108:111], v[160:163], v[36:39]
	v_mfma_f32_16x16x32_bf16 v[36:39], v[116:119], v[164:167], v[36:39]
	v_mfma_f32_16x16x32_bf16 v[32:35], v[128:131], v[160:163], v[32:35]
	v_mfma_f32_16x16x32_bf16 v[32:35], v[140:143], v[164:167], v[32:35]
	v_mfma_f32_16x16x32_bf16 v[20:23], v[108:111], v[168:171], v[20:23]
	v_mfma_f32_16x16x32_bf16 v[20:23], v[116:119], v[180:183], v[20:23]
	v_mfma_f32_16x16x32_bf16 v[16:19], v[128:131], v[168:171], v[16:19]
	v_mfma_f32_16x16x32_bf16 v[16:19], v[140:143], v[180:183], v[16:19]
	v_mfma_f32_16x16x32_bf16 v[4:7], v[108:111], v[184:187], v[4:7]
	v_mfma_f32_16x16x32_bf16 v[4:7], v[116:119], v[188:191], v[4:7]
	v_mfma_f32_16x16x32_bf16 v[0:3], v[128:131], v[184:187], v[0:3]
	v_mfma_f32_16x16x32_bf16 v[0:3], v[140:143], v[188:191], v[0:3]
	s_barrier
	s_add_i32 vcc_lo, vcc_lo, 2
	s_add_u32 s81, s81, 0x100
	s_addc_u32 s96, s96, 0
	s_cmpk_gt_u32 vcc_lo, 0x55
	s_mov_b64 s[78:79], s[82:83]
	s_cbranch_scc0 .LBB0_1290
	s_and_b64 vcc, exec, s[70:71]
	s_cbranch_vccz .LBB0_1293
	s_barrier
